# stack: in-proj rstd loaded at tile start, up-proj epilogue paired 16-byte stores, redundant setprio pairs removed in GEMM MFMA blocks, MLA loop two-phase restructure with staggered wave halves
# speedup vs baseline: 1.0117x; 1.0117x over previous
; #define PG8_STAGE(bufoff, gbase, voff) do { _Pragma("unroll") for (int _i = 0; _i < 2; ++_i) \
;         __builtin_amdgcn_global_load_lds((const unsigned*)((const char*)(gbase) + (voff)[_i]), (PG8_LAS unsigned*)(lds + (bufoff) + ldsw + _i * 8192), 16, 0, 0); } while (0)
; #define PG8_LDA(dst, b, h) do { _Pragma("unroll") for (int m = 0; m < 4; ++m) _Pragma("unroll") for (int k = 0; k < 2; ++k) dst[m][k] = *(const PG8_LAS bf16x8*)(lds + PG8_SA(b, h) + aoff + m * 2048 + k * 1024); } while (0)
; #define PG8_LDB(dst, b, h) do { _Pragma("unroll") for (int n = 0; n < 2; ++n) _Pragma("unroll") for (int k = 0; k < 2; ++k) dst[n][k] = *(const PG8_LAS bf16x8*)(lds + PG8_SB(b, h) + boff + n * 2048 + k * 1024); } while (0)
; #define PG8_MMA(ai, bj, At, Bt) do { __builtin_amdgcn_s_setprio(1); _Pragma("unroll") for (int m = 0; m < 4; ++m) _Pragma("unroll") for (int n = 0; n < 2; ++n) _Pragma("unroll") for (int k = 0; k < 2; ++k) \
;         acc[ai][bj][m][n] = __builtin_amdgcn_mfma_f32_16x16x32_bf16(Bt[n][k], At[m][k], acc[ai][bj][m][n], 0, 0, 0); __builtin_amdgcn_s_setprio(0); } while (0)
; #define PG8_BAR __builtin_amdgcn_s_barrier()
; template <class Epi, class Sched, bool ALIGN_EPI = false, bool SP2 = false>
; __device__ __forceinline__ void gemm_phase(PG8_LAS unsigned char* lds, const Gemm g, const Sched& S, const Epi& E, int tid_in) {
;     ...
;             PG8_LDB(B0, 0, 0); PG8_LDB(B1, 0, 1); PG8_SCHED; PG8_LDA(At, 0, 0); PG8_STAGE(PG8_SA(1, 1), a1 + hstep, voffA);
;             PG8_WAIT_V(8); PG8_WAIT_L(0); PG8_BAR; PG8_MMA(0, 0, At, B0); PG8_MMA(0, 1, At, B1); PG8_BAR; PG8_SCHED;
;             PG8_LDA(At, 0, 1); PG8_STAGE(PG8_SB(0, 0), b2, voffB); PG8_STAGE(PG8_SB(0, 1), b2 + hstep, voffB); PG8_STAGE(PG8_SA(0, 0), a2, voffA);
;             PG8_WAIT_V(8); PG8_WAIT_L(0); PG8_BAR; PG8_MMA(1, 0, At, B0); PG8_MMA(1, 1, At, B1); PG8_BAR; PG8_SCHED;
;             PG8_LDB(B0, 1, 0); PG8_LDB(B1, 1, 1); PG8_SCHED; PG8_LDA(At, 1, 0); PG8_STAGE(PG8_SA(0, 1), a2 + hstep, voffA);
;             PG8_WAIT_V(8); PG8_WAIT_L(0); PG8_BAR; PG8_MMA(0, 0, At, B0); PG8_MMA(0, 1, At, B1); PG8_BAR; PG8_SCHED;
;             PG8_LDA(At, 1, 1); PG8_STAGE(PG8_SB(1, 0), b3, voffB); PG8_STAGE(PG8_SB(1, 1), b3 + hstep, voffB); PG8_STAGE(PG8_SA(1, 0), a3, voffA);
;             PG8_WAIT_V(8); PG8_WAIT_L(0); PG8_BAR; PG8_MMA(1, 0, At, B0); PG8_MMA(1, 1, At, B1); PG8_BAR; PG8_SCHED;
.LBB0_75:
	s_add_u32 s24, s22, 0x100
	s_addc_u32 s25, s23, 0
	s_add_i32 s45, 0, 0x10000
	s_cmp_eq_u32 s44, 40
	s_cselect_b32 s29, s61, s25
	s_cselect_b32 s28, s60, s24
	s_cselect_b32 s27, s21, s31
	s_cselect_b32 s26, s20, s30
	s_add_i32 s48, 0, 0x14000
	v_add_u32_e32 v152, s45, v159
	v_add_u32_e32 v156, s48, v159
	ds_read_b128 v[130:133], v152
	ds_read_b128 v[134:137], v152 offset:1024
	ds_read_b128 v[148:151], v152 offset:2048
	ds_read_b128 v[152:155], v152 offset:3072
	ds_read_b128 v[180:183], v156
	ds_read_b128 v[184:187], v156 offset:1024
	ds_read_b128 v[188:191], v156 offset:2048
	ds_read_b128 v[192:195], v156 offset:3072
	v_lshl_add_u64 v[156:157], s[22:23], 0, v[144:145]
	s_add_i32 m0, s62, 0xc000
	ds_read_b128 v[196:199], v178
	ds_read_b128 v[200:203], v178 offset:1024
	ds_read_b128 v[204:207], v178 offset:2048
	ds_read_b128 v[208:211], v178 offset:3072
	ds_read_b128 v[212:215], v178 offset:4096
	ds_read_b128 v[216:219], v178 offset:5120
	ds_read_b128 v[220:223], v178 offset:6144
	ds_read_b128 v[242:245], v178 offset:7168
	global_load_lds_dwordx4 v[156:157], off
	v_lshl_add_u64 v[156:157], s[22:23], 0, v[146:147]
	s_add_i32 m0, s62, 0xe000
	s_nop 0
	global_load_lds_dwordx4 v[156:157], off
	s_waitcnt vmcnt(8)
	s_waitcnt lgkmcnt(0)
	s_barrier
	s_setprio 1
	s_waitcnt lgkmcnt(0)
	v_mfma_f32_16x16x32_bf16 v[126:129], v[130:133], v[196:199], v[126:129]
	v_mfma_f32_16x16x32_bf16 v[122:125], v[148:151], v[196:199], v[122:125]
	v_mfma_f32_16x16x32_bf16 v[110:113], v[130:133], v[204:207], v[110:113]
	v_mfma_f32_16x16x32_bf16 v[106:109], v[148:151], v[204:207], v[106:109]
	v_mfma_f32_16x16x32_bf16 v[94:97], v[130:133], v[212:215], v[94:97]
	v_mfma_f32_16x16x32_bf16 v[90:93], v[148:151], v[212:215], v[90:93]
	v_mfma_f32_16x16x32_bf16 v[78:81], v[130:133], v[220:223], v[78:81]
	v_mfma_f32_16x16x32_bf16 v[74:77], v[148:151], v[220:223], v[74:77]
	v_mfma_f32_16x16x32_bf16 v[126:129], v[134:137], v[200:203], v[126:129]
	v_mfma_f32_16x16x32_bf16 v[122:125], v[152:155], v[200:203], v[122:125]
	v_mfma_f32_16x16x32_bf16 v[110:113], v[134:137], v[208:211], v[110:113]
	v_mfma_f32_16x16x32_bf16 v[106:109], v[152:155], v[208:211], v[106:109]
	v_mfma_f32_16x16x32_bf16 v[94:97], v[134:137], v[216:219], v[94:97]
	v_mfma_f32_16x16x32_bf16 v[90:93], v[152:155], v[216:219], v[90:93]
	v_mfma_f32_16x16x32_bf16 v[78:81], v[134:137], v[242:245], v[78:81]
	v_mfma_f32_16x16x32_bf16 v[74:77], v[152:155], v[242:245], v[74:77]
	v_mfma_f32_16x16x32_bf16 v[118:121], v[180:183], v[196:199], v[118:121]
	v_mfma_f32_16x16x32_bf16 v[114:117], v[188:191], v[196:199], v[114:117]
	v_mfma_f32_16x16x32_bf16 v[102:105], v[180:183], v[204:207], v[102:105]
	v_mfma_f32_16x16x32_bf16 v[98:101], v[188:191], v[204:207], v[98:101]
	v_mfma_f32_16x16x32_bf16 v[86:89], v[180:183], v[212:215], v[86:89]
	v_mfma_f32_16x16x32_bf16 v[82:85], v[188:191], v[212:215], v[82:85]
	v_mfma_f32_16x16x32_bf16 v[70:73], v[180:183], v[220:223], v[70:73]
	v_mfma_f32_16x16x32_bf16 v[66:69], v[188:191], v[220:223], v[66:69]
	v_mfma_f32_16x16x32_bf16 v[118:121], v[184:187], v[200:203], v[118:121]
	v_mfma_f32_16x16x32_bf16 v[114:117], v[192:195], v[200:203], v[114:117]
	v_mfma_f32_16x16x32_bf16 v[102:105], v[184:187], v[208:211], v[102:105]
	v_mfma_f32_16x16x32_bf16 v[98:101], v[192:195], v[208:211], v[98:101]
	v_mfma_f32_16x16x32_bf16 v[86:89], v[184:187], v[216:219], v[86:89]
	v_mfma_f32_16x16x32_bf16 v[82:85], v[192:195], v[216:219], v[82:85]
	v_mfma_f32_16x16x32_bf16 v[70:73], v[184:187], v[242:245], v[70:73]
	v_mfma_f32_16x16x32_bf16 v[66:69], v[192:195], v[242:245], v[66:69]
	s_setprio 0
	s_barrier
	s_add_i32 s22, s45, s37
	v_lshl_add_u64 v[156:157], s[26:27], 0, v[64:65]
	s_mov_b32 m0, s22
	ds_read_b128 v[196:199], v178 offset:16384
	ds_read_b128 v[200:203], v178 offset:17408
	ds_read_b128 v[204:207], v178 offset:18432
	ds_read_b128 v[208:211], v178 offset:19456
	ds_read_b128 v[212:215], v178 offset:20480
	ds_read_b128 v[216:219], v178 offset:21504
	ds_read_b128 v[220:223], v178 offset:22528
	ds_read_b128 v[242:245], v178 offset:23552
	global_load_lds_dwordx4 v[156:157], off
	s_add_i32 m0, s22, 0x2000
	s_add_u32 s22, s26, 0xb0000
	v_lshl_add_u64 v[172:173], s[26:27], 0, v[142:143]
	s_addc_u32 s23, s27, 0
	s_add_i32 s45, s48, s37
	global_load_lds_dwordx4 v[172:173], off
	v_lshl_add_u64 v[224:225], s[22:23], 0, v[64:65]
	s_mov_b32 m0, s45
	v_lshl_add_u64 v[232:233], s[28:29], 0, v[140:141]
	global_load_lds_dwordx4 v[224:225], off
	v_lshl_add_u64 v[224:225], s[22:23], 0, v[142:143]
	s_add_i32 m0, s45, 0x2000
	s_nop 0
	global_load_lds_dwordx4 v[224:225], off
	v_lshl_add_u64 v[224:225], s[28:29], 0, v[138:139]
	s_mov_b32 m0, s62
	s_nop 0
	global_load_lds_dwordx4 v[224:225], off
	s_mov_b32 m0, s63
	s_nop 0
	global_load_lds_dwordx4 v[232:233], off
	s_waitcnt vmcnt(8)
	s_waitcnt lgkmcnt(0)
	s_barrier
; #define PG8_STAGE(bufoff, gbase, voff) do { _Pragma("unroll") for (int _i = 0; _i < 2; ++_i) \
;         __builtin_amdgcn_global_load_lds((const unsigned*)((const char*)(gbase) + (voff)[_i]), (PG8_LAS unsigned*)(lds + (bufoff) + ldsw + _i * 8192), 16, 0, 0); } while (0)
; #define PG8_LDA(dst, b, h) do { _Pragma("unroll") for (int m = 0; m < 4; ++m) _Pragma("unroll") for (int k = 0; k < 2; ++k) dst[m][k] = *(const PG8_LAS bf16x8*)(lds + PG8_SA(b, h) + aoff + m * 2048 + k * 1024); } while (0)
; #define PG8_LDB(dst, b, h) do { _Pragma("unroll") for (int n = 0; n < 2; ++n) _Pragma("unroll") for (int k = 0; k < 2; ++k) dst[n][k] = *(const PG8_LAS bf16x8*)(lds + PG8_SB(b, h) + boff + n * 2048 + k * 1024); } while (0)
; #define PG8_MMA(ai, bj, At, Bt) do { __builtin_amdgcn_s_setprio(1); _Pragma("unroll") for (int m = 0; m < 4; ++m) _Pragma("unroll") for (int n = 0; n < 2; ++n) _Pragma("unroll") for (int k = 0; k < 2; ++k) \
;         acc[ai][bj][m][n] = __builtin_amdgcn_mfma_f32_16x16x32_bf16(Bt[n][k], At[m][k], acc[ai][bj][m][n], 0, 0, 0); __builtin_amdgcn_s_setprio(0); } while (0)
; #define PG8_BAR __builtin_amdgcn_s_barrier()
; template <class Epi, class Sched, bool ALIGN_EPI = false, bool SP2 = false>
; __device__ __forceinline__ void gemm_phase(PG8_LAS unsigned char* lds, const Gemm g, const Sched& S, const Epi& E, int tid_in) {
;     ...
;             PG8_LDB(B0, 0, 0); PG8_LDB(B1, 0, 1); PG8_SCHED; PG8_LDA(At, 0, 0); PG8_STAGE(PG8_SA(1, 1), a1 + hstep, voffA);
;             PG8_WAIT_V(8); PG8_WAIT_L(0); PG8_BAR; PG8_MMA(0, 0, At, B0); PG8_MMA(0, 1, At, B1); PG8_BAR; PG8_SCHED;
;             PG8_LDA(At, 0, 1); PG8_STAGE(PG8_SB(0, 0), b2, voffB); PG8_STAGE(PG8_SB(0, 1), b2 + hstep, voffB); PG8_STAGE(PG8_SA(0, 0), a2, voffA);
;             PG8_WAIT_V(8); PG8_WAIT_L(0); PG8_BAR; PG8_MMA(1, 0, At, B0); PG8_MMA(1, 1, At, B1); PG8_BAR; PG8_SCHED;
;             PG8_LDB(B0, 1, 0); PG8_LDB(B1, 1, 1); PG8_SCHED; PG8_LDA(At, 1, 0); PG8_STAGE(PG8_SA(0, 1), a2 + hstep, voffA);
;             PG8_WAIT_V(8); PG8_WAIT_L(0); PG8_BAR; PG8_MMA(0, 0, At, B0); PG8_MMA(0, 1, At, B1); PG8_BAR; PG8_SCHED;
;             PG8_LDA(At, 1, 1); PG8_STAGE(PG8_SB(1, 0), b3, voffB); PG8_STAGE(PG8_SB(1, 1), b3 + hstep, voffB); PG8_STAGE(PG8_SA(1, 0), a3, voffA);
;             PG8_WAIT_V(8); PG8_WAIT_L(0); PG8_BAR; PG8_MMA(1, 0, At, B0); PG8_MMA(1, 1, At, B1); PG8_BAR; PG8_SCHED;
	s_setprio 1
	s_waitcnt lgkmcnt(0)
	v_mfma_f32_16x16x32_bf16 v[60:63], v[130:133], v[196:199], v[60:63]
	v_mfma_f32_16x16x32_bf16 v[56:59], v[148:151], v[196:199], v[56:59]
	v_mfma_f32_16x16x32_bf16 v[44:47], v[130:133], v[204:207], v[44:47]
	v_mfma_f32_16x16x32_bf16 v[40:43], v[148:151], v[204:207], v[40:43]
	v_mfma_f32_16x16x32_bf16 v[28:31], v[130:133], v[212:215], v[28:31]
	v_mfma_f32_16x16x32_bf16 v[24:27], v[148:151], v[212:215], v[24:27]
	v_mfma_f32_16x16x32_bf16 v[12:15], v[130:133], v[220:223], v[12:15]
	v_mfma_f32_16x16x32_bf16 v[8:11], v[148:151], v[220:223], v[8:11]
	v_mfma_f32_16x16x32_bf16 v[60:63], v[134:137], v[200:203], v[60:63]
	v_mfma_f32_16x16x32_bf16 v[56:59], v[152:155], v[200:203], v[56:59]
	v_mfma_f32_16x16x32_bf16 v[44:47], v[134:137], v[208:211], v[44:47]
	v_mfma_f32_16x16x32_bf16 v[40:43], v[152:155], v[208:211], v[40:43]
	v_mfma_f32_16x16x32_bf16 v[28:31], v[134:137], v[216:219], v[28:31]
	v_mfma_f32_16x16x32_bf16 v[24:27], v[152:155], v[216:219], v[24:27]
	v_mfma_f32_16x16x32_bf16 v[12:15], v[134:137], v[242:245], v[12:15]
	v_mfma_f32_16x16x32_bf16 v[8:11], v[152:155], v[242:245], v[8:11]
	v_mfma_f32_16x16x32_bf16 v[52:55], v[180:183], v[196:199], v[52:55]
	v_mfma_f32_16x16x32_bf16 v[48:51], v[188:191], v[196:199], v[48:51]
	v_mfma_f32_16x16x32_bf16 v[36:39], v[180:183], v[204:207], v[36:39]
	v_mfma_f32_16x16x32_bf16 v[32:35], v[188:191], v[204:207], v[32:35]
	v_mfma_f32_16x16x32_bf16 v[20:23], v[180:183], v[212:215], v[20:23]
	v_mfma_f32_16x16x32_bf16 v[16:19], v[188:191], v[212:215], v[16:19]
	v_mfma_f32_16x16x32_bf16 v[4:7], v[180:183], v[220:223], v[4:7]
	v_mfma_f32_16x16x32_bf16 v[0:3], v[188:191], v[220:223], v[0:3]
	v_mfma_f32_16x16x32_bf16 v[52:55], v[184:187], v[200:203], v[52:55]
	v_mfma_f32_16x16x32_bf16 v[48:51], v[192:195], v[200:203], v[48:51]
	v_mfma_f32_16x16x32_bf16 v[36:39], v[184:187], v[208:211], v[36:39]
	v_mfma_f32_16x16x32_bf16 v[32:35], v[192:195], v[208:211], v[32:35]
	v_mfma_f32_16x16x32_bf16 v[20:23], v[184:187], v[216:219], v[20:23]
	v_mfma_f32_16x16x32_bf16 v[16:19], v[192:195], v[216:219], v[16:19]
	v_mfma_f32_16x16x32_bf16 v[4:7], v[184:187], v[242:245], v[4:7]
	v_mfma_f32_16x16x32_bf16 v[0:3], v[192:195], v[242:245], v[0:3]
	s_setprio 0
	s_barrier
	s_add_i32 s45, 0, 0x18000
	s_add_i32 s48, 0, 0x1c000
	v_add_u32_e32 v152, s45, v159
	v_add_u32_e32 v179, s48, v159
	ds_read_b128 v[130:133], v152
	ds_read_b128 v[134:137], v152 offset:1024
	ds_read_b128 v[148:151], v152 offset:2048
	ds_read_b128 v[152:155], v152 offset:3072
	ds_read_b128 v[180:183], v179
	ds_read_b128 v[184:187], v179 offset:1024
	ds_read_b128 v[188:191], v179 offset:2048
	ds_read_b128 v[192:195], v179 offset:3072
	s_add_u32 s22, s28, 0xb0000
	s_addc_u32 s23, s29, 0
	s_mov_b32 m0, s66
	v_lshl_add_u64 v[238:239], s[22:23], 0, v[138:139]
	ds_read_b128 v[196:199], v178 offset:32768
	ds_read_b128 v[200:203], v178 offset:33792
	ds_read_b128 v[204:207], v178 offset:34816
	ds_read_b128 v[208:211], v178 offset:35840
	ds_read_b128 v[212:215], v178 offset:36864
	ds_read_b128 v[216:219], v178 offset:37888
	ds_read_b128 v[220:223], v178 offset:38912
	ds_read_b128 v[242:245], v178 offset:39936
	global_load_lds_dwordx4 v[238:239], off
	v_lshl_add_u64 v[238:239], s[22:23], 0, v[140:141]
	s_mov_b32 m0, s67
	s_nop 0
	global_load_lds_dwordx4 v[238:239], off
	s_waitcnt vmcnt(8)
	s_waitcnt lgkmcnt(0)
	s_barrier
	s_setprio 1
	s_waitcnt lgkmcnt(0)
	v_mfma_f32_16x16x32_bf16 v[126:129], v[130:133], v[196:199], v[126:129]
	v_mfma_f32_16x16x32_bf16 v[122:125], v[148:151], v[196:199], v[122:125]
	v_mfma_f32_16x16x32_bf16 v[110:113], v[130:133], v[204:207], v[110:113]
	v_mfma_f32_16x16x32_bf16 v[106:109], v[148:151], v[204:207], v[106:109]
	v_mfma_f32_16x16x32_bf16 v[94:97], v[130:133], v[212:215], v[94:97]
	v_mfma_f32_16x16x32_bf16 v[90:93], v[148:151], v[212:215], v[90:93]
	v_mfma_f32_16x16x32_bf16 v[78:81], v[130:133], v[220:223], v[78:81]
	v_mfma_f32_16x16x32_bf16 v[74:77], v[148:151], v[220:223], v[74:77]
	v_mfma_f32_16x16x32_bf16 v[126:129], v[134:137], v[200:203], v[126:129]
	v_mfma_f32_16x16x32_bf16 v[122:125], v[152:155], v[200:203], v[122:125]
	v_mfma_f32_16x16x32_bf16 v[110:113], v[134:137], v[208:211], v[110:113]
	v_mfma_f32_16x16x32_bf16 v[106:109], v[152:155], v[208:211], v[106:109]
	v_mfma_f32_16x16x32_bf16 v[94:97], v[134:137], v[216:219], v[94:97]
	v_mfma_f32_16x16x32_bf16 v[90:93], v[152:155], v[216:219], v[90:93]
	v_mfma_f32_16x16x32_bf16 v[78:81], v[134:137], v[242:245], v[78:81]
	v_mfma_f32_16x16x32_bf16 v[74:77], v[152:155], v[242:245], v[74:77]
	v_mfma_f32_16x16x32_bf16 v[118:121], v[180:183], v[196:199], v[118:121]
	v_mfma_f32_16x16x32_bf16 v[114:117], v[188:191], v[196:199], v[114:117]
	v_mfma_f32_16x16x32_bf16 v[102:105], v[180:183], v[204:207], v[102:105]
	v_mfma_f32_16x16x32_bf16 v[98:101], v[188:191], v[204:207], v[98:101]
	v_mfma_f32_16x16x32_bf16 v[86:89], v[180:183], v[212:215], v[86:89]
	v_mfma_f32_16x16x32_bf16 v[82:85], v[188:191], v[212:215], v[82:85]
	v_mfma_f32_16x16x32_bf16 v[70:73], v[180:183], v[220:223], v[70:73]
	v_mfma_f32_16x16x32_bf16 v[66:69], v[188:191], v[220:223], v[66:69]
	v_mfma_f32_16x16x32_bf16 v[118:121], v[184:187], v[200:203], v[118:121]
	v_mfma_f32_16x16x32_bf16 v[114:117], v[192:195], v[200:203], v[114:117]
	v_mfma_f32_16x16x32_bf16 v[102:105], v[184:187], v[208:211], v[102:105]
	v_mfma_f32_16x16x32_bf16 v[98:101], v[192:195], v[208:211], v[98:101]
	v_mfma_f32_16x16x32_bf16 v[86:89], v[184:187], v[216:219], v[86:89]
	v_mfma_f32_16x16x32_bf16 v[82:85], v[192:195], v[216:219], v[82:85]
	v_mfma_f32_16x16x32_bf16 v[70:73], v[184:187], v[242:245], v[70:73]
	v_mfma_f32_16x16x32_bf16 v[66:69], v[192:195], v[242:245], v[66:69]
	s_setprio 0
	s_barrier
; #define PG8_STAGE(bufoff, gbase, voff) do { _Pragma("unroll") for (int _i = 0; _i < 2; ++_i) \
;         __builtin_amdgcn_global_load_lds((const unsigned*)((const char*)(gbase) + (voff)[_i]), (PG8_LAS unsigned*)(lds + (bufoff) + ldsw + _i * 8192), 16, 0, 0); } while (0)
; #define PG8_LDA(dst, b, h) do { _Pragma("unroll") for (int m = 0; m < 4; ++m) _Pragma("unroll") for (int k = 0; k < 2; ++k) dst[m][k] = *(const PG8_LAS bf16x8*)(lds + PG8_SA(b, h) + aoff + m * 2048 + k * 1024); } while (0)
; #define PG8_LDB(dst, b, h) do { _Pragma("unroll") for (int n = 0; n < 2; ++n) _Pragma("unroll") for (int k = 0; k < 2; ++k) dst[n][k] = *(const PG8_LAS bf16x8*)(lds + PG8_SB(b, h) + boff + n * 2048 + k * 1024); } while (0)
; #define PG8_MMA(ai, bj, At, Bt) do { __builtin_amdgcn_s_setprio(1); _Pragma("unroll") for (int m = 0; m < 4; ++m) _Pragma("unroll") for (int n = 0; n < 2; ++n) _Pragma("unroll") for (int k = 0; k < 2; ++k) \
;         acc[ai][bj][m][n] = __builtin_amdgcn_mfma_f32_16x16x32_bf16(Bt[n][k], At[m][k], acc[ai][bj][m][n], 0, 0, 0); __builtin_amdgcn_s_setprio(0); } while (0)
; #define PG8_BAR __builtin_amdgcn_s_barrier()
; template <class Epi, class Sched, bool ALIGN_EPI = false, bool SP2 = false>
; __device__ __forceinline__ void gemm_phase(PG8_LAS unsigned char* lds, const Gemm g, const Sched& S, const Epi& E, int tid_in) {
;     ...
;             PG8_LDB(B0, 0, 0); PG8_LDB(B1, 0, 1); PG8_SCHED; PG8_LDA(At, 0, 0); PG8_STAGE(PG8_SA(1, 1), a1 + hstep, voffA);
;             PG8_WAIT_V(8); PG8_WAIT_L(0); PG8_BAR; PG8_MMA(0, 0, At, B0); PG8_MMA(0, 1, At, B1); PG8_BAR; PG8_SCHED;
;             PG8_LDA(At, 0, 1); PG8_STAGE(PG8_SB(0, 0), b2, voffB); PG8_STAGE(PG8_SB(0, 1), b2 + hstep, voffB); PG8_STAGE(PG8_SA(0, 0), a2, voffA);
;             PG8_WAIT_V(8); PG8_WAIT_L(0); PG8_BAR; PG8_MMA(1, 0, At, B0); PG8_MMA(1, 1, At, B1); PG8_BAR; PG8_SCHED;
;             PG8_LDB(B0, 1, 0); PG8_LDB(B1, 1, 1); PG8_SCHED; PG8_LDA(At, 1, 0); PG8_STAGE(PG8_SA(0, 1), a2 + hstep, voffA);
;             PG8_WAIT_V(8); PG8_WAIT_L(0); PG8_BAR; PG8_MMA(0, 0, At, B0); PG8_MMA(0, 1, At, B1); PG8_BAR; PG8_SCHED;
;             PG8_LDA(At, 1, 1); PG8_STAGE(PG8_SB(1, 0), b3, voffB); PG8_STAGE(PG8_SB(1, 1), b3 + hstep, voffB); PG8_STAGE(PG8_SA(1, 0), a3, voffA);
;             PG8_WAIT_V(8); PG8_WAIT_L(0); PG8_BAR; PG8_MMA(1, 0, At, B0); PG8_MMA(1, 1, At, B1); PG8_BAR; PG8_SCHED;
	s_add_i32 s22, s45, s37
	v_lshl_add_u64 v[156:157], v[156:157], 0, s[92:93]
	s_mov_b32 m0, s22
	ds_read_b128 v[196:199], v178 offset:49152
	ds_read_b128 v[200:203], v178 offset:50176
	ds_read_b128 v[204:207], v178 offset:51200
	ds_read_b128 v[208:211], v178 offset:52224
	ds_read_b128 v[212:215], v178 offset:53248
	ds_read_b128 v[216:219], v178 offset:54272
	ds_read_b128 v[220:223], v178 offset:55296
	ds_read_b128 v[242:245], v178 offset:56320
	global_load_lds_dwordx4 v[156:157], off
	s_add_i32 m0, s22, 0x2000
	s_add_u32 s22, s26, 0xb0080
	v_lshl_add_u64 v[156:157], v[172:173], 0, s[92:93]
	s_addc_u32 s23, s27, 0
	s_add_i32 s26, s48, s37
	global_load_lds_dwordx4 v[156:157], off
	v_lshl_add_u64 v[156:157], s[22:23], 0, v[64:65]
	s_mov_b32 m0, s26
	s_nop 0
	global_load_lds_dwordx4 v[156:157], off
	v_lshl_add_u64 v[156:157], s[22:23], 0, v[142:143]
	s_add_i32 m0, s26, 0x2000
	s_nop 0
	global_load_lds_dwordx4 v[156:157], off
	v_lshl_add_u64 v[156:157], v[224:225], 0, s[92:93]
	s_mov_b32 m0, s69
	s_nop 0
	global_load_lds_dwordx4 v[156:157], off
	v_lshl_add_u64 v[156:157], v[232:233], 0, s[92:93]
	s_mov_b32 m0, s74
	s_nop 0
	global_load_lds_dwordx4 v[156:157], off
	s_waitcnt vmcnt(8)
	s_waitcnt lgkmcnt(0)
	s_barrier
	s_setprio 1
	s_waitcnt lgkmcnt(0)
	v_mfma_f32_16x16x32_bf16 v[60:63], v[130:133], v[196:199], v[60:63]
	v_mfma_f32_16x16x32_bf16 v[56:59], v[148:151], v[196:199], v[56:59]
	v_mfma_f32_16x16x32_bf16 v[44:47], v[130:133], v[204:207], v[44:47]
	v_mfma_f32_16x16x32_bf16 v[40:43], v[148:151], v[204:207], v[40:43]
	v_mfma_f32_16x16x32_bf16 v[28:31], v[130:133], v[212:215], v[28:31]
	v_mfma_f32_16x16x32_bf16 v[24:27], v[148:151], v[212:215], v[24:27]
	v_mfma_f32_16x16x32_bf16 v[12:15], v[130:133], v[220:223], v[12:15]
	v_mfma_f32_16x16x32_bf16 v[8:11], v[148:151], v[220:223], v[8:11]
	v_mfma_f32_16x16x32_bf16 v[60:63], v[134:137], v[200:203], v[60:63]
	v_mfma_f32_16x16x32_bf16 v[56:59], v[152:155], v[200:203], v[56:59]
	v_mfma_f32_16x16x32_bf16 v[44:47], v[134:137], v[208:211], v[44:47]
	v_mfma_f32_16x16x32_bf16 v[40:43], v[152:155], v[208:211], v[40:43]
	v_mfma_f32_16x16x32_bf16 v[28:31], v[134:137], v[216:219], v[28:31]
	v_mfma_f32_16x16x32_bf16 v[24:27], v[152:155], v[216:219], v[24:27]
	v_mfma_f32_16x16x32_bf16 v[12:15], v[134:137], v[242:245], v[12:15]
	v_mfma_f32_16x16x32_bf16 v[8:11], v[152:155], v[242:245], v[8:11]
	v_mfma_f32_16x16x32_bf16 v[52:55], v[180:183], v[196:199], v[52:55]
	v_mfma_f32_16x16x32_bf16 v[48:51], v[188:191], v[196:199], v[48:51]
	v_mfma_f32_16x16x32_bf16 v[36:39], v[180:183], v[204:207], v[36:39]
	v_mfma_f32_16x16x32_bf16 v[32:35], v[188:191], v[204:207], v[32:35]
	v_mfma_f32_16x16x32_bf16 v[20:23], v[180:183], v[212:215], v[20:23]
	v_mfma_f32_16x16x32_bf16 v[16:19], v[188:191], v[212:215], v[16:19]
	v_mfma_f32_16x16x32_bf16 v[4:7], v[180:183], v[220:223], v[4:7]
	v_mfma_f32_16x16x32_bf16 v[0:3], v[188:191], v[220:223], v[0:3]
	v_mfma_f32_16x16x32_bf16 v[52:55], v[184:187], v[200:203], v[52:55]
	v_mfma_f32_16x16x32_bf16 v[48:51], v[192:195], v[200:203], v[48:51]
	v_mfma_f32_16x16x32_bf16 v[36:39], v[184:187], v[208:211], v[36:39]
	v_mfma_f32_16x16x32_bf16 v[32:35], v[192:195], v[208:211], v[32:35]
	v_mfma_f32_16x16x32_bf16 v[20:23], v[184:187], v[216:219], v[20:23]
	v_mfma_f32_16x16x32_bf16 v[16:19], v[192:195], v[216:219], v[16:19]
	v_mfma_f32_16x16x32_bf16 v[4:7], v[184:187], v[242:245], v[4:7]
	v_mfma_f32_16x16x32_bf16 v[0:3], v[192:195], v[242:245], v[0:3]
	s_setprio 0
	s_barrier
	s_add_i32 s44, s44, 2
	s_add_u32 s30, s30, 0x100
	s_addc_u32 s31, s31, 0
	s_cmp_gt_u32 s44, 41
	s_mov_b64 s[22:23], s[24:25]
	s_cbranch_scc0 .LBB0_75
	s_and_b64 vcc, exec, s[46:47]
	s_cbranch_vccz .LBB0_78
	s_barrier

; #define PG8_STAGE(bufoff, gbase, voff) do { _Pragma("unroll") for (int _i = 0; _i < 2; ++_i) \
;         __builtin_amdgcn_global_load_lds((const unsigned*)((const char*)(gbase) + (voff)[_i]), (PG8_LAS unsigned*)(lds + (bufoff) + ldsw + _i * 8192), 16, 0, 0); } while (0)
; #define PG8_LDA(dst, b, h) do { _Pragma("unroll") for (int m = 0; m < 4; ++m) _Pragma("unroll") for (int k = 0; k < 2; ++k) dst[m][k] = *(const PG8_LAS bf16x8*)(lds + PG8_SA(b, h) + aoff + m * 2048 + k * 1024); } while (0)
; #define PG8_LDB(dst, b, h) do { _Pragma("unroll") for (int n = 0; n < 2; ++n) _Pragma("unroll") for (int k = 0; k < 2; ++k) dst[n][k] = *(const PG8_LAS bf16x8*)(lds + PG8_SB(b, h) + boff + n * 2048 + k * 1024); } while (0)
; #define PG8_MMA(ai, bj, At, Bt) do { __builtin_amdgcn_s_setprio(1); _Pragma("unroll") for (int m = 0; m < 4; ++m) _Pragma("unroll") for (int n = 0; n < 2; ++n) _Pragma("unroll") for (int k = 0; k < 2; ++k) \
;         acc[ai][bj][m][n] = __builtin_amdgcn_mfma_f32_16x16x32_bf16(Bt[n][k], At[m][k], acc[ai][bj][m][n], 0, 0, 0); __builtin_amdgcn_s_setprio(0); } while (0)
; #define PG8_BAR __builtin_amdgcn_s_barrier()
; template <class Epi, class Sched, bool ALIGN_EPI = false, bool SP2 = false>
; __device__ __forceinline__ void gemm_phase(PG8_LAS unsigned char* lds, const Gemm g, const Sched& S, const Epi& E, int tid_in) {
;     ...
;             PG8_LDB(B0, 0, 0); PG8_LDB(B1, 0, 1); PG8_SCHED; PG8_LDA(At, 0, 0); PG8_STAGE(PG8_SA(1, 1), a1 + hstep, voffA);
;             PG8_WAIT_V(8); PG8_WAIT_L(0); PG8_BAR; PG8_MMA(0, 0, At, B0); PG8_MMA(0, 1, At, B1); PG8_BAR; PG8_SCHED;
;             PG8_LDA(At, 0, 1); PG8_STAGE(PG8_SB(0, 0), b2, voffB); PG8_STAGE(PG8_SB(0, 1), b2 + hstep, voffB); PG8_STAGE(PG8_SA(0, 0), a2, voffA);
;             PG8_WAIT_V(8); PG8_WAIT_L(0); PG8_BAR; PG8_MMA(1, 0, At, B0); PG8_MMA(1, 1, At, B1); PG8_BAR; PG8_SCHED;
;             PG8_LDB(B0, 1, 0); PG8_LDB(B1, 1, 1); PG8_SCHED; PG8_LDA(At, 1, 0); PG8_STAGE(PG8_SA(0, 1), a2 + hstep, voffA);
;             PG8_WAIT_V(8); PG8_WAIT_L(0); PG8_BAR; PG8_MMA(0, 0, At, B0); PG8_MMA(0, 1, At, B1); PG8_BAR; PG8_SCHED;
;             PG8_LDA(At, 1, 1); PG8_STAGE(PG8_SB(1, 0), b3, voffB); PG8_STAGE(PG8_SB(1, 1), b3 + hstep, voffB); PG8_STAGE(PG8_SA(1, 0), a3, voffA);
;             PG8_WAIT_V(8); PG8_WAIT_L(0); PG8_BAR; PG8_MMA(1, 0, At, B0); PG8_MMA(1, 1, At, B1); PG8_BAR; PG8_SCHED;
.LBB0_242:
	s_add_u32 s28, s26, 0xfffc0080
	s_addc_u32 s29, s27, -1
	s_add_i32 s45, 0, 0x10000
	s_cmp_eq_u32 s44, 12
	s_cselect_b32 s31, s23, s29
	s_cselect_b32 s30, s25, s28
	v_add_u32_e32 v64, s45, v171
	s_cselect_b32 s29, s34, s43
	s_cselect_b32 s28, s35, s42
	s_add_i32 s49, 0, 0x14000
	ds_read_b128 v[122:125], v64
	ds_read_b128 v[126:129], v64 offset:1024
	ds_read_b128 v[130:133], v64 offset:2048
	ds_read_b128 v[134:137], v64 offset:3072
	v_add_u32_e32 v64, s49, v171
	ds_read_b128 v[146:149], v64
	ds_read_b128 v[150:153], v64 offset:1024
	ds_read_b128 v[154:157], v64 offset:2048
	ds_read_b128 v[158:161], v64 offset:3072
	v_lshl_add_u64 v[172:173], s[26:27], 0, v[188:189]
	s_add_i32 m0, s67, 0xc000
	ds_read_b128 v[162:165], v216
	ds_read_b128 v[166:169], v216 offset:1024
	ds_read_b128 v[192:195], v216 offset:2048
	ds_read_b128 v[196:199], v216 offset:3072
	ds_read_b128 v[200:203], v216 offset:4096
	ds_read_b128 v[204:207], v216 offset:5120
	ds_read_b128 v[208:211], v216 offset:6144
	ds_read_b128 v[212:215], v216 offset:7168
	global_load_lds_dwordx4 v[172:173], off
	v_lshl_add_u64 v[172:173], s[26:27], 0, v[190:191]
	s_add_i32 m0, s67, 0xe000
	s_nop 0
	global_load_lds_dwordx4 v[172:173], off
	s_waitcnt vmcnt(8)
	s_waitcnt lgkmcnt(0)
	s_barrier
	s_setprio 1
	s_waitcnt lgkmcnt(0)
	v_mfma_f32_16x16x32_bf16 v[114:117], v[122:125], v[162:165], v[114:117]
	v_mfma_f32_16x16x32_bf16 v[106:109], v[130:133], v[162:165], v[106:109]
	v_mfma_f32_16x16x32_bf16 v[142:145], v[122:125], v[192:195], v[142:145]
	v_mfma_f32_16x16x32_bf16 v[44:47], v[130:133], v[192:195], v[44:47]
	v_mfma_f32_16x16x32_bf16 v[110:113], v[122:125], v[200:203], v[110:113]
	v_mfma_f32_16x16x32_bf16 v[36:39], v[130:133], v[200:203], v[36:39]
	v_mfma_f32_16x16x32_bf16 v[118:121], v[122:125], v[208:211], v[118:121]
	v_mfma_f32_16x16x32_bf16 v[52:55], v[130:133], v[208:211], v[52:55]
	v_mfma_f32_16x16x32_bf16 v[114:117], v[126:129], v[166:169], v[114:117]
	v_mfma_f32_16x16x32_bf16 v[106:109], v[134:137], v[166:169], v[106:109]
	v_mfma_f32_16x16x32_bf16 v[142:145], v[126:129], v[196:199], v[142:145]
	v_mfma_f32_16x16x32_bf16 v[44:47], v[134:137], v[196:199], v[44:47]
	v_mfma_f32_16x16x32_bf16 v[110:113], v[126:129], v[204:207], v[110:113]
	v_mfma_f32_16x16x32_bf16 v[36:39], v[134:137], v[204:207], v[36:39]
	v_mfma_f32_16x16x32_bf16 v[118:121], v[126:129], v[212:215], v[118:121]
	v_mfma_f32_16x16x32_bf16 v[52:55], v[134:137], v[212:215], v[52:55]
	v_mfma_f32_16x16x32_bf16 v[102:105], v[146:149], v[162:165], v[102:105]
	v_mfma_f32_16x16x32_bf16 v[78:81], v[154:157], v[162:165], v[78:81]
	v_mfma_f32_16x16x32_bf16 v[138:141], v[146:149], v[192:195], v[138:141]
	v_mfma_f32_16x16x32_bf16 v[40:43], v[154:157], v[192:195], v[40:43]
	v_mfma_f32_16x16x32_bf16 v[98:101], v[146:149], v[200:203], v[98:101]
	v_mfma_f32_16x16x32_bf16 v[32:35], v[154:157], v[200:203], v[32:35]
	v_mfma_f32_16x16x32_bf16 v[94:97], v[146:149], v[208:211], v[94:97]
	v_mfma_f32_16x16x32_bf16 v[48:51], v[154:157], v[208:211], v[48:51]
	v_mfma_f32_16x16x32_bf16 v[102:105], v[150:153], v[166:169], v[102:105]
	v_mfma_f32_16x16x32_bf16 v[78:81], v[158:161], v[166:169], v[78:81]
	v_mfma_f32_16x16x32_bf16 v[138:141], v[150:153], v[196:199], v[138:141]
	v_mfma_f32_16x16x32_bf16 v[40:43], v[158:161], v[196:199], v[40:43]
	v_mfma_f32_16x16x32_bf16 v[98:101], v[150:153], v[204:207], v[98:101]
	v_mfma_f32_16x16x32_bf16 v[32:35], v[158:161], v[204:207], v[32:35]
	v_mfma_f32_16x16x32_bf16 v[94:97], v[150:153], v[212:215], v[94:97]
	v_mfma_f32_16x16x32_bf16 v[48:51], v[158:161], v[212:215], v[48:51]
	s_setprio 0
	s_barrier
	s_add_i32 s45, s45, s9
	v_lshl_add_u64 v[172:173], s[28:29], 0, v[178:179]
	s_mov_b32 m0, s45
	ds_read_b128 v[162:165], v216 offset:16384
	ds_read_b128 v[166:169], v216 offset:17408
	ds_read_b128 v[192:195], v216 offset:18432
	ds_read_b128 v[196:199], v216 offset:19456
	ds_read_b128 v[200:203], v216 offset:20480
	ds_read_b128 v[204:207], v216 offset:21504
	ds_read_b128 v[208:211], v216 offset:22528
	ds_read_b128 v[212:215], v216 offset:23552
	global_load_lds_dwordx4 v[172:173], off
	s_add_i32 m0, s45, 0x2000
	s_add_u32 s46, s28, 0x40000
	v_lshl_add_u64 v[220:221], s[28:29], 0, v[182:183]
	s_addc_u32 s47, s29, 0
	s_add_i32 s45, s49, s9
	global_load_lds_dwordx4 v[220:221], off
	v_lshl_add_u64 v[222:223], s[46:47], 0, v[178:179]
	s_mov_b32 m0, s45
	v_lshl_add_u64 v[224:225], s[30:31], 0, v[180:181]
	global_load_lds_dwordx4 v[222:223], off
	v_lshl_add_u64 v[222:223], s[46:47], 0, v[182:183]
	s_add_i32 m0, s45, 0x2000
	s_nop 0
	global_load_lds_dwordx4 v[222:223], off
	v_lshl_add_u64 v[222:223], s[30:31], 0, v[176:177]
	s_mov_b32 m0, s67
	s_nop 0
	global_load_lds_dwordx4 v[222:223], off
	s_mov_b32 m0, s69
	s_nop 0
	global_load_lds_dwordx4 v[224:225], off
	s_waitcnt vmcnt(8)
	s_waitcnt lgkmcnt(0)
	s_barrier
; #define PG8_STAGE(bufoff, gbase, voff) do { _Pragma("unroll") for (int _i = 0; _i < 2; ++_i) \
;         __builtin_amdgcn_global_load_lds((const unsigned*)((const char*)(gbase) + (voff)[_i]), (PG8_LAS unsigned*)(lds + (bufoff) + ldsw + _i * 8192), 16, 0, 0); } while (0)
; #define PG8_LDA(dst, b, h) do { _Pragma("unroll") for (int m = 0; m < 4; ++m) _Pragma("unroll") for (int k = 0; k < 2; ++k) dst[m][k] = *(const PG8_LAS bf16x8*)(lds + PG8_SA(b, h) + aoff + m * 2048 + k * 1024); } while (0)
; #define PG8_LDB(dst, b, h) do { _Pragma("unroll") for (int n = 0; n < 2; ++n) _Pragma("unroll") for (int k = 0; k < 2; ++k) dst[n][k] = *(const PG8_LAS bf16x8*)(lds + PG8_SB(b, h) + boff + n * 2048 + k * 1024); } while (0)
; #define PG8_MMA(ai, bj, At, Bt) do { __builtin_amdgcn_s_setprio(1); _Pragma("unroll") for (int m = 0; m < 4; ++m) _Pragma("unroll") for (int n = 0; n < 2; ++n) _Pragma("unroll") for (int k = 0; k < 2; ++k) \
;         acc[ai][bj][m][n] = __builtin_amdgcn_mfma_f32_16x16x32_bf16(Bt[n][k], At[m][k], acc[ai][bj][m][n], 0, 0, 0); __builtin_amdgcn_s_setprio(0); } while (0)
; #define PG8_BAR __builtin_amdgcn_s_barrier()
; template <class Epi, class Sched, bool ALIGN_EPI = false, bool SP2 = false>
; __device__ __forceinline__ void gemm_phase(PG8_LAS unsigned char* lds, const Gemm g, const Sched& S, const Epi& E, int tid_in) {
;     ...
;             PG8_LDB(B0, 0, 0); PG8_LDB(B1, 0, 1); PG8_SCHED; PG8_LDA(At, 0, 0); PG8_STAGE(PG8_SA(1, 1), a1 + hstep, voffA);
;             PG8_WAIT_V(8); PG8_WAIT_L(0); PG8_BAR; PG8_MMA(0, 0, At, B0); PG8_MMA(0, 1, At, B1); PG8_BAR; PG8_SCHED;
;             PG8_LDA(At, 0, 1); PG8_STAGE(PG8_SB(0, 0), b2, voffB); PG8_STAGE(PG8_SB(0, 1), b2 + hstep, voffB); PG8_STAGE(PG8_SA(0, 0), a2, voffA);
;             PG8_WAIT_V(8); PG8_WAIT_L(0); PG8_BAR; PG8_MMA(1, 0, At, B0); PG8_MMA(1, 1, At, B1); PG8_BAR; PG8_SCHED;
;             PG8_LDB(B0, 1, 0); PG8_LDB(B1, 1, 1); PG8_SCHED; PG8_LDA(At, 1, 0); PG8_STAGE(PG8_SA(0, 1), a2 + hstep, voffA);
;             PG8_WAIT_V(8); PG8_WAIT_L(0); PG8_BAR; PG8_MMA(0, 0, At, B0); PG8_MMA(0, 1, At, B1); PG8_BAR; PG8_SCHED;
;             PG8_LDA(At, 1, 1); PG8_STAGE(PG8_SB(1, 0), b3, voffB); PG8_STAGE(PG8_SB(1, 1), b3 + hstep, voffB); PG8_STAGE(PG8_SA(1, 0), a3, voffA);
;             PG8_WAIT_V(8); PG8_WAIT_L(0); PG8_BAR; PG8_MMA(1, 0, At, B0); PG8_MMA(1, 1, At, B1); PG8_BAR; PG8_SCHED;
	s_setprio 1
	s_waitcnt lgkmcnt(0)
	v_mfma_f32_16x16x32_bf16 v[82:85], v[122:125], v[162:165], v[82:85]
	v_mfma_f32_16x16x32_bf16 v[20:23], v[130:133], v[162:165], v[20:23]
	v_mfma_f32_16x16x32_bf16 v[70:73], v[122:125], v[192:195], v[70:73]
	v_mfma_f32_16x16x32_bf16 v[12:15], v[130:133], v[192:195], v[12:15]
	v_mfma_f32_16x16x32_bf16 v[60:63], v[122:125], v[200:203], v[60:63]
	v_mfma_f32_16x16x32_bf16 v[4:7], v[130:133], v[200:203], v[4:7]
	v_mfma_f32_16x16x32_bf16 v[90:93], v[122:125], v[208:211], v[90:93]
	v_mfma_f32_16x16x32_bf16 v[28:31], v[130:133], v[208:211], v[28:31]
	v_mfma_f32_16x16x32_bf16 v[82:85], v[126:129], v[166:169], v[82:85]
	v_mfma_f32_16x16x32_bf16 v[20:23], v[134:137], v[166:169], v[20:23]
	v_mfma_f32_16x16x32_bf16 v[70:73], v[126:129], v[196:199], v[70:73]
	v_mfma_f32_16x16x32_bf16 v[12:15], v[134:137], v[196:199], v[12:15]
	v_mfma_f32_16x16x32_bf16 v[60:63], v[126:129], v[204:207], v[60:63]
	v_mfma_f32_16x16x32_bf16 v[4:7], v[134:137], v[204:207], v[4:7]
	v_mfma_f32_16x16x32_bf16 v[90:93], v[126:129], v[212:215], v[90:93]
	v_mfma_f32_16x16x32_bf16 v[28:31], v[134:137], v[212:215], v[28:31]
	v_mfma_f32_16x16x32_bf16 v[74:77], v[146:149], v[162:165], v[74:77]
	v_mfma_f32_16x16x32_bf16 v[16:19], v[154:157], v[162:165], v[16:19]
	v_mfma_f32_16x16x32_bf16 v[66:69], v[146:149], v[192:195], v[66:69]
	v_mfma_f32_16x16x32_bf16 v[8:11], v[154:157], v[192:195], v[8:11]
	v_mfma_f32_16x16x32_bf16 v[56:59], v[146:149], v[200:203], v[56:59]
	v_mfma_f32_16x16x32_bf16 v[0:3], v[154:157], v[200:203], v[0:3]
	v_mfma_f32_16x16x32_bf16 v[86:89], v[146:149], v[208:211], v[86:89]
	v_mfma_f32_16x16x32_bf16 v[24:27], v[154:157], v[208:211], v[24:27]
	v_mfma_f32_16x16x32_bf16 v[74:77], v[150:153], v[166:169], v[74:77]
	v_mfma_f32_16x16x32_bf16 v[16:19], v[158:161], v[166:169], v[16:19]
	v_mfma_f32_16x16x32_bf16 v[66:69], v[150:153], v[196:199], v[66:69]
	v_mfma_f32_16x16x32_bf16 v[8:11], v[158:161], v[196:199], v[8:11]
	v_mfma_f32_16x16x32_bf16 v[56:59], v[150:153], v[204:207], v[56:59]
	v_mfma_f32_16x16x32_bf16 v[0:3], v[158:161], v[204:207], v[0:3]
	v_mfma_f32_16x16x32_bf16 v[86:89], v[150:153], v[212:215], v[86:89]
	v_mfma_f32_16x16x32_bf16 v[24:27], v[158:161], v[212:215], v[24:27]
	s_setprio 0
	s_barrier
	s_add_i32 s45, 0, 0x18000
	v_add_u32_e32 v64, s45, v171
	s_add_i32 s46, 0, 0x1c000
	ds_read_b128 v[122:125], v64
	ds_read_b128 v[126:129], v64 offset:1024
	ds_read_b128 v[130:133], v64 offset:2048
	ds_read_b128 v[134:137], v64 offset:3072
	v_add_u32_e32 v64, s46, v171
	ds_read_b128 v[146:149], v64
	ds_read_b128 v[150:153], v64 offset:1024
	ds_read_b128 v[154:157], v64 offset:2048
	ds_read_b128 v[158:161], v64 offset:3072
	s_add_u32 s30, s30, 0x40000
	s_addc_u32 s31, s31, 0
	s_mov_b32 m0, s79
	v_lshl_add_u64 v[232:233], s[30:31], 0, v[176:177]
	ds_read_b128 v[162:165], v216 offset:32768
	ds_read_b128 v[166:169], v216 offset:33792
	ds_read_b128 v[192:195], v216 offset:34816
	ds_read_b128 v[196:199], v216 offset:35840
	ds_read_b128 v[200:203], v216 offset:36864
	ds_read_b128 v[204:207], v216 offset:37888
	ds_read_b128 v[208:211], v216 offset:38912
	ds_read_b128 v[212:215], v216 offset:39936
	global_load_lds_dwordx4 v[232:233], off
	v_lshl_add_u64 v[232:233], s[30:31], 0, v[180:181]
	s_mov_b32 m0, s82
	s_nop 0
	global_load_lds_dwordx4 v[232:233], off
	s_waitcnt vmcnt(8)
	s_waitcnt lgkmcnt(0)
	s_barrier
	s_setprio 1
	s_waitcnt lgkmcnt(0)
	v_mfma_f32_16x16x32_bf16 v[114:117], v[122:125], v[162:165], v[114:117]
	v_mfma_f32_16x16x32_bf16 v[106:109], v[130:133], v[162:165], v[106:109]
	v_mfma_f32_16x16x32_bf16 v[142:145], v[122:125], v[192:195], v[142:145]
	v_mfma_f32_16x16x32_bf16 v[44:47], v[130:133], v[192:195], v[44:47]
	v_mfma_f32_16x16x32_bf16 v[110:113], v[122:125], v[200:203], v[110:113]
	v_mfma_f32_16x16x32_bf16 v[36:39], v[130:133], v[200:203], v[36:39]
	v_mfma_f32_16x16x32_bf16 v[118:121], v[122:125], v[208:211], v[118:121]
	v_mfma_f32_16x16x32_bf16 v[52:55], v[130:133], v[208:211], v[52:55]
	v_mfma_f32_16x16x32_bf16 v[114:117], v[126:129], v[166:169], v[114:117]
	v_mfma_f32_16x16x32_bf16 v[106:109], v[134:137], v[166:169], v[106:109]
	v_mfma_f32_16x16x32_bf16 v[142:145], v[126:129], v[196:199], v[142:145]
	v_mfma_f32_16x16x32_bf16 v[44:47], v[134:137], v[196:199], v[44:47]
	v_mfma_f32_16x16x32_bf16 v[110:113], v[126:129], v[204:207], v[110:113]
	v_mfma_f32_16x16x32_bf16 v[36:39], v[134:137], v[204:207], v[36:39]
	v_mfma_f32_16x16x32_bf16 v[118:121], v[126:129], v[212:215], v[118:121]
	v_mfma_f32_16x16x32_bf16 v[52:55], v[134:137], v[212:215], v[52:55]
	v_mfma_f32_16x16x32_bf16 v[102:105], v[146:149], v[162:165], v[102:105]
	v_mfma_f32_16x16x32_bf16 v[78:81], v[154:157], v[162:165], v[78:81]
	v_mfma_f32_16x16x32_bf16 v[138:141], v[146:149], v[192:195], v[138:141]
	v_mfma_f32_16x16x32_bf16 v[40:43], v[154:157], v[192:195], v[40:43]
	v_mfma_f32_16x16x32_bf16 v[98:101], v[146:149], v[200:203], v[98:101]
	v_mfma_f32_16x16x32_bf16 v[32:35], v[154:157], v[200:203], v[32:35]
	v_mfma_f32_16x16x32_bf16 v[94:97], v[146:149], v[208:211], v[94:97]
	v_mfma_f32_16x16x32_bf16 v[48:51], v[154:157], v[208:211], v[48:51]
	v_mfma_f32_16x16x32_bf16 v[102:105], v[150:153], v[166:169], v[102:105]
	v_mfma_f32_16x16x32_bf16 v[78:81], v[158:161], v[166:169], v[78:81]
	v_mfma_f32_16x16x32_bf16 v[138:141], v[150:153], v[196:199], v[138:141]
	v_mfma_f32_16x16x32_bf16 v[40:43], v[158:161], v[196:199], v[40:43]
	v_mfma_f32_16x16x32_bf16 v[98:101], v[150:153], v[204:207], v[98:101]
	v_mfma_f32_16x16x32_bf16 v[32:35], v[158:161], v[204:207], v[32:35]
	v_mfma_f32_16x16x32_bf16 v[94:97], v[150:153], v[212:215], v[94:97]
	v_mfma_f32_16x16x32_bf16 v[48:51], v[158:161], v[212:215], v[48:51]
	s_setprio 0
	s_barrier
; #define PG8_STAGE(bufoff, gbase, voff) do { _Pragma("unroll") for (int _i = 0; _i < 2; ++_i) \
;         __builtin_amdgcn_global_load_lds((const unsigned*)((const char*)(gbase) + (voff)[_i]), (PG8_LAS unsigned*)(lds + (bufoff) + ldsw + _i * 8192), 16, 0, 0); } while (0)
; #define PG8_LDA(dst, b, h) do { _Pragma("unroll") for (int m = 0; m < 4; ++m) _Pragma("unroll") for (int k = 0; k < 2; ++k) dst[m][k] = *(const PG8_LAS bf16x8*)(lds + PG8_SA(b, h) + aoff + m * 2048 + k * 1024); } while (0)
; #define PG8_LDB(dst, b, h) do { _Pragma("unroll") for (int n = 0; n < 2; ++n) _Pragma("unroll") for (int k = 0; k < 2; ++k) dst[n][k] = *(const PG8_LAS bf16x8*)(lds + PG8_SB(b, h) + boff + n * 2048 + k * 1024); } while (0)
; #define PG8_MMA(ai, bj, At, Bt) do { __builtin_amdgcn_s_setprio(1); _Pragma("unroll") for (int m = 0; m < 4; ++m) _Pragma("unroll") for (int n = 0; n < 2; ++n) _Pragma("unroll") for (int k = 0; k < 2; ++k) \
;         acc[ai][bj][m][n] = __builtin_amdgcn_mfma_f32_16x16x32_bf16(Bt[n][k], At[m][k], acc[ai][bj][m][n], 0, 0, 0); __builtin_amdgcn_s_setprio(0); } while (0)
; #define PG8_BAR __builtin_amdgcn_s_barrier()
; template <class Epi, class Sched, bool ALIGN_EPI = false, bool SP2 = false>
; __device__ __forceinline__ void gemm_phase(PG8_LAS unsigned char* lds, const Gemm g, const Sched& S, const Epi& E, int tid_in) {
;     ...
;             PG8_LDB(B0, 0, 0); PG8_LDB(B1, 0, 1); PG8_SCHED; PG8_LDA(At, 0, 0); PG8_STAGE(PG8_SA(1, 1), a1 + hstep, voffA);
;             PG8_WAIT_V(8); PG8_WAIT_L(0); PG8_BAR; PG8_MMA(0, 0, At, B0); PG8_MMA(0, 1, At, B1); PG8_BAR; PG8_SCHED;
;             PG8_LDA(At, 0, 1); PG8_STAGE(PG8_SB(0, 0), b2, voffB); PG8_STAGE(PG8_SB(0, 1), b2 + hstep, voffB); PG8_STAGE(PG8_SA(0, 0), a2, voffA);
;             PG8_WAIT_V(8); PG8_WAIT_L(0); PG8_BAR; PG8_MMA(1, 0, At, B0); PG8_MMA(1, 1, At, B1); PG8_BAR; PG8_SCHED;
;             PG8_LDB(B0, 1, 0); PG8_LDB(B1, 1, 1); PG8_SCHED; PG8_LDA(At, 1, 0); PG8_STAGE(PG8_SA(0, 1), a2 + hstep, voffA);
;             PG8_WAIT_V(8); PG8_WAIT_L(0); PG8_BAR; PG8_MMA(0, 0, At, B0); PG8_MMA(0, 1, At, B1); PG8_BAR; PG8_SCHED;
;             PG8_LDA(At, 1, 1); PG8_STAGE(PG8_SB(1, 0), b3, voffB); PG8_STAGE(PG8_SB(1, 1), b3 + hstep, voffB); PG8_STAGE(PG8_SA(1, 0), a3, voffA);
;             PG8_WAIT_V(8); PG8_WAIT_L(0); PG8_BAR; PG8_MMA(1, 0, At, B0); PG8_MMA(1, 1, At, B1); PG8_BAR; PG8_SCHED;
	s_add_i32 s30, s45, s9
	v_lshl_add_u64 v[172:173], v[172:173], 0, s[92:93]
	s_mov_b32 m0, s30
	ds_read_b128 v[162:165], v216 offset:49152
	ds_read_b128 v[166:169], v216 offset:50176
	ds_read_b128 v[192:195], v216 offset:51200
	ds_read_b128 v[196:199], v216 offset:52224
	ds_read_b128 v[200:203], v216 offset:53248
	ds_read_b128 v[204:207], v216 offset:54272
	ds_read_b128 v[208:211], v216 offset:55296
	ds_read_b128 v[212:215], v216 offset:56320
	global_load_lds_dwordx4 v[172:173], off
	s_add_i32 m0, s30, 0x2000
	s_add_u32 s28, s28, 0x40080
	v_lshl_add_u64 v[172:173], v[220:221], 0, s[92:93]
	s_addc_u32 s29, s29, 0
	s_add_i32 s30, s46, s9
	global_load_lds_dwordx4 v[172:173], off
	v_lshl_add_u64 v[172:173], s[28:29], 0, v[178:179]
	s_mov_b32 m0, s30
	s_nop 0
	global_load_lds_dwordx4 v[172:173], off
	v_lshl_add_u64 v[172:173], s[28:29], 0, v[182:183]
	s_add_i32 m0, s30, 0x2000
	s_nop 0
	global_load_lds_dwordx4 v[172:173], off
	v_lshl_add_u64 v[172:173], v[222:223], 0, s[92:93]
	s_mov_b32 m0, s85
	s_nop 0
	global_load_lds_dwordx4 v[172:173], off
	v_lshl_add_u64 v[172:173], v[224:225], 0, s[92:93]
	s_mov_b32 m0, s8
	s_nop 0
	global_load_lds_dwordx4 v[172:173], off
	s_waitcnt vmcnt(8)
	s_waitcnt lgkmcnt(0)
	s_barrier
	s_setprio 1
	s_waitcnt lgkmcnt(0)
	v_mfma_f32_16x16x32_bf16 v[82:85], v[122:125], v[162:165], v[82:85]
	v_mfma_f32_16x16x32_bf16 v[20:23], v[130:133], v[162:165], v[20:23]
	v_mfma_f32_16x16x32_bf16 v[70:73], v[122:125], v[192:195], v[70:73]
	v_mfma_f32_16x16x32_bf16 v[12:15], v[130:133], v[192:195], v[12:15]
	v_mfma_f32_16x16x32_bf16 v[60:63], v[122:125], v[200:203], v[60:63]
	v_mfma_f32_16x16x32_bf16 v[4:7], v[130:133], v[200:203], v[4:7]
	v_mfma_f32_16x16x32_bf16 v[90:93], v[122:125], v[208:211], v[90:93]
	v_mfma_f32_16x16x32_bf16 v[28:31], v[130:133], v[208:211], v[28:31]
	v_mfma_f32_16x16x32_bf16 v[82:85], v[126:129], v[166:169], v[82:85]
	v_mfma_f32_16x16x32_bf16 v[20:23], v[134:137], v[166:169], v[20:23]
	v_mfma_f32_16x16x32_bf16 v[70:73], v[126:129], v[196:199], v[70:73]
	v_mfma_f32_16x16x32_bf16 v[12:15], v[134:137], v[196:199], v[12:15]
	v_mfma_f32_16x16x32_bf16 v[60:63], v[126:129], v[204:207], v[60:63]
	v_mfma_f32_16x16x32_bf16 v[4:7], v[134:137], v[204:207], v[4:7]
	v_mfma_f32_16x16x32_bf16 v[90:93], v[126:129], v[212:215], v[90:93]
	v_mfma_f32_16x16x32_bf16 v[28:31], v[134:137], v[212:215], v[28:31]
	v_mfma_f32_16x16x32_bf16 v[74:77], v[146:149], v[162:165], v[74:77]
	v_mfma_f32_16x16x32_bf16 v[16:19], v[154:157], v[162:165], v[16:19]
	v_mfma_f32_16x16x32_bf16 v[66:69], v[146:149], v[192:195], v[66:69]
	v_mfma_f32_16x16x32_bf16 v[8:11], v[154:157], v[192:195], v[8:11]
	v_mfma_f32_16x16x32_bf16 v[56:59], v[146:149], v[200:203], v[56:59]
	v_mfma_f32_16x16x32_bf16 v[0:3], v[154:157], v[200:203], v[0:3]
	v_mfma_f32_16x16x32_bf16 v[86:89], v[146:149], v[208:211], v[86:89]
	v_mfma_f32_16x16x32_bf16 v[24:27], v[154:157], v[208:211], v[24:27]
	v_mfma_f32_16x16x32_bf16 v[74:77], v[150:153], v[166:169], v[74:77]
	v_mfma_f32_16x16x32_bf16 v[16:19], v[158:161], v[166:169], v[16:19]
	v_mfma_f32_16x16x32_bf16 v[66:69], v[150:153], v[196:199], v[66:69]
	v_mfma_f32_16x16x32_bf16 v[8:11], v[158:161], v[196:199], v[8:11]
	v_mfma_f32_16x16x32_bf16 v[56:59], v[150:153], v[204:207], v[56:59]
	v_mfma_f32_16x16x32_bf16 v[0:3], v[158:161], v[204:207], v[0:3]
	v_mfma_f32_16x16x32_bf16 v[86:89], v[150:153], v[212:215], v[86:89]
	v_mfma_f32_16x16x32_bf16 v[24:27], v[158:161], v[212:215], v[24:27]
	s_setprio 0
	s_barrier
	s_add_i32 s44, s44, 2
	s_add_u32 s26, s26, 0x100
	s_addc_u32 s27, s27, 0
	s_add_u32 s42, s42, 0x100
	s_addc_u32 s43, s43, 0
	s_cmp_gt_u32 s44, 13
	s_cbranch_scc0 .LBB0_242
	s_and_b64 vcc, exec, s[16:17]
	s_cbranch_vccz .LBB0_245
	s_barrier

; DI unsigned pk2(float lo, float hi) { f32x2_t v = {lo, hi}; bf16x2_t b = __builtin_convertvector(v, bf16x2_t); return __builtin_bit_cast(unsigned, b); }
; template <int CTRL> DI float dppf(float v) { return __int_as_float(__builtin_amdgcn_mov_dpp(__float_as_int(v), CTRL, 0xf, 0xf, true)); }
;     DI void operator()(pg8::f32x4 (&acc)[2][2][4][2], const pg8::Unit& u, int wr, int wc, int fr, int fq) const {
;     ...
;                 for (int m = 0; m < 4; ++m) {
;                     float cv[2][4];
; #pragma unroll
;                     for (int bj = 0; bj < 2; ++bj) {
;                         const pg8::f32x4 cur = acc[ai][bj][m][n];
;                         pg8::f32x4 prv;
;                         if (m > 0) prv = acc[ai][bj][m > 0 ? m - 1 : 0][n]; else prv = (pg8::f32x4){hal[bj][0], hal[bj][1], hal[bj][2], hal[bj][3]};
; #pragma unroll
;                         for (int i = 0; i < 4; ++i) {
;                             const float q1 = dppf<0x121>(prv[i]), q2 = dppf<0x122>(prv[i]);
;                             const float p1 = __int_as_float(__builtin_amdgcn_update_dpp(__float_as_int(q1), __float_as_int(cur[i]), 0x111, 0xf, 0xf, false));
;                             const float p2 = __int_as_float(__builtin_amdgcn_update_dpp(__float_as_int(q2), __float_as_int(cur[i]), 0x112, 0xf, 0xf, false));
;                             cv[bj][i] = cb[bj][i] + w0[bj][i] * p2 + w1[bj][i] * p1 + w2[bj][i] * cur[i];
;                         }
;                     }
;                     float o[4];
; #pragma unroll
;                     for (int i = 0; i < 4; ++i) o[i] = gelu_tanh(cv[0][i]) * cv[1][i];
;                     const int row = u.pm * 256 + ai * 128 + wr * 64 + m * 16 + fr;
;                     v2u w; w.x = pk2(o[0], o[1]); w.y = pk2(o[2], o[3]);
;                     *(v2u*)(a_row(wsb, row) + u.pn * 128 + wc * 32 + 8 * fq + 4 * n) = w;
;                 }
.LBB0_261:
	s_waitcnt vmcnt(1)
	v_pk_fma_f32 v[172:173], v[122:123], v[214:215], v[134:135]
	v_pk_fma_f32 v[206:207], v[124:125], v[206:207], v[136:137]
	v_pk_fma_f32 v[172:173], v[126:127], v[212:213], v[172:173]
	v_pk_fma_f32 v[204:205], v[128:129], v[204:205], v[206:207]
	v_pk_fma_f32 v[172:173], v[158:159], v[130:131], v[172:173]
	v_pk_fma_f32 v[204:205], v[160:161], v[132:133], v[204:205]
	v_pk_mul_f32 v[212:213], v[172:173], v[172:173]
	v_pk_mul_f32 v[206:207], v[204:205], v[204:205]
	v_fmamk_f32 v64, v212, 0xbdd2d3e7, v175
	v_mul_f32_e32 v64, v172, v64
	v_fmamk_f32 v163, v213, 0xbdd2d3e7, v175
	v_exp_f32_e32 v64, v64
	v_mul_f32_e32 v163, v173, v163
	v_exp_f32_e32 v163, v163
	s_waitcnt vmcnt(0)
	v_pk_fma_f32 v[164:165], v[104:105], v[164:165], v[120:121]
	v_add_f32_e32 v64, 1.0, v64
	v_rcp_f32_e32 v212, v64
	v_add_f32_e32 v64, 1.0, v163
	v_rcp_f32_e32 v213, v64
	v_fmamk_f32 v64, v206, 0xbdd2d3e7, v175
	v_mul_f32_e32 v64, v204, v64
	v_fmamk_f32 v163, v207, 0xbdd2d3e7, v175
	v_exp_f32_e32 v64, v64
	v_mul_f32_e32 v163, v205, v163
	v_exp_f32_e32 v163, v163
	v_pk_fma_f32 v[164:165], v[108:109], v[166:167], v[164:165]
	v_add_f32_e32 v64, 1.0, v64
	v_rcp_f32_e32 v206, v64
	v_add_f32_e32 v64, 1.0, v163
	v_rcp_f32_e32 v207, v64
	v_pk_fma_f32 v[210:211], v[102:103], v[210:211], v[118:119]
	v_pk_fma_f32 v[164:165], v[156:157], v[116:117], v[164:165]
	s_lshl_b32 s22, s22, 7
	v_pk_mul_f32 v[166:167], v[204:205], v[206:207]
	v_pk_fma_f32 v[208:209], v[106:107], v[208:209], v[210:211]
	v_pk_mul_f32 v[164:165], v[166:167], v[164:165]
	s_ashr_i32 s23, s22, 31
	v_pk_fma_f32 v[208:209], v[154:155], v[114:115], v[208:209]
	v_pk_mul_f32 v[172:173], v[172:173], v[212:213]
	v_cvt_pk_bf16_f32 v221, v164, v165
	v_pk_mul_f32 v[164:165], v[142:143], v[200:201] op_sel_hi:[1,0]
	v_pk_mul_f32 v[142:143], v[138:139], v[200:201] op_sel_hi:[1,0]
	v_lshl_add_u64 v[138:139], s[22:23], 1, v[168:169]
	s_lshl_b32 s72, s6, 1
	v_pk_mul_f32 v[172:173], v[172:173], v[208:209]
	v_lshl_add_u64 v[138:139], v[138:139], 0, s[72:73]
	v_lshlrev_b32_e32 v64, 1, v184
	v_cvt_pk_bf16_f32 v220, v172, v173
	v_lshl_add_u64 v[138:139], v[138:139], 0, v[64:65]
	v_pk_mul_f32 v[144:145], v[144:145], v[200:201] op_sel_hi:[1,0]
	v_pk_mul_f32 v[140:141], v[140:141], v[200:201] op_sel_hi:[1,0]
	v_mov_b32_dpp v206, v158 row_ror:1 row_mask:0xf bank_mask:0xf bound_ctrl:1
	v_mov_b32_dpp v208, v158 row_ror:2 row_mask:0xf bank_mask:0xf bound_ctrl:1
	v_mov_b32_dpp v207, v159 row_ror:1 row_mask:0xf bank_mask:0xf bound_ctrl:1
	v_mov_b32_dpp v209, v159 row_ror:2 row_mask:0xf bank_mask:0xf bound_ctrl:1
	v_mov_b32_dpp v158, v160 row_ror:1 row_mask:0xf bank_mask:0xf bound_ctrl:1
	v_mov_b32_dpp v160, v160 row_ror:2 row_mask:0xf bank_mask:0xf bound_ctrl:1
	v_mov_b32_dpp v159, v161 row_ror:1 row_mask:0xf bank_mask:0xf bound_ctrl:1
	v_mov_b32_dpp v161, v161 row_ror:2 row_mask:0xf bank_mask:0xf bound_ctrl:1
	v_mov_b32_dpp v168, v154 row_ror:1 row_mask:0xf bank_mask:0xf bound_ctrl:1
	v_mov_b32_dpp v204, v154 row_ror:2 row_mask:0xf bank_mask:0xf bound_ctrl:1
	v_mov_b32_dpp v169, v155 row_ror:1 row_mask:0xf bank_mask:0xf bound_ctrl:1
	v_mov_b32_dpp v205, v155 row_ror:2 row_mask:0xf bank_mask:0xf bound_ctrl:1
	v_mov_b32_dpp v154, v156 row_ror:1 row_mask:0xf bank_mask:0xf bound_ctrl:1
	v_mov_b32_dpp v156, v156 row_ror:2 row_mask:0xf bank_mask:0xf bound_ctrl:1
	v_mov_b32_dpp v155, v157 row_ror:1 row_mask:0xf bank_mask:0xf bound_ctrl:1
	v_mov_b32_dpp v157, v157 row_ror:2 row_mask:0xf bank_mask:0xf bound_ctrl:1
	v_cndmask_b32_e64 v138, 0, 1, s[26:27]
	v_mov_b32_dpp v206, v164 row_shr:1 row_mask:0xf bank_mask:0xf
	v_mov_b32_dpp v208, v164 row_shr:2 row_mask:0xf bank_mask:0xf
	v_mov_b32_dpp v207, v165 row_shr:1 row_mask:0xf bank_mask:0xf
	v_mov_b32_dpp v209, v165 row_shr:2 row_mask:0xf bank_mask:0xf
	v_mov_b32_dpp v158, v144 row_shr:1 row_mask:0xf bank_mask:0xf
	v_mov_b32_dpp v160, v144 row_shr:2 row_mask:0xf bank_mask:0xf
	v_mov_b32_dpp v159, v145 row_shr:1 row_mask:0xf bank_mask:0xf
	v_mov_b32_dpp v161, v145 row_shr:2 row_mask:0xf bank_mask:0xf
	v_mov_b32_dpp v168, v142 row_shr:1 row_mask:0xf bank_mask:0xf
	v_mov_b32_dpp v204, v142 row_shr:2 row_mask:0xf bank_mask:0xf
	v_mov_b32_dpp v169, v143 row_shr:1 row_mask:0xf bank_mask:0xf
	v_mov_b32_dpp v205, v143 row_shr:2 row_mask:0xf bank_mask:0xf
	v_mov_b32_dpp v154, v140 row_shr:1 row_mask:0xf bank_mask:0xf
	v_mov_b32_dpp v156, v140 row_shr:2 row_mask:0xf bank_mask:0xf
	v_mov_b32_dpp v155, v141 row_shr:1 row_mask:0xf bank_mask:0xf
	v_mov_b32_dpp v157, v141 row_shr:2 row_mask:0xf bank_mask:0xf
	s_mov_b64 s[30:31], -1
	v_cmp_ne_u32_e64 s[44:45], 1, v138
	s_andn2_b64 vcc, exec, s[26:27]
	v_add_u32_e32 v199, 0xfffff510, v201
	s_cbranch_vccnz .LBB0_263
	s_add_u32 s26, s55, s24
	s_addc_u32 s27, s58, s25
	v_mov_b64_e32 v[138:139], s[26:27]
	v_mad_u64_u32 v[166:167], s[26:27], v199, s0, v[138:139]
	s_mov_b64 s[30:31], 0

; DI unsigned pk2(float lo, float hi) { f32x2_t v = {lo, hi}; bf16x2_t b = __builtin_convertvector(v, bf16x2_t); return __builtin_bit_cast(unsigned, b); }
; template <int CTRL> DI float dppf(float v) { return __int_as_float(__builtin_amdgcn_mov_dpp(__float_as_int(v), CTRL, 0xf, 0xf, true)); }
;     DI void operator()(pg8::f32x4 (&acc)[2][2][4][2], const pg8::Unit& u, int wr, int wc, int fr, int fq) const {
;     ...
;                 for (int m = 0; m < 4; ++m) {
;                     float cv[2][4];
; #pragma unroll
;                     for (int bj = 0; bj < 2; ++bj) {
;                         const pg8::f32x4 cur = acc[ai][bj][m][n];
;                         pg8::f32x4 prv;
;                         if (m > 0) prv = acc[ai][bj][m > 0 ? m - 1 : 0][n]; else prv = (pg8::f32x4){hal[bj][0], hal[bj][1], hal[bj][2], hal[bj][3]};
; #pragma unroll
;                         for (int i = 0; i < 4; ++i) {
;                             const float q1 = dppf<0x121>(prv[i]), q2 = dppf<0x122>(prv[i]);
;                             const float p1 = __int_as_float(__builtin_amdgcn_update_dpp(__float_as_int(q1), __float_as_int(cur[i]), 0x111, 0xf, 0xf, false));
;                             const float p2 = __int_as_float(__builtin_amdgcn_update_dpp(__float_as_int(q2), __float_as_int(cur[i]), 0x112, 0xf, 0xf, false));
;                             cv[bj][i] = cb[bj][i] + w0[bj][i] * p2 + w1[bj][i] * p1 + w2[bj][i] * cur[i];
;                         }
;                     }
;                     float o[4];
; #pragma unroll
;                     for (int i = 0; i < 4; ++i) o[i] = gelu_tanh(cv[0][i]) * cv[1][i];
;                     const int row = u.pm * 256 + ai * 128 + wr * 64 + m * 16 + fr;
;                     v2u w; w.x = pk2(o[0], o[1]); w.y = pk2(o[2], o[3]);
;                     *(v2u*)(a_row(wsb, row) + u.pn * 128 + wc * 32 + 8 * fq + 4 * n) = w;
;                 }
.LBB0_265:
	v_pk_fma_f32 v[172:173], v[122:123], v[208:209], v[134:135]
	v_pk_fma_f32 v[160:161], v[124:125], v[160:161], v[136:137]
	v_pk_fma_f32 v[172:173], v[126:127], v[206:207], v[172:173]
	v_pk_fma_f32 v[158:159], v[128:129], v[158:159], v[160:161]
	v_pk_fma_f32 v[172:173], v[164:165], v[130:131], v[172:173]
	v_pk_fma_f32 v[158:159], v[144:145], v[132:133], v[158:159]
	v_pk_mul_f32 v[206:207], v[172:173], v[172:173]
	v_pk_mul_f32 v[160:161], v[158:159], v[158:159]
	v_fmamk_f32 v139, v206, 0xbdd2d3e7, v175
	v_mul_f32_e32 v139, v172, v139
	v_fmamk_f32 v163, v207, 0xbdd2d3e7, v175
	v_exp_f32_e32 v139, v139
	v_mul_f32_e32 v163, v173, v163
	v_exp_f32_e32 v163, v163
	v_pk_fma_f32 v[204:205], v[102:103], v[204:205], v[118:119]
	v_add_f32_e32 v139, 1.0, v139
	v_rcp_f32_e32 v206, v139
	v_add_f32_e32 v139, 1.0, v163
	v_rcp_f32_e32 v207, v139
	v_fmamk_f32 v139, v160, 0xbdd2d3e7, v175
	v_mul_f32_e32 v139, v158, v139
	v_fmamk_f32 v160, v161, 0xbdd2d3e7, v175
	v_exp_f32_e32 v139, v139
	v_mul_f32_e32 v160, v159, v160
	v_exp_f32_e32 v163, v160
	v_pk_fma_f32 v[168:169], v[106:107], v[168:169], v[204:205]
	v_pk_mul_f32 v[172:173], v[172:173], v[206:207]
	v_pk_fma_f32 v[168:169], v[142:143], v[114:115], v[168:169]
	v_add_f32_e32 v139, 1.0, v139
	v_pk_mul_f32 v[160:161], v[172:173], v[168:169]
	v_rcp_f32_e32 v168, v139
	v_add_f32_e32 v139, 1.0, v163
	v_rcp_f32_e32 v169, v139
	v_pk_fma_f32 v[156:157], v[104:105], v[156:157], v[120:121]
	v_pk_mul_f32 v[112:113], v[112:113], v[198:199] op_sel_hi:[1,0]
	v_pk_fma_f32 v[154:155], v[108:109], v[154:155], v[156:157]
	v_pk_mul_f32 v[156:157], v[158:159], v[168:169]
	v_pk_fma_f32 v[154:155], v[140:141], v[116:117], v[154:155]
	v_pk_mul_f32 v[100:101], v[100:101], v[198:199] op_sel_hi:[1,0]
	v_pk_mul_f32 v[154:155], v[156:157], v[154:155]
	v_cvt_pk_bf16_f32 v222, v160, v161
	v_cvt_pk_bf16_f32 v223, v154, v155
	v_pk_mul_f32 v[154:155], v[110:111], v[198:199] op_sel_hi:[1,0]
	v_lshl_add_u64 v[110:111], s[22:23], 1, v[166:167]
	v_lshl_add_u64 v[110:111], v[110:111], 0, s[72:73]
	v_lshl_add_u64 v[110:111], v[110:111], 0, v[64:65]
	v_pk_mul_f32 v[98:99], v[98:99], v[198:199] op_sel_hi:[1,0]
	v_mov_b32_dpp v166, v164 row_ror:1 row_mask:0xf bank_mask:0xf bound_ctrl:1
	v_mov_b32_dpp v168, v164 row_ror:2 row_mask:0xf bank_mask:0xf bound_ctrl:1
	v_mov_b32_dpp v167, v165 row_ror:1 row_mask:0xf bank_mask:0xf bound_ctrl:1
	v_mov_b32_dpp v169, v165 row_ror:2 row_mask:0xf bank_mask:0xf bound_ctrl:1
	v_mov_b32_dpp v156, v144 row_ror:1 row_mask:0xf bank_mask:0xf bound_ctrl:1
	v_mov_b32_dpp v144, v144 row_ror:2 row_mask:0xf bank_mask:0xf bound_ctrl:1
	v_mov_b32_dpp v157, v145 row_ror:1 row_mask:0xf bank_mask:0xf bound_ctrl:1
	v_mov_b32_dpp v145, v145 row_ror:2 row_mask:0xf bank_mask:0xf bound_ctrl:1
	v_mov_b32_dpp v160, v142 row_ror:1 row_mask:0xf bank_mask:0xf bound_ctrl:1
	v_mov_b32_dpp v164, v142 row_ror:2 row_mask:0xf bank_mask:0xf bound_ctrl:1
	v_mov_b32_dpp v161, v143 row_ror:1 row_mask:0xf bank_mask:0xf bound_ctrl:1
	v_mov_b32_dpp v165, v143 row_ror:2 row_mask:0xf bank_mask:0xf bound_ctrl:1
	v_mov_b32_dpp v142, v140 row_ror:1 row_mask:0xf bank_mask:0xf bound_ctrl:1
	v_mov_b32_dpp v140, v140 row_ror:2 row_mask:0xf bank_mask:0xf bound_ctrl:1
	v_mov_b32_dpp v143, v141 row_ror:1 row_mask:0xf bank_mask:0xf bound_ctrl:1
	v_mov_b32_dpp v141, v141 row_ror:2 row_mask:0xf bank_mask:0xf bound_ctrl:1
	v_mov_b32_dpp v166, v154 row_shr:1 row_mask:0xf bank_mask:0xf
	v_mov_b32_dpp v168, v154 row_shr:2 row_mask:0xf bank_mask:0xf
	v_mov_b32_dpp v167, v155 row_shr:1 row_mask:0xf bank_mask:0xf
	v_mov_b32_dpp v169, v155 row_shr:2 row_mask:0xf bank_mask:0xf
	v_mov_b32_dpp v156, v112 row_shr:1 row_mask:0xf bank_mask:0xf
	v_mov_b32_dpp v144, v112 row_shr:2 row_mask:0xf bank_mask:0xf
	v_mov_b32_dpp v157, v113 row_shr:1 row_mask:0xf bank_mask:0xf
	v_mov_b32_dpp v145, v113 row_shr:2 row_mask:0xf bank_mask:0xf
	v_mov_b32_dpp v160, v98 row_shr:1 row_mask:0xf bank_mask:0xf
	v_mov_b32_dpp v164, v98 row_shr:2 row_mask:0xf bank_mask:0xf
	v_mov_b32_dpp v161, v99 row_shr:1 row_mask:0xf bank_mask:0xf
	v_mov_b32_dpp v165, v99 row_shr:2 row_mask:0xf bank_mask:0xf
	v_mov_b32_dpp v142, v100 row_shr:1 row_mask:0xf bank_mask:0xf
	v_mov_b32_dpp v140, v100 row_shr:2 row_mask:0xf bank_mask:0xf
	v_mov_b32_dpp v143, v101 row_shr:1 row_mask:0xf bank_mask:0xf
	v_mov_b32_dpp v141, v101 row_shr:2 row_mask:0xf bank_mask:0xf
	s_mov_b64 s[26:27], -1
	s_and_b64 vcc, exec, s[44:45]
	v_add_u32_e32 v197, 0xfffff520, v201
	s_cbranch_vccnz .LBB0_267
	s_add_u32 s26, s55, s24
	s_addc_u32 s27, s58, s25
	v_mov_b64_e32 v[110:111], s[26:27]
	v_mad_u64_u32 v[158:159], s[26:27], v197, s0, v[110:111]
	s_mov_b64 s[26:27], 0

; DI unsigned pk2(float lo, float hi) { f32x2_t v = {lo, hi}; bf16x2_t b = __builtin_convertvector(v, bf16x2_t); return __builtin_bit_cast(unsigned, b); }
; template <int CTRL> DI float dppf(float v) { return __int_as_float(__builtin_amdgcn_mov_dpp(__float_as_int(v), CTRL, 0xf, 0xf, true)); }
;     DI void operator()(pg8::f32x4 (&acc)[2][2][4][2], const pg8::Unit& u, int wr, int wc, int fr, int fq) const {
;     ...
;                 for (int m = 0; m < 4; ++m) {
;                     float cv[2][4];
; #pragma unroll
;                     for (int bj = 0; bj < 2; ++bj) {
;                         const pg8::f32x4 cur = acc[ai][bj][m][n];
;                         pg8::f32x4 prv;
;                         if (m > 0) prv = acc[ai][bj][m > 0 ? m - 1 : 0][n]; else prv = (pg8::f32x4){hal[bj][0], hal[bj][1], hal[bj][2], hal[bj][3]};
; #pragma unroll
;                         for (int i = 0; i < 4; ++i) {
;                             const float q1 = dppf<0x121>(prv[i]), q2 = dppf<0x122>(prv[i]);
;                             const float p1 = __int_as_float(__builtin_amdgcn_update_dpp(__float_as_int(q1), __float_as_int(cur[i]), 0x111, 0xf, 0xf, false));
;                             const float p2 = __int_as_float(__builtin_amdgcn_update_dpp(__float_as_int(q2), __float_as_int(cur[i]), 0x112, 0xf, 0xf, false));
;                             cv[bj][i] = cb[bj][i] + w0[bj][i] * p2 + w1[bj][i] * p1 + w2[bj][i] * cur[i];
;                         }
;                     }
;                     float o[4];
; #pragma unroll
;                     for (int i = 0; i < 4; ++i) o[i] = gelu_tanh(cv[0][i]) * cv[1][i];
;                     const int row = u.pm * 256 + ai * 128 + wr * 64 + m * 16 + fr;
;                     v2u w; w.x = pk2(o[0], o[1]); w.y = pk2(o[2], o[3]);
;                     *(v2u*)(a_row(wsb, row) + u.pn * 128 + wc * 32 + 8 * fq + 4 * n) = w;
;                 }
.LBB0_269:
	v_pk_fma_f32 v[168:169], v[122:123], v[168:169], v[134:135]
	v_pk_fma_f32 v[144:145], v[124:125], v[144:145], v[136:137]
	v_pk_fma_f32 v[166:167], v[126:127], v[166:167], v[168:169]
	v_pk_fma_f32 v[144:145], v[128:129], v[156:157], v[144:145]
	v_pk_fma_f32 v[166:167], v[154:155], v[130:131], v[166:167]
	v_pk_fma_f32 v[144:145], v[112:113], v[132:133], v[144:145]
	v_pk_mul_f32 v[168:169], v[166:167], v[166:167]
	v_pk_mul_f32 v[156:157], v[144:145], v[144:145]
	v_fmamk_f32 v111, v168, 0xbdd2d3e7, v175
	v_mul_f32_e32 v111, v166, v111
	v_fmamk_f32 v139, v169, 0xbdd2d3e7, v175
	v_exp_f32_e32 v111, v111
	v_mul_f32_e32 v139, v167, v139
	v_exp_f32_e32 v139, v139
	v_pk_fma_f32 v[164:165], v[102:103], v[164:165], v[118:119]
	v_add_f32_e32 v111, 1.0, v111
	v_rcp_f32_e32 v168, v111
	v_add_f32_e32 v111, 1.0, v139
	v_rcp_f32_e32 v169, v111
	v_fmamk_f32 v111, v156, 0xbdd2d3e7, v175
	v_mul_f32_e32 v111, v144, v111
	v_fmamk_f32 v139, v157, 0xbdd2d3e7, v175
	v_exp_f32_e32 v111, v111
	v_mul_f32_e32 v139, v145, v139
	v_exp_f32_e32 v139, v139
	v_pk_fma_f32 v[160:161], v[106:107], v[160:161], v[164:165]
	v_pk_mul_f32 v[164:165], v[166:167], v[168:169]
	v_pk_fma_f32 v[160:161], v[98:99], v[114:115], v[160:161]
	v_add_f32_e32 v111, 1.0, v111
	v_pk_mul_f32 v[156:157], v[164:165], v[160:161]
	v_rcp_f32_e32 v160, v111
	v_add_f32_e32 v111, 1.0, v139
	v_rcp_f32_e32 v161, v111
	v_pk_fma_f32 v[140:141], v[104:105], v[140:141], v[120:121]
	s_mov_b64 s[26:27], -1
	v_pk_fma_f32 v[140:141], v[108:109], v[142:143], v[140:141]
	v_pk_mul_f32 v[142:143], v[144:145], v[160:161]
	v_pk_fma_f32 v[140:141], v[100:101], v[116:117], v[140:141]
	v_mov_b32_dpp v160, v154 row_ror:2 row_mask:0xf bank_mask:0xf bound_ctrl:1
	v_pk_mul_f32 v[140:141], v[142:143], v[140:141]
	v_cvt_pk_bf16_f32 v224, v156, v157
	v_cvt_pk_bf16_f32 v225, v140, v141
	v_lshl_add_u64 v[140:141], s[22:23], 1, v[158:159]
	v_lshl_add_u64 v[140:141], v[140:141], 0, s[72:73]
	v_lshl_add_u64 v[140:141], v[140:141], 0, v[64:65]
	v_mov_b32_dpp v158, v154 row_ror:1 row_mask:0xf bank_mask:0xf bound_ctrl:1
	v_mov_b32_dpp v159, v155 row_ror:1 row_mask:0xf bank_mask:0xf bound_ctrl:1
	v_mov_b32_dpp v161, v155 row_ror:2 row_mask:0xf bank_mask:0xf bound_ctrl:1
	v_mov_b32_dpp v140, v112 row_ror:1 row_mask:0xf bank_mask:0xf bound_ctrl:1
	v_mov_b32_dpp v142, v112 row_ror:2 row_mask:0xf bank_mask:0xf bound_ctrl:1
	v_mov_b32_dpp v141, v113 row_ror:1 row_mask:0xf bank_mask:0xf bound_ctrl:1
	v_mov_b32_dpp v143, v113 row_ror:2 row_mask:0xf bank_mask:0xf bound_ctrl:1
	v_mov_b32_dpp v154, v98 row_ror:1 row_mask:0xf bank_mask:0xf bound_ctrl:1
	v_mov_b32_dpp v156, v98 row_ror:2 row_mask:0xf bank_mask:0xf bound_ctrl:1
	v_mov_b32_dpp v155, v99 row_ror:1 row_mask:0xf bank_mask:0xf bound_ctrl:1
	v_mov_b32_dpp v157, v99 row_ror:2 row_mask:0xf bank_mask:0xf bound_ctrl:1
	v_mov_b32_dpp v98, v100 row_ror:1 row_mask:0xf bank_mask:0xf bound_ctrl:1
	v_mov_b32_dpp v100, v100 row_ror:2 row_mask:0xf bank_mask:0xf bound_ctrl:1
	v_mov_b32_dpp v99, v101 row_ror:1 row_mask:0xf bank_mask:0xf bound_ctrl:1
	v_mov_b32_dpp v101, v101 row_ror:2 row_mask:0xf bank_mask:0xf bound_ctrl:1
	v_mov_b32_dpp v158, v150 row_shr:1 row_mask:0xf bank_mask:0xf
	v_mov_b32_dpp v160, v150 row_shr:2 row_mask:0xf bank_mask:0xf
	v_mov_b32_dpp v159, v151 row_shr:1 row_mask:0xf bank_mask:0xf
	v_mov_b32_dpp v161, v151 row_shr:2 row_mask:0xf bank_mask:0xf
	v_mov_b32_dpp v140, v152 row_shr:1 row_mask:0xf bank_mask:0xf
	v_mov_b32_dpp v142, v152 row_shr:2 row_mask:0xf bank_mask:0xf
	v_mov_b32_dpp v141, v153 row_shr:1 row_mask:0xf bank_mask:0xf
	v_mov_b32_dpp v143, v153 row_shr:2 row_mask:0xf bank_mask:0xf
	v_mov_b32_dpp v154, v146 row_shr:1 row_mask:0xf bank_mask:0xf
	v_mov_b32_dpp v156, v146 row_shr:2 row_mask:0xf bank_mask:0xf
	v_mov_b32_dpp v155, v147 row_shr:1 row_mask:0xf bank_mask:0xf
	v_mov_b32_dpp v157, v147 row_shr:2 row_mask:0xf bank_mask:0xf
	v_mov_b32_dpp v98, v148 row_shr:1 row_mask:0xf bank_mask:0xf
	v_mov_b32_dpp v100, v148 row_shr:2 row_mask:0xf bank_mask:0xf
	v_mov_b32_dpp v99, v149 row_shr:1 row_mask:0xf bank_mask:0xf
	v_mov_b32_dpp v101, v149 row_shr:2 row_mask:0xf bank_mask:0xf
	s_and_b64 vcc, exec, s[44:45]
	v_add_u32_e32 v164, 0xfffff530, v201
	s_cbranch_vccnz .LBB0_271
	s_add_u32 s26, s55, s24
	s_addc_u32 s27, s58, s25
	v_mov_b64_e32 v[112:113], s[26:27]
	v_mad_u64_u32 v[144:145], s[26:27], v164, s0, v[112:113]
	s_mov_b64 s[26:27], 0

; DI unsigned pk2(float lo, float hi) { f32x2_t v = {lo, hi}; bf16x2_t b = __builtin_convertvector(v, bf16x2_t); return __builtin_bit_cast(unsigned, b); }
; template <int CTRL> DI float dppf(float v) { return __int_as_float(__builtin_amdgcn_mov_dpp(__float_as_int(v), CTRL, 0xf, 0xf, true)); }
;     DI void operator()(pg8::f32x4 (&acc)[2][2][4][2], const pg8::Unit& u, int wr, int wc, int fr, int fq) const {
;     ...
;                 for (int m = 0; m < 4; ++m) {
;                     float cv[2][4];
; #pragma unroll
;                     for (int bj = 0; bj < 2; ++bj) {
;                         const pg8::f32x4 cur = acc[ai][bj][m][n];
;                         pg8::f32x4 prv;
;                         if (m > 0) prv = acc[ai][bj][m > 0 ? m - 1 : 0][n]; else prv = (pg8::f32x4){hal[bj][0], hal[bj][1], hal[bj][2], hal[bj][3]};
; #pragma unroll
;                         for (int i = 0; i < 4; ++i) {
;                             const float q1 = dppf<0x121>(prv[i]), q2 = dppf<0x122>(prv[i]);
;                             const float p1 = __int_as_float(__builtin_amdgcn_update_dpp(__float_as_int(q1), __float_as_int(cur[i]), 0x111, 0xf, 0xf, false));
;                             const float p2 = __int_as_float(__builtin_amdgcn_update_dpp(__float_as_int(q2), __float_as_int(cur[i]), 0x112, 0xf, 0xf, false));
;                             cv[bj][i] = cb[bj][i] + w0[bj][i] * p2 + w1[bj][i] * p1 + w2[bj][i] * cur[i];
;                         }
;                     }
;                     float o[4];
; #pragma unroll
;                     for (int i = 0; i < 4; ++i) o[i] = gelu_tanh(cv[0][i]) * cv[1][i];
;                     const int row = u.pm * 256 + ai * 128 + wr * 64 + m * 16 + fr;
;                     v2u w; w.x = pk2(o[0], o[1]); w.y = pk2(o[2], o[3]);
;                     *(v2u*)(a_row(wsb, row) + u.pn * 128 + wc * 32 + 8 * fq + 4 * n) = w;
;                 }
.LBB0_273:
	v_pk_fma_f32 v[160:161], v[122:123], v[160:161], v[134:135]
	v_pk_fma_f32 v[142:143], v[124:125], v[142:143], v[136:137]
	v_pk_fma_f32 v[158:159], v[126:127], v[158:159], v[160:161]
	v_pk_fma_f32 v[140:141], v[128:129], v[140:141], v[142:143]
	v_pk_fma_f32 v[150:151], v[150:151], v[130:131], v[158:159]
	v_pk_fma_f32 v[140:141], v[152:153], v[132:133], v[140:141]
	v_pk_mul_f32 v[158:159], v[150:151], v[150:151]
	v_pk_mul_f32 v[142:143], v[140:141], v[140:141]
	v_fmamk_f32 v111, v158, 0xbdd2d3e7, v175
	v_mul_f32_e32 v111, v150, v111
	v_fmamk_f32 v113, v159, 0xbdd2d3e7, v175
	v_exp_f32_e32 v111, v111
	v_mul_f32_e32 v113, v151, v113
	v_exp_f32_e32 v113, v113
	v_pk_fma_f32 v[156:157], v[102:103], v[156:157], v[118:119]
	v_add_f32_e32 v111, 1.0, v111
	v_rcp_f32_e32 v158, v111
	v_add_f32_e32 v111, 1.0, v113
	v_rcp_f32_e32 v159, v111
	v_fmamk_f32 v111, v142, 0xbdd2d3e7, v175
	v_mul_f32_e32 v111, v140, v111
	v_fmamk_f32 v113, v143, 0xbdd2d3e7, v175
	v_exp_f32_e32 v111, v111
	v_mul_f32_e32 v113, v141, v113
	v_exp_f32_e32 v113, v113
	v_pk_fma_f32 v[154:155], v[106:107], v[154:155], v[156:157]
	v_pk_mul_f32 v[150:151], v[150:151], v[158:159]
	v_pk_fma_f32 v[146:147], v[146:147], v[114:115], v[154:155]
	v_add_f32_e32 v111, 1.0, v111
	v_pk_mul_f32 v[142:143], v[150:151], v[146:147]
	v_rcp_f32_e32 v146, v111
	v_add_f32_e32 v111, 1.0, v113
	v_rcp_f32_e32 v147, v111
	v_pk_fma_f32 v[100:101], v[104:105], v[100:101], v[120:121]
	s_addk_i32 s34, 0x80
	v_pk_fma_f32 v[98:99], v[108:109], v[98:99], v[100:101]
	v_pk_mul_f32 v[100:101], v[140:141], v[146:147]
	v_pk_fma_f32 v[98:99], v[148:149], v[116:117], v[98:99]
	s_ashr_i32 s30, s34, 12
	v_pk_mul_f32 v[98:99], v[100:101], v[98:99]
	v_cvt_pk_bf16_f32 v232, v142, v143
	v_cvt_pk_bf16_f32 v233, v98, v99
	v_lshl_add_u64 v[98:99], s[22:23], 1, v[144:145]
	v_lshl_add_u64 v[98:99], v[98:99], 0, s[72:73]
	v_lshl_add_u64 v[98:99], v[98:99], 0, v[64:65]
	ds_read_b128 v[140:143], v218
	ds_read_b128 v[144:147], v218 offset:256
	s_ashr_i32 s31, s30, 31
	s_and_b32 s49, s34, 0xfc0
	s_lshl_b64 s[26:27], s[30:31], 23
	v_pk_mul_f32 v[84:85], v[84:85], v[196:197] op_sel_hi:[1,0]
	v_pk_mul_f32 v[82:83], v[82:83], v[196:197] op_sel_hi:[1,0]
	v_pk_mul_f32 v[76:77], v[76:77], v[196:197] op_sel_hi:[1,0]
	v_pk_mul_f32 v[74:75], v[74:75], v[196:197] op_sel_hi:[1,0]
	s_waitcnt lgkmcnt(1)
	v_mov_b32_dpp v152, v140 row_ror:1 row_mask:0xf bank_mask:0xf bound_ctrl:1
	v_mov_b32_dpp v154, v140 row_ror:2 row_mask:0xf bank_mask:0xf bound_ctrl:1
	v_mov_b32_dpp v153, v141 row_ror:1 row_mask:0xf bank_mask:0xf bound_ctrl:1
	v_mov_b32_dpp v155, v141 row_ror:2 row_mask:0xf bank_mask:0xf bound_ctrl:1
	v_mov_b32_dpp v100, v142 row_ror:1 row_mask:0xf bank_mask:0xf bound_ctrl:1
	v_mov_b32_dpp v142, v142 row_ror:2 row_mask:0xf bank_mask:0xf bound_ctrl:1
	v_mov_b32_dpp v101, v143 row_ror:1 row_mask:0xf bank_mask:0xf bound_ctrl:1
	v_mov_b32_dpp v143, v143 row_ror:2 row_mask:0xf bank_mask:0xf bound_ctrl:1
	s_waitcnt lgkmcnt(0)
	v_mov_b32_dpp v148, v144 row_ror:1 row_mask:0xf bank_mask:0xf bound_ctrl:1
	v_mov_b32_dpp v150, v144 row_ror:2 row_mask:0xf bank_mask:0xf bound_ctrl:1
	v_mov_b32_dpp v149, v145 row_ror:1 row_mask:0xf bank_mask:0xf bound_ctrl:1
	v_mov_b32_dpp v151, v145 row_ror:2 row_mask:0xf bank_mask:0xf bound_ctrl:1
	v_mov_b32_dpp v98, v146 row_ror:1 row_mask:0xf bank_mask:0xf bound_ctrl:1
	v_mov_b32_dpp v140, v146 row_ror:2 row_mask:0xf bank_mask:0xf bound_ctrl:1
	v_mov_b32_dpp v99, v147 row_ror:1 row_mask:0xf bank_mask:0xf bound_ctrl:1
	v_mov_b32_dpp v141, v147 row_ror:2 row_mask:0xf bank_mask:0xf bound_ctrl:1
	v_or_b32_e32 v111, s49, v170
	s_cmpk_gt_u32 s49, 0xaff
	v_mov_b32_dpp v152, v82 row_shr:1 row_mask:0xf bank_mask:0xf
	v_mov_b32_dpp v154, v82 row_shr:2 row_mask:0xf bank_mask:0xf
	v_mov_b32_dpp v153, v83 row_shr:1 row_mask:0xf bank_mask:0xf
	v_mov_b32_dpp v155, v83 row_shr:2 row_mask:0xf bank_mask:0xf
	v_mov_b32_dpp v100, v84 row_shr:1 row_mask:0xf bank_mask:0xf
	v_mov_b32_dpp v142, v84 row_shr:2 row_mask:0xf bank_mask:0xf
	v_mov_b32_dpp v101, v85 row_shr:1 row_mask:0xf bank_mask:0xf
	v_mov_b32_dpp v143, v85 row_shr:2 row_mask:0xf bank_mask:0xf
	v_mov_b32_dpp v148, v74 row_shr:1 row_mask:0xf bank_mask:0xf
	v_mov_b32_dpp v150, v74 row_shr:2 row_mask:0xf bank_mask:0xf
	v_mov_b32_dpp v149, v75 row_shr:1 row_mask:0xf bank_mask:0xf
	v_mov_b32_dpp v151, v75 row_shr:2 row_mask:0xf bank_mask:0xf
	v_mov_b32_dpp v98, v76 row_shr:1 row_mask:0xf bank_mask:0xf
	v_mov_b32_dpp v140, v76 row_shr:2 row_mask:0xf bank_mask:0xf
	v_mov_b32_dpp v99, v77 row_shr:1 row_mask:0xf bank_mask:0xf
	v_mov_b32_dpp v141, v77 row_shr:2 row_mask:0xf bank_mask:0xf
	s_mov_b64 s[46:47], -1
	s_cselect_b64 s[34:35], -1, 0
	s_cmpk_lt_u32 s49, 0xb00
	v_add_u32_e32 v156, 0xfffff500, v111
	s_cbranch_scc1 .LBB0_275
	s_add_u32 s46, s55, s26
	s_addc_u32 s47, s58, s27
	v_mov_b64_e32 v[144:145], s[46:47]
	v_mad_u64_u32 v[144:145], s[46:47], v156, s0, v[144:145]
	s_mov_b64 s[46:47], 0

; DI unsigned pk2(float lo, float hi) { f32x2_t v = {lo, hi}; bf16x2_t b = __builtin_convertvector(v, bf16x2_t); return __builtin_bit_cast(unsigned, b); }
; template <int CTRL> DI float dppf(float v) { return __int_as_float(__builtin_amdgcn_mov_dpp(__float_as_int(v), CTRL, 0xf, 0xf, true)); }
;     DI void operator()(pg8::f32x4 (&acc)[2][2][4][2], const pg8::Unit& u, int wr, int wc, int fr, int fq) const {
;     ...
;                 for (int m = 0; m < 4; ++m) {
;                     float cv[2][4];
; #pragma unroll
;                     for (int bj = 0; bj < 2; ++bj) {
;                         const pg8::f32x4 cur = acc[ai][bj][m][n];
;                         pg8::f32x4 prv;
;                         if (m > 0) prv = acc[ai][bj][m > 0 ? m - 1 : 0][n]; else prv = (pg8::f32x4){hal[bj][0], hal[bj][1], hal[bj][2], hal[bj][3]};
; #pragma unroll
;                         for (int i = 0; i < 4; ++i) {
;                             const float q1 = dppf<0x121>(prv[i]), q2 = dppf<0x122>(prv[i]);
;                             const float p1 = __int_as_float(__builtin_amdgcn_update_dpp(__float_as_int(q1), __float_as_int(cur[i]), 0x111, 0xf, 0xf, false));
;                             const float p2 = __int_as_float(__builtin_amdgcn_update_dpp(__float_as_int(q2), __float_as_int(cur[i]), 0x112, 0xf, 0xf, false));
;                             cv[bj][i] = cb[bj][i] + w0[bj][i] * p2 + w1[bj][i] * p1 + w2[bj][i] * cur[i];
;                         }
;                     }
;                     float o[4];
; #pragma unroll
;                     for (int i = 0; i < 4; ++i) o[i] = gelu_tanh(cv[0][i]) * cv[1][i];
;                     const int row = u.pm * 256 + ai * 128 + wr * 64 + m * 16 + fr;
;                     v2u w; w.x = pk2(o[0], o[1]); w.y = pk2(o[2], o[3]);
;                     *(v2u*)(a_row(wsb, row) + u.pn * 128 + wc * 32 + 8 * fq + 4 * n) = w;
;                 }
.LBB0_277:
	v_pk_fma_f32 v[154:155], v[122:123], v[154:155], v[134:135]
	v_pk_fma_f32 v[142:143], v[124:125], v[142:143], v[136:137]
	v_pk_fma_f32 v[152:153], v[126:127], v[152:153], v[154:155]
	v_pk_fma_f32 v[100:101], v[128:129], v[100:101], v[142:143]
	v_pk_fma_f32 v[152:153], v[82:83], v[130:131], v[152:153]
	v_pk_fma_f32 v[100:101], v[84:85], v[132:133], v[100:101]
	v_pk_mul_f32 v[154:155], v[152:153], v[152:153]
	v_pk_mul_f32 v[142:143], v[100:101], v[100:101]
	v_fmamk_f32 v113, v154, 0xbdd2d3e7, v175
	v_mul_f32_e32 v113, v152, v113
	v_fmamk_f32 v139, v155, 0xbdd2d3e7, v175
	v_exp_f32_e32 v113, v113
	v_mul_f32_e32 v139, v153, v139
	v_exp_f32_e32 v139, v139
	v_pk_fma_f32 v[150:151], v[102:103], v[150:151], v[118:119]
	v_add_f32_e32 v113, 1.0, v113
	v_rcp_f32_e32 v154, v113
	v_add_f32_e32 v113, 1.0, v139
	v_rcp_f32_e32 v155, v113
	v_fmamk_f32 v113, v142, 0xbdd2d3e7, v175
	v_mul_f32_e32 v113, v100, v113
	v_fmamk_f32 v139, v143, 0xbdd2d3e7, v175
	v_exp_f32_e32 v113, v113
	v_mul_f32_e32 v139, v101, v139
	v_exp_f32_e32 v139, v139
	v_pk_fma_f32 v[148:149], v[106:107], v[148:149], v[150:151]
	v_pk_mul_f32 v[150:151], v[152:153], v[154:155]
	v_pk_fma_f32 v[148:149], v[74:75], v[114:115], v[148:149]
	v_add_f32_e32 v113, 1.0, v113
	v_pk_mul_f32 v[142:143], v[150:151], v[148:149]
	v_rcp_f32_e32 v148, v113
	v_add_f32_e32 v113, 1.0, v139
	v_rcp_f32_e32 v149, v113
	v_pk_fma_f32 v[140:141], v[104:105], v[140:141], v[120:121]
	v_pk_mul_f32 v[72:73], v[72:73], v[194:195] op_sel_hi:[1,0]
	v_pk_fma_f32 v[98:99], v[108:109], v[98:99], v[140:141]
	v_pk_mul_f32 v[100:101], v[100:101], v[148:149]
	v_pk_fma_f32 v[98:99], v[76:77], v[116:117], v[98:99]
	v_pk_mul_f32 v[70:71], v[70:71], v[194:195] op_sel_hi:[1,0]
	v_pk_mul_f32 v[98:99], v[100:101], v[98:99]
	v_cvt_pk_bf16_f32 v238, v142, v143
	v_cvt_pk_bf16_f32 v239, v98, v99
	v_lshl_add_u64 v[98:99], s[22:23], 1, v[144:145]
	v_lshl_add_u64 v[98:99], v[98:99], 0, s[72:73]
	v_lshl_add_u64 v[98:99], v[98:99], 0, v[64:65]
	v_pk_mul_f32 v[68:69], v[68:69], v[194:195] op_sel_hi:[1,0]
	v_pk_mul_f32 v[66:67], v[66:67], v[194:195] op_sel_hi:[1,0]
	v_mov_b32_dpp v142, v82 row_ror:1 row_mask:0xf bank_mask:0xf bound_ctrl:1
	v_mov_b32_dpp v148, v82 row_ror:2 row_mask:0xf bank_mask:0xf bound_ctrl:1
	v_mov_b32_dpp v143, v83 row_ror:1 row_mask:0xf bank_mask:0xf bound_ctrl:1
	v_mov_b32_dpp v149, v83 row_ror:2 row_mask:0xf bank_mask:0xf bound_ctrl:1
	v_mov_b32_dpp v82, v84 row_ror:1 row_mask:0xf bank_mask:0xf bound_ctrl:1
	v_mov_b32_dpp v84, v84 row_ror:2 row_mask:0xf bank_mask:0xf bound_ctrl:1
	v_mov_b32_dpp v83, v85 row_ror:1 row_mask:0xf bank_mask:0xf bound_ctrl:1
	v_mov_b32_dpp v85, v85 row_ror:2 row_mask:0xf bank_mask:0xf bound_ctrl:1
	v_mov_b32_dpp v100, v74 row_ror:1 row_mask:0xf bank_mask:0xf bound_ctrl:1
	v_mov_b32_dpp v140, v74 row_ror:2 row_mask:0xf bank_mask:0xf bound_ctrl:1
	v_mov_b32_dpp v101, v75 row_ror:1 row_mask:0xf bank_mask:0xf bound_ctrl:1
	v_mov_b32_dpp v141, v75 row_ror:2 row_mask:0xf bank_mask:0xf bound_ctrl:1
	v_mov_b32_dpp v74, v76 row_ror:1 row_mask:0xf bank_mask:0xf bound_ctrl:1
	v_mov_b32_dpp v76, v76 row_ror:2 row_mask:0xf bank_mask:0xf bound_ctrl:1
	v_mov_b32_dpp v75, v77 row_ror:1 row_mask:0xf bank_mask:0xf bound_ctrl:1
	v_mov_b32_dpp v77, v77 row_ror:2 row_mask:0xf bank_mask:0xf bound_ctrl:1
	v_cndmask_b32_e64 v98, 0, 1, s[34:35]
	v_mov_b32_dpp v142, v70 row_shr:1 row_mask:0xf bank_mask:0xf
	v_mov_b32_dpp v148, v70 row_shr:2 row_mask:0xf bank_mask:0xf
	v_mov_b32_dpp v143, v71 row_shr:1 row_mask:0xf bank_mask:0xf
	v_mov_b32_dpp v149, v71 row_shr:2 row_mask:0xf bank_mask:0xf
	v_mov_b32_dpp v82, v72 row_shr:1 row_mask:0xf bank_mask:0xf
	v_mov_b32_dpp v84, v72 row_shr:2 row_mask:0xf bank_mask:0xf
	v_mov_b32_dpp v83, v73 row_shr:1 row_mask:0xf bank_mask:0xf
	v_mov_b32_dpp v85, v73 row_shr:2 row_mask:0xf bank_mask:0xf
	v_mov_b32_dpp v100, v66 row_shr:1 row_mask:0xf bank_mask:0xf
	v_mov_b32_dpp v140, v66 row_shr:2 row_mask:0xf bank_mask:0xf
	v_mov_b32_dpp v101, v67 row_shr:1 row_mask:0xf bank_mask:0xf
	v_mov_b32_dpp v141, v67 row_shr:2 row_mask:0xf bank_mask:0xf
	v_mov_b32_dpp v74, v68 row_shr:1 row_mask:0xf bank_mask:0xf
	v_mov_b32_dpp v76, v68 row_shr:2 row_mask:0xf bank_mask:0xf
	v_mov_b32_dpp v75, v69 row_shr:1 row_mask:0xf bank_mask:0xf
	v_mov_b32_dpp v77, v69 row_shr:2 row_mask:0xf bank_mask:0xf
	s_mov_b64 s[74:75], -1
	v_cmp_ne_u32_e64 s[46:47], 1, v98
	s_andn2_b64 vcc, exec, s[34:35]
	v_add_u32_e32 v150, 0xfffff510, v111
	s_cbranch_vccnz .LBB0_279
	s_add_u32 s34, s55, s26
	s_addc_u32 s35, s58, s27
	v_mov_b64_e32 v[98:99], s[34:35]
	v_mad_u64_u32 v[98:99], s[34:35], v150, s0, v[98:99]
	s_mov_b64 s[74:75], 0

; DI unsigned pk2(float lo, float hi) { f32x2_t v = {lo, hi}; bf16x2_t b = __builtin_convertvector(v, bf16x2_t); return __builtin_bit_cast(unsigned, b); }
; template <int CTRL> DI float dppf(float v) { return __int_as_float(__builtin_amdgcn_mov_dpp(__float_as_int(v), CTRL, 0xf, 0xf, true)); }
;     DI void operator()(pg8::f32x4 (&acc)[2][2][4][2], const pg8::Unit& u, int wr, int wc, int fr, int fq) const {
;     ...
;                 for (int m = 0; m < 4; ++m) {
;                     float cv[2][4];
; #pragma unroll
;                     for (int bj = 0; bj < 2; ++bj) {
;                         const pg8::f32x4 cur = acc[ai][bj][m][n];
;                         pg8::f32x4 prv;
;                         if (m > 0) prv = acc[ai][bj][m > 0 ? m - 1 : 0][n]; else prv = (pg8::f32x4){hal[bj][0], hal[bj][1], hal[bj][2], hal[bj][3]};
; #pragma unroll
;                         for (int i = 0; i < 4; ++i) {
;                             const float q1 = dppf<0x121>(prv[i]), q2 = dppf<0x122>(prv[i]);
;                             const float p1 = __int_as_float(__builtin_amdgcn_update_dpp(__float_as_int(q1), __float_as_int(cur[i]), 0x111, 0xf, 0xf, false));
;                             const float p2 = __int_as_float(__builtin_amdgcn_update_dpp(__float_as_int(q2), __float_as_int(cur[i]), 0x112, 0xf, 0xf, false));
;                             cv[bj][i] = cb[bj][i] + w0[bj][i] * p2 + w1[bj][i] * p1 + w2[bj][i] * cur[i];
;                         }
;                     }
;                     float o[4];
; #pragma unroll
;                     for (int i = 0; i < 4; ++i) o[i] = gelu_tanh(cv[0][i]) * cv[1][i];
;                     const int row = u.pm * 256 + ai * 128 + wr * 64 + m * 16 + fr;
;                     v2u w; w.x = pk2(o[0], o[1]); w.y = pk2(o[2], o[3]);
;                     *(v2u*)(a_row(wsb, row) + u.pn * 128 + wc * 32 + 8 * fq + 4 * n) = w;
;                 }
.LBB0_281:
	v_pk_fma_f32 v[148:149], v[122:123], v[148:149], v[134:135]
	v_pk_fma_f32 v[84:85], v[124:125], v[84:85], v[136:137]
	v_pk_fma_f32 v[142:143], v[126:127], v[142:143], v[148:149]
	v_pk_fma_f32 v[82:83], v[128:129], v[82:83], v[84:85]
	v_pk_fma_f32 v[142:143], v[70:71], v[130:131], v[142:143]
	v_pk_fma_f32 v[82:83], v[72:73], v[132:133], v[82:83]
	v_pk_mul_f32 v[148:149], v[142:143], v[142:143]
	v_pk_mul_f32 v[84:85], v[82:83], v[82:83]
	v_fmamk_f32 v113, v148, 0xbdd2d3e7, v175
	v_mul_f32_e32 v113, v142, v113
	v_fmamk_f32 v139, v149, 0xbdd2d3e7, v175
	v_exp_f32_e32 v113, v113
	v_mul_f32_e32 v139, v143, v139
	v_exp_f32_e32 v139, v139
	v_fmamk_f32 v84, v84, 0xbdd2d3e7, v175
	v_add_f32_e32 v113, 1.0, v113
	v_rcp_f32_e32 v148, v113
	v_add_f32_e32 v113, 1.0, v139
	v_mul_f32_e32 v84, v82, v84
	v_rcp_f32_e32 v149, v113
	v_exp_f32_e32 v113, v84
	v_fmamk_f32 v84, v85, 0xbdd2d3e7, v175
	v_mul_f32_e32 v84, v83, v84
	v_exp_f32_e32 v139, v84
	v_pk_fma_f32 v[140:141], v[102:103], v[140:141], v[118:119]
	v_pk_fma_f32 v[76:77], v[104:105], v[76:77], v[120:121]
	v_pk_fma_f32 v[100:101], v[106:107], v[100:101], v[140:141]
	v_pk_mul_f32 v[140:141], v[142:143], v[148:149]
	v_pk_fma_f32 v[100:101], v[66:67], v[114:115], v[100:101]
	v_pk_fma_f32 v[74:75], v[108:109], v[74:75], v[76:77]
	v_pk_mul_f32 v[84:85], v[140:141], v[100:101]
	v_add_f32_e32 v100, 1.0, v113
	v_add_f32_e32 v101, 1.0, v139
	v_rcp_f32_e32 v100, v100
	v_rcp_f32_e32 v101, v101
	v_pk_fma_f32 v[74:75], v[68:69], v[116:117], v[74:75]
	v_pk_mul_f32 v[62:63], v[62:63], v[192:193] op_sel_hi:[1,0]
	v_pk_mul_f32 v[60:61], v[60:61], v[192:193] op_sel_hi:[1,0]
	v_pk_mul_f32 v[76:77], v[82:83], v[100:101]
	v_pk_mul_f32 v[58:59], v[58:59], v[192:193] op_sel_hi:[1,0]
	v_pk_mul_f32 v[74:75], v[76:77], v[74:75]
	v_cvt_pk_bf16_f32 v242, v84, v85
	v_cvt_pk_bf16_f32 v243, v74, v75
	v_lshl_add_u64 v[74:75], s[22:23], 1, v[98:99]
	v_lshl_add_u64 v[74:75], v[74:75], 0, s[72:73]
	v_lshl_add_u64 v[74:75], v[74:75], 0, v[64:65]
	v_pk_mul_f32 v[56:57], v[56:57], v[192:193] op_sel_hi:[1,0]
	v_mov_b32_dpp v84, v70 row_ror:1 row_mask:0xf bank_mask:0xf bound_ctrl:1
	v_mov_b32_dpp v98, v70 row_ror:2 row_mask:0xf bank_mask:0xf bound_ctrl:1
	v_mov_b32_dpp v85, v71 row_ror:1 row_mask:0xf bank_mask:0xf bound_ctrl:1
	v_mov_b32_dpp v99, v71 row_ror:2 row_mask:0xf bank_mask:0xf bound_ctrl:1
	v_mov_b32_dpp v70, v72 row_ror:1 row_mask:0xf bank_mask:0xf bound_ctrl:1
	v_mov_b32_dpp v72, v72 row_ror:2 row_mask:0xf bank_mask:0xf bound_ctrl:1
	v_mov_b32_dpp v71, v73 row_ror:1 row_mask:0xf bank_mask:0xf bound_ctrl:1
	v_mov_b32_dpp v73, v73 row_ror:2 row_mask:0xf bank_mask:0xf bound_ctrl:1
	v_mov_b32_dpp v76, v66 row_ror:1 row_mask:0xf bank_mask:0xf bound_ctrl:1
	v_mov_b32_dpp v82, v66 row_ror:2 row_mask:0xf bank_mask:0xf bound_ctrl:1
	v_mov_b32_dpp v77, v67 row_ror:1 row_mask:0xf bank_mask:0xf bound_ctrl:1
	v_mov_b32_dpp v83, v67 row_ror:2 row_mask:0xf bank_mask:0xf bound_ctrl:1
	v_mov_b32_dpp v66, v68 row_ror:1 row_mask:0xf bank_mask:0xf bound_ctrl:1
	v_mov_b32_dpp v68, v68 row_ror:2 row_mask:0xf bank_mask:0xf bound_ctrl:1
	v_mov_b32_dpp v67, v69 row_ror:1 row_mask:0xf bank_mask:0xf bound_ctrl:1
	v_mov_b32_dpp v69, v69 row_ror:2 row_mask:0xf bank_mask:0xf bound_ctrl:1
	v_mov_b32_dpp v84, v60 row_shr:1 row_mask:0xf bank_mask:0xf
	v_mov_b32_dpp v98, v60 row_shr:2 row_mask:0xf bank_mask:0xf
	v_mov_b32_dpp v85, v61 row_shr:1 row_mask:0xf bank_mask:0xf
	v_mov_b32_dpp v99, v61 row_shr:2 row_mask:0xf bank_mask:0xf
	v_mov_b32_dpp v70, v62 row_shr:1 row_mask:0xf bank_mask:0xf
	v_mov_b32_dpp v72, v62 row_shr:2 row_mask:0xf bank_mask:0xf
	v_mov_b32_dpp v71, v63 row_shr:1 row_mask:0xf bank_mask:0xf
	v_mov_b32_dpp v73, v63 row_shr:2 row_mask:0xf bank_mask:0xf
	v_mov_b32_dpp v76, v56 row_shr:1 row_mask:0xf bank_mask:0xf
	v_mov_b32_dpp v82, v56 row_shr:2 row_mask:0xf bank_mask:0xf
	v_mov_b32_dpp v77, v57 row_shr:1 row_mask:0xf bank_mask:0xf
	v_mov_b32_dpp v83, v57 row_shr:2 row_mask:0xf bank_mask:0xf
	v_mov_b32_dpp v66, v58 row_shr:1 row_mask:0xf bank_mask:0xf
	v_mov_b32_dpp v68, v58 row_shr:2 row_mask:0xf bank_mask:0xf
	v_mov_b32_dpp v67, v59 row_shr:1 row_mask:0xf bank_mask:0xf
	v_mov_b32_dpp v69, v59 row_shr:2 row_mask:0xf bank_mask:0xf
	s_mov_b64 s[34:35], -1
	s_and_b64 vcc, exec, s[46:47]
	v_add_u32_e32 v148, 0xfffff520, v111
	s_cbranch_vccnz .LBB0_283
	s_add_u32 s34, s55, s26
	s_addc_u32 s35, s58, s27
	v_mov_b64_e32 v[74:75], s[34:35]
	v_mad_u64_u32 v[74:75], s[34:35], v148, s0, v[74:75]
	s_mov_b64 s[34:35], 0

; DI unsigned pk2(float lo, float hi) { f32x2_t v = {lo, hi}; bf16x2_t b = __builtin_convertvector(v, bf16x2_t); return __builtin_bit_cast(unsigned, b); }
; template <int CTRL> DI float dppf(float v) { return __int_as_float(__builtin_amdgcn_mov_dpp(__float_as_int(v), CTRL, 0xf, 0xf, true)); }
;     DI void operator()(pg8::f32x4 (&acc)[2][2][4][2], const pg8::Unit& u, int wr, int wc, int fr, int fq) const {
;     ...
;                 for (int m = 0; m < 4; ++m) {
;                     float cv[2][4];
; #pragma unroll
;                     for (int bj = 0; bj < 2; ++bj) {
;                         const pg8::f32x4 cur = acc[ai][bj][m][n];
;                         pg8::f32x4 prv;
;                         if (m > 0) prv = acc[ai][bj][m > 0 ? m - 1 : 0][n]; else prv = (pg8::f32x4){hal[bj][0], hal[bj][1], hal[bj][2], hal[bj][3]};
; #pragma unroll
;                         for (int i = 0; i < 4; ++i) {
;                             const float q1 = dppf<0x121>(prv[i]), q2 = dppf<0x122>(prv[i]);
;                             const float p1 = __int_as_float(__builtin_amdgcn_update_dpp(__float_as_int(q1), __float_as_int(cur[i]), 0x111, 0xf, 0xf, false));
;                             const float p2 = __int_as_float(__builtin_amdgcn_update_dpp(__float_as_int(q2), __float_as_int(cur[i]), 0x112, 0xf, 0xf, false));
;                             cv[bj][i] = cb[bj][i] + w0[bj][i] * p2 + w1[bj][i] * p1 + w2[bj][i] * cur[i];
;                         }
;                     }
;                     float o[4];
; #pragma unroll
;                     for (int i = 0; i < 4; ++i) o[i] = gelu_tanh(cv[0][i]) * cv[1][i];
;                     const int row = u.pm * 256 + ai * 128 + wr * 64 + m * 16 + fr;
;                     v2u w; w.x = pk2(o[0], o[1]); w.y = pk2(o[2], o[3]);
;                     *(v2u*)(a_row(wsb, row) + u.pn * 128 + wc * 32 + 8 * fq + 4 * n) = w;
;                 }
.LBB0_285:
	v_pk_fma_f32 v[98:99], v[122:123], v[98:99], v[134:135]
	v_pk_fma_f32 v[72:73], v[124:125], v[72:73], v[136:137]
	v_pk_fma_f32 v[84:85], v[126:127], v[84:85], v[98:99]
	v_pk_fma_f32 v[70:71], v[128:129], v[70:71], v[72:73]
	v_pk_fma_f32 v[84:85], v[60:61], v[130:131], v[84:85]
	v_pk_fma_f32 v[70:71], v[62:63], v[132:133], v[70:71]
	v_pk_mul_f32 v[98:99], v[84:85], v[84:85]
	v_pk_mul_f32 v[72:73], v[70:71], v[70:71]
	v_fmamk_f32 v98, v98, 0xbdd2d3e7, v175
	v_fmamk_f32 v99, v99, 0xbdd2d3e7, v175
	v_mul_f32_e32 v98, v84, v98
	v_mul_f32_e32 v99, v85, v99
	v_exp_f32_e32 v98, v98
	v_exp_f32_e32 v99, v99
	v_fmamk_f32 v72, v72, 0xbdd2d3e7, v175
	v_pk_fma_f32 v[82:83], v[102:103], v[82:83], v[118:119]
	v_add_f32_e32 v98, 1.0, v98
	v_add_f32_e32 v99, 1.0, v99
	v_rcp_f32_e32 v98, v98
	v_rcp_f32_e32 v99, v99
	v_mul_f32_e32 v72, v70, v72
	v_pk_fma_f32 v[76:77], v[106:107], v[76:77], v[82:83]
	v_pk_fma_f32 v[68:69], v[104:105], v[68:69], v[120:121]
	v_pk_mul_f32 v[82:83], v[84:85], v[98:99]
	v_exp_f32_e32 v84, v72
	v_fmamk_f32 v72, v73, 0xbdd2d3e7, v175
	v_mul_f32_e32 v72, v71, v72
	v_exp_f32_e32 v85, v72
	v_pk_fma_f32 v[76:77], v[56:57], v[114:115], v[76:77]
	v_pk_fma_f32 v[66:67], v[108:109], v[66:67], v[68:69]
	v_pk_mul_f32 v[72:73], v[82:83], v[76:77]
	v_add_f32_e32 v76, 1.0, v84
	v_add_f32_e32 v77, 1.0, v85
	v_rcp_f32_e32 v76, v76
	v_rcp_f32_e32 v77, v77
	v_pk_fma_f32 v[66:67], v[58:59], v[116:117], v[66:67]
	s_mov_b64 s[34:35], -1
	s_and_b64 vcc, exec, s[46:47]
	v_pk_mul_f32 v[68:69], v[70:71], v[76:77]
	v_mov_b32_dpp v70, v56 row_ror:2 row_mask:0xf bank_mask:0xf bound_ctrl:1
	v_pk_mul_f32 v[66:67], v[68:69], v[66:67]
	v_cvt_pk_bf16_f32 v248, v72, v73
	v_cvt_pk_bf16_f32 v249, v66, v67
	v_lshl_add_u64 v[66:67], s[22:23], 1, v[74:75]
	v_lshl_add_u64 v[66:67], v[66:67], 0, s[72:73]
	v_lshl_add_u64 v[66:67], v[66:67], 0, v[64:65]
	v_mov_b32_dpp v72, v60 row_ror:1 row_mask:0xf bank_mask:0xf bound_ctrl:1
	v_mov_b32_dpp v74, v60 row_ror:2 row_mask:0xf bank_mask:0xf bound_ctrl:1
	v_mov_b32_dpp v73, v61 row_ror:1 row_mask:0xf bank_mask:0xf bound_ctrl:1
	v_mov_b32_dpp v75, v61 row_ror:2 row_mask:0xf bank_mask:0xf bound_ctrl:1
	v_mov_b32_dpp v60, v62 row_ror:1 row_mask:0xf bank_mask:0xf bound_ctrl:1
	v_mov_b32_dpp v62, v62 row_ror:2 row_mask:0xf bank_mask:0xf bound_ctrl:1
	v_mov_b32_dpp v61, v63 row_ror:1 row_mask:0xf bank_mask:0xf bound_ctrl:1
	v_mov_b32_dpp v63, v63 row_ror:2 row_mask:0xf bank_mask:0xf bound_ctrl:1
	v_mov_b32_dpp v68, v56 row_ror:1 row_mask:0xf bank_mask:0xf bound_ctrl:1
	v_mov_b32_dpp v69, v57 row_ror:1 row_mask:0xf bank_mask:0xf bound_ctrl:1
	v_mov_b32_dpp v71, v57 row_ror:2 row_mask:0xf bank_mask:0xf bound_ctrl:1
	v_mov_b32_dpp v56, v58 row_ror:1 row_mask:0xf bank_mask:0xf bound_ctrl:1
	v_mov_b32_dpp v58, v58 row_ror:2 row_mask:0xf bank_mask:0xf bound_ctrl:1
	v_mov_b32_dpp v57, v59 row_ror:1 row_mask:0xf bank_mask:0xf bound_ctrl:1
	v_mov_b32_dpp v59, v59 row_ror:2 row_mask:0xf bank_mask:0xf bound_ctrl:1
	v_mov_b32_dpp v72, v94 row_shr:1 row_mask:0xf bank_mask:0xf
	v_mov_b32_dpp v74, v94 row_shr:2 row_mask:0xf bank_mask:0xf
	v_mov_b32_dpp v73, v95 row_shr:1 row_mask:0xf bank_mask:0xf
	v_mov_b32_dpp v75, v95 row_shr:2 row_mask:0xf bank_mask:0xf
	v_mov_b32_dpp v60, v96 row_shr:1 row_mask:0xf bank_mask:0xf
	v_mov_b32_dpp v62, v96 row_shr:2 row_mask:0xf bank_mask:0xf
	v_mov_b32_dpp v61, v97 row_shr:1 row_mask:0xf bank_mask:0xf
	v_mov_b32_dpp v63, v97 row_shr:2 row_mask:0xf bank_mask:0xf
	v_mov_b32_dpp v68, v90 row_shr:1 row_mask:0xf bank_mask:0xf
	v_mov_b32_dpp v70, v90 row_shr:2 row_mask:0xf bank_mask:0xf
	v_mov_b32_dpp v69, v91 row_shr:1 row_mask:0xf bank_mask:0xf
	v_mov_b32_dpp v71, v91 row_shr:2 row_mask:0xf bank_mask:0xf
	v_mov_b32_dpp v56, v92 row_shr:1 row_mask:0xf bank_mask:0xf
	v_mov_b32_dpp v58, v92 row_shr:2 row_mask:0xf bank_mask:0xf
	v_mov_b32_dpp v57, v93 row_shr:1 row_mask:0xf bank_mask:0xf
	v_mov_b32_dpp v59, v93 row_shr:2 row_mask:0xf bank_mask:0xf
	v_add_u32_e32 v149, 0xfffff530, v111
	s_cbranch_vccnz .LBB0_287
	s_add_u32 s34, s55, s26
	s_addc_u32 s35, s58, s27
	v_mov_b64_e32 v[66:67], s[34:35]
	v_mad_u64_u32 v[66:67], s[34:35], v149, s0, v[66:67]
	s_mov_b64 s[34:35], 0

; DI unsigned pk2(float lo, float hi) { f32x2_t v = {lo, hi}; bf16x2_t b = __builtin_convertvector(v, bf16x2_t); return __builtin_bit_cast(unsigned, b); }
; template <int CTRL> DI float dppf(float v) { return __int_as_float(__builtin_amdgcn_mov_dpp(__float_as_int(v), CTRL, 0xf, 0xf, true)); }
;     DI void operator()(pg8::f32x4 (&acc)[2][2][4][2], const pg8::Unit& u, int wr, int wc, int fr, int fq) const {
;     ...
;             for (int bj = 0; bj < 2; ++bj) {
;                 const float* p = cwp + u.pn * 256 + bj * 128 + wc * 32 + 8 * fq + 4 * n;
;                 w0[bj] = *(const v4f*)p; w1[bj] = *(const v4f*)(p + NUP); w2[bj] = *(const v4f*)(p + 2 * NUP); cb[bj] = *(const v4f*)(p + 3 * NUP);
;             }
;     ...
;                         for (int i = 0; i < 4; ++i) {
;                             const float q1 = dppf<0x121>(prv[i]), q2 = dppf<0x122>(prv[i]);
;                             const float p1 = __int_as_float(__builtin_amdgcn_update_dpp(__float_as_int(q1), __float_as_int(cur[i]), 0x111, 0xf, 0xf, false));
;                             const float p2 = __int_as_float(__builtin_amdgcn_update_dpp(__float_as_int(q2), __float_as_int(cur[i]), 0x112, 0xf, 0xf, false));
;                             cv[bj][i] = cb[bj][i] + w0[bj][i] * p2 + w1[bj][i] * p1 + w2[bj][i] * cur[i];
;                         }
;                     }
;                     float o[4];
; #pragma unroll
;                     for (int i = 0; i < 4; ++i) o[i] = gelu_tanh(cv[0][i]) * cv[1][i];
;                     const int row = u.pm * 256 + ai * 128 + wr * 64 + m * 16 + fr;
;                     v2u w; w.x = pk2(o[0], o[1]); w.y = pk2(o[2], o[3]);
;                     *(v2u*)(a_row(wsb, row) + u.pn * 128 + wc * 32 + 8 * fq + 4 * n) = w;
.LBB0_289:
	v_pk_fma_f32 v[74:75], v[122:123], v[74:75], v[134:135]
	v_pk_fma_f32 v[62:63], v[124:125], v[62:63], v[136:137]
	v_pk_fma_f32 v[72:73], v[126:127], v[72:73], v[74:75]
	v_pk_fma_f32 v[60:61], v[128:129], v[60:61], v[62:63]
	v_pk_fma_f32 v[72:73], v[94:95], v[130:131], v[72:73]
	v_pk_fma_f32 v[60:61], v[96:97], v[132:133], v[60:61]
	v_pk_mul_f32 v[74:75], v[72:73], v[72:73]
	v_pk_mul_f32 v[62:63], v[60:61], v[60:61]
	v_fmamk_f32 v74, v74, 0xbdd2d3e7, v175
	v_fmamk_f32 v75, v75, 0xbdd2d3e7, v175
	v_mul_f32_e32 v74, v72, v74
	v_mul_f32_e32 v75, v73, v75
	v_exp_f32_e32 v74, v74
	v_exp_f32_e32 v75, v75
	v_fmamk_f32 v62, v62, 0xbdd2d3e7, v175
	v_pk_fma_f32 v[70:71], v[102:103], v[70:71], v[118:119]
	v_add_f32_e32 v74, 1.0, v74
	v_add_f32_e32 v75, 1.0, v75
	v_rcp_f32_e32 v74, v74
	v_rcp_f32_e32 v75, v75
	v_mul_f32_e32 v62, v60, v62
	v_pk_fma_f32 v[68:69], v[106:107], v[68:69], v[70:71]
	v_pk_fma_f32 v[58:59], v[104:105], v[58:59], v[120:121]
	v_pk_mul_f32 v[70:71], v[72:73], v[74:75]
	v_exp_f32_e32 v72, v62
	v_fmamk_f32 v62, v63, 0xbdd2d3e7, v175
	v_mul_f32_e32 v62, v61, v62
	v_exp_f32_e32 v73, v62
	v_pk_fma_f32 v[68:69], v[90:91], v[114:115], v[68:69]
	v_pk_fma_f32 v[56:57], v[108:109], v[56:57], v[58:59]
	v_pk_mul_f32 v[62:63], v[70:71], v[68:69]
	v_add_f32_e32 v68, 1.0, v72
	v_add_f32_e32 v69, 1.0, v73
	v_rcp_f32_e32 v68, v68
	v_rcp_f32_e32 v69, v69
	v_pk_fma_f32 v[56:57], v[92:93], v[116:117], v[56:57]
	v_mov_b32_e32 v98, 0
	v_mov_b32_e32 v102, 0
	v_pk_mul_f32 v[58:59], v[60:61], v[68:69]
	v_add_co_u32_e32 v60, vcc, 0x5000, v202
	v_pk_mul_f32 v[56:57], v[58:59], v[56:57]
	s_nop 0
	v_addc_co_u32_e32 v61, vcc, 0, v203, vcc
	v_cvt_pk_bf16_f32 v251, v56, v57
	v_lshl_add_u64 v[56:57], s[22:23], 1, v[66:67]
	v_add_co_u32_e32 v66, vcc, 0xb000, v202
	v_lshl_add_u64 v[56:57], v[56:57], 0, s[72:73]
	s_nop 0
	v_addc_co_u32_e32 v67, vcc, 0, v203, vcc
	v_cvt_pk_bf16_f32 v250, v62, v63
	v_lshl_add_u64 v[56:57], v[56:57], 0, v[64:65]
	v_add_co_u32_e32 v70, vcc, 0x10000, v202
	s_nop 0
	v_addc_co_u32_e32 v71, vcc, 0, v203, vcc
	global_load_dwordx4 v[74:77], v[202:203], off offset:16
	global_load_dwordx4 v[56:59], v[202:203], off offset:528
	global_load_dwordx4 v[82:85], v[60:61], off offset:2064
	s_nop 0
	global_load_dwordx4 v[60:63], v[60:61], off offset:2576
	s_nop 0
	global_load_dwordx4 v[90:93], v[66:67], off offset:16
	s_nop 0
	global_load_dwordx4 v[66:69], v[66:67], off offset:528
	s_nop 0
	global_load_dwordx4 v[94:97], v[70:71], off offset:2064
	s_nop 0
	global_load_dwordx4 v[70:73], v[70:71], off offset:2576
	s_and_b64 vcc, exec, s[42:43]
	v_mov_b32_e32 v103, 0
	v_mov_b32_e32 v104, 0
	v_mov_b32_e32 v105, 0
	s_cbranch_vccnz .LBB0_291
	ds_read_b128 v[102:105], v193 offset:128

; DI unsigned pk2(float lo, float hi) { f32x2_t v = {lo, hi}; bf16x2_t b = __builtin_convertvector(v, bf16x2_t); return __builtin_bit_cast(unsigned, b); }
; template <int CTRL> DI float dppf(float v) { return __int_as_float(__builtin_amdgcn_mov_dpp(__float_as_int(v), CTRL, 0xf, 0xf, true)); }
;     DI void operator()(pg8::f32x4 (&acc)[2][2][4][2], const pg8::Unit& u, int wr, int wc, int fr, int fq) const {
;     ...
;                 for (int m = 0; m < 4; ++m) {
;                     float cv[2][4];
; #pragma unroll
;                     for (int bj = 0; bj < 2; ++bj) {
;                         const pg8::f32x4 cur = acc[ai][bj][m][n];
;                         pg8::f32x4 prv;
;                         if (m > 0) prv = acc[ai][bj][m > 0 ? m - 1 : 0][n]; else prv = (pg8::f32x4){hal[bj][0], hal[bj][1], hal[bj][2], hal[bj][3]};
; #pragma unroll
;                         for (int i = 0; i < 4; ++i) {
;                             const float q1 = dppf<0x121>(prv[i]), q2 = dppf<0x122>(prv[i]);
;                             const float p1 = __int_as_float(__builtin_amdgcn_update_dpp(__float_as_int(q1), __float_as_int(cur[i]), 0x111, 0xf, 0xf, false));
;                             const float p2 = __int_as_float(__builtin_amdgcn_update_dpp(__float_as_int(q2), __float_as_int(cur[i]), 0x112, 0xf, 0xf, false));
;                             cv[bj][i] = cb[bj][i] + w0[bj][i] * p2 + w1[bj][i] * p1 + w2[bj][i] * cur[i];
;                         }
;                     }
;                     float o[4];
; #pragma unroll
;                     for (int i = 0; i < 4; ++i) o[i] = gelu_tanh(cv[0][i]) * cv[1][i];
;                     const int row = u.pm * 256 + ai * 128 + wr * 64 + m * 16 + fr;
;                     v2u w; w.x = pk2(o[0], o[1]); w.y = pk2(o[2], o[3]);
;                     *(v2u*)(a_row(wsb, row) + u.pn * 128 + wc * 32 + 8 * fq + 4 * n) = w;
.LBB0_297:
	s_waitcnt vmcnt(1)
	v_pk_fma_f32 v[118:119], v[74:75], v[118:119], v[94:95]
	v_pk_fma_f32 v[106:107], v[76:77], v[106:107], v[96:97]
	v_pk_fma_f32 v[116:117], v[82:83], v[116:117], v[118:119]
	v_pk_fma_f32 v[102:103], v[84:85], v[102:103], v[106:107]
	v_pk_fma_f32 v[116:117], v[86:87], v[90:91], v[116:117]
	v_pk_fma_f32 v[102:103], v[88:89], v[92:93], v[102:103]
	v_pk_mul_f32 v[118:119], v[116:117], v[116:117]
	v_pk_mul_f32 v[106:107], v[102:103], v[102:103]
	v_fmamk_f32 v111, v118, 0xbdd2d3e7, v175
	v_mul_f32_e32 v111, v116, v111
	v_fmamk_f32 v113, v119, 0xbdd2d3e7, v175
	v_exp_f32_e32 v111, v111
	v_mul_f32_e32 v113, v117, v113
	v_exp_f32_e32 v113, v113
	v_fmamk_f32 v106, v106, 0xbdd2d3e7, v175
	v_add_f32_e32 v111, 1.0, v111
	v_rcp_f32_e32 v118, v111
	v_add_f32_e32 v111, 1.0, v113
	v_mul_f32_e32 v106, v102, v106
	v_rcp_f32_e32 v119, v111
	v_exp_f32_e32 v111, v106
	v_fmamk_f32 v106, v107, 0xbdd2d3e7, v175
	v_mul_f32_e32 v106, v103, v106
	v_exp_f32_e32 v113, v106
	s_waitcnt vmcnt(0)
	v_pk_fma_f32 v[114:115], v[56:57], v[114:115], v[70:71]
	v_pk_fma_f32 v[100:101], v[58:59], v[100:101], v[72:73]
	v_pk_fma_f32 v[108:109], v[60:61], v[108:109], v[114:115]
	v_pk_mul_f32 v[114:115], v[116:117], v[118:119]
	v_pk_fma_f32 v[108:109], v[78:79], v[66:67], v[108:109]
	v_pk_fma_f32 v[98:99], v[62:63], v[98:99], v[100:101]
	v_pk_mul_f32 v[106:107], v[114:115], v[108:109]
	v_add_f32_e32 v108, 1.0, v111
	v_add_f32_e32 v109, 1.0, v113
	v_rcp_f32_e32 v108, v108
	v_rcp_f32_e32 v109, v109
	v_pk_fma_f32 v[98:99], v[80:81], v[68:69], v[98:99]
	v_mov_b32_e32 v201, v200
	v_pk_mul_f32 v[44:45], v[44:45], v[200:201]
	v_pk_mul_f32 v[100:101], v[102:103], v[108:109]
	v_pk_mul_f32 v[40:41], v[40:41], v[200:201]
	v_pk_mul_f32 v[98:99], v[100:101], v[98:99]
	v_cvt_pk_bf16_f32 v246, v106, v107
	v_cvt_pk_bf16_f32 v247, v98, v99
	v_mov_b32_e32 v98, v200
	v_mov_b32_e32 v99, v200
	v_pk_mul_f32 v[46:47], v[46:47], v[98:99]
	v_pk_mul_f32 v[42:43], v[42:43], v[98:99]
	v_lshl_add_u64 v[98:99], s[22:23], 1, v[104:105]
	v_lshl_add_u64 v[98:99], v[98:99], 0, s[72:73]
	v_lshl_add_u64 v[98:99], v[98:99], 0, v[64:65]
	v_mov_b32_e32 v244, v220
	v_mov_b32_e32 v245, v221
	global_store_dwordx4 v[98:99], v[244:247], off
	v_mov_b32_dpp v104, v86 row_ror:1 row_mask:0xf bank_mask:0xf bound_ctrl:1
	v_mov_b32_dpp v106, v86 row_ror:2 row_mask:0xf bank_mask:0xf bound_ctrl:1
	v_mov_b32_dpp v105, v87 row_ror:1 row_mask:0xf bank_mask:0xf bound_ctrl:1
	v_mov_b32_dpp v107, v87 row_ror:2 row_mask:0xf bank_mask:0xf bound_ctrl:1
	v_mov_b32_dpp v86, v88 row_ror:1 row_mask:0xf bank_mask:0xf bound_ctrl:1
	v_mov_b32_dpp v88, v88 row_ror:2 row_mask:0xf bank_mask:0xf bound_ctrl:1
	v_mov_b32_dpp v87, v89 row_ror:1 row_mask:0xf bank_mask:0xf bound_ctrl:1
	v_mov_b32_dpp v89, v89 row_ror:2 row_mask:0xf bank_mask:0xf bound_ctrl:1
	v_mov_b32_dpp v100, v78 row_ror:1 row_mask:0xf bank_mask:0xf bound_ctrl:1
	v_mov_b32_dpp v102, v78 row_ror:2 row_mask:0xf bank_mask:0xf bound_ctrl:1
	v_mov_b32_dpp v101, v79 row_ror:1 row_mask:0xf bank_mask:0xf bound_ctrl:1
	v_mov_b32_dpp v103, v79 row_ror:2 row_mask:0xf bank_mask:0xf bound_ctrl:1
	v_mov_b32_dpp v78, v80 row_ror:1 row_mask:0xf bank_mask:0xf bound_ctrl:1
	v_mov_b32_dpp v80, v80 row_ror:2 row_mask:0xf bank_mask:0xf bound_ctrl:1
	v_mov_b32_dpp v79, v81 row_ror:1 row_mask:0xf bank_mask:0xf bound_ctrl:1
	v_mov_b32_dpp v81, v81 row_ror:2 row_mask:0xf bank_mask:0xf bound_ctrl:1
	v_mov_b32_dpp v104, v44 row_shr:1 row_mask:0xf bank_mask:0xf
	v_mov_b32_dpp v106, v44 row_shr:2 row_mask:0xf bank_mask:0xf
	v_mov_b32_dpp v105, v45 row_shr:1 row_mask:0xf bank_mask:0xf
	v_mov_b32_dpp v107, v45 row_shr:2 row_mask:0xf bank_mask:0xf
	v_mov_b32_dpp v86, v46 row_shr:1 row_mask:0xf bank_mask:0xf
	v_mov_b32_dpp v88, v46 row_shr:2 row_mask:0xf bank_mask:0xf
	v_mov_b32_dpp v87, v47 row_shr:1 row_mask:0xf bank_mask:0xf
	v_mov_b32_dpp v89, v47 row_shr:2 row_mask:0xf bank_mask:0xf
	v_mov_b32_dpp v100, v40 row_shr:1 row_mask:0xf bank_mask:0xf
	v_mov_b32_dpp v102, v40 row_shr:2 row_mask:0xf bank_mask:0xf
	v_mov_b32_dpp v101, v41 row_shr:1 row_mask:0xf bank_mask:0xf
	v_mov_b32_dpp v103, v41 row_shr:2 row_mask:0xf bank_mask:0xf
	v_mov_b32_dpp v78, v42 row_shr:1 row_mask:0xf bank_mask:0xf
	v_mov_b32_dpp v80, v42 row_shr:2 row_mask:0xf bank_mask:0xf
	v_mov_b32_dpp v79, v43 row_shr:1 row_mask:0xf bank_mask:0xf
	v_mov_b32_dpp v81, v43 row_shr:2 row_mask:0xf bank_mask:0xf
	s_and_b64 vcc, exec, s[44:45]
	s_mov_b64 s[34:35], -1
	s_cbranch_vccnz .LBB0_299
	s_add_u32 s34, s55, s24
	s_addc_u32 s35, s58, s25
	v_mov_b64_e32 v[98:99], s[34:35]
	v_mad_u64_u32 v[98:99], s[34:35], v199, s0, v[98:99]
	s_mov_b64 s[34:35], 0

; DI unsigned pk2(float lo, float hi) { f32x2_t v = {lo, hi}; bf16x2_t b = __builtin_convertvector(v, bf16x2_t); return __builtin_bit_cast(unsigned, b); }
; template <int CTRL> DI float dppf(float v) { return __int_as_float(__builtin_amdgcn_mov_dpp(__float_as_int(v), CTRL, 0xf, 0xf, true)); }
;     DI void operator()(pg8::f32x4 (&acc)[2][2][4][2], const pg8::Unit& u, int wr, int wc, int fr, int fq) const {
;     ...
;                 for (int m = 0; m < 4; ++m) {
;                     float cv[2][4];
; #pragma unroll
;                     for (int bj = 0; bj < 2; ++bj) {
;                         const pg8::f32x4 cur = acc[ai][bj][m][n];
;                         pg8::f32x4 prv;
;                         if (m > 0) prv = acc[ai][bj][m > 0 ? m - 1 : 0][n]; else prv = (pg8::f32x4){hal[bj][0], hal[bj][1], hal[bj][2], hal[bj][3]};
; #pragma unroll
;                         for (int i = 0; i < 4; ++i) {
;                             const float q1 = dppf<0x121>(prv[i]), q2 = dppf<0x122>(prv[i]);
;                             const float p1 = __int_as_float(__builtin_amdgcn_update_dpp(__float_as_int(q1), __float_as_int(cur[i]), 0x111, 0xf, 0xf, false));
;                             const float p2 = __int_as_float(__builtin_amdgcn_update_dpp(__float_as_int(q2), __float_as_int(cur[i]), 0x112, 0xf, 0xf, false));
;                             cv[bj][i] = cb[bj][i] + w0[bj][i] * p2 + w1[bj][i] * p1 + w2[bj][i] * cur[i];
;                         }
;                     }
;                     float o[4];
; #pragma unroll
;                     for (int i = 0; i < 4; ++i) o[i] = gelu_tanh(cv[0][i]) * cv[1][i];
;                     const int row = u.pm * 256 + ai * 128 + wr * 64 + m * 16 + fr;
;                     v2u w; w.x = pk2(o[0], o[1]); w.y = pk2(o[2], o[3]);
;                     *(v2u*)(a_row(wsb, row) + u.pn * 128 + wc * 32 + 8 * fq + 4 * n) = w;
.LBB0_301:
	v_pk_fma_f32 v[106:107], v[74:75], v[106:107], v[94:95]
	v_pk_fma_f32 v[88:89], v[76:77], v[88:89], v[96:97]
	v_pk_fma_f32 v[104:105], v[82:83], v[104:105], v[106:107]
	v_pk_fma_f32 v[86:87], v[84:85], v[86:87], v[88:89]
	v_pk_fma_f32 v[104:105], v[44:45], v[90:91], v[104:105]
	v_pk_fma_f32 v[86:87], v[46:47], v[92:93], v[86:87]
	v_pk_mul_f32 v[106:107], v[104:105], v[104:105]
	v_pk_mul_f32 v[88:89], v[86:87], v[86:87]
	v_fmamk_f32 v106, v106, 0xbdd2d3e7, v175
	v_fmamk_f32 v107, v107, 0xbdd2d3e7, v175
	v_mul_f32_e32 v106, v104, v106
	v_mul_f32_e32 v107, v105, v107
	v_exp_f32_e32 v106, v106
	v_exp_f32_e32 v107, v107
	v_fmamk_f32 v88, v88, 0xbdd2d3e7, v175
	v_pk_fma_f32 v[102:103], v[56:57], v[102:103], v[70:71]
	v_add_f32_e32 v106, 1.0, v106
	v_add_f32_e32 v107, 1.0, v107
	v_rcp_f32_e32 v106, v106
	v_rcp_f32_e32 v107, v107
	v_mul_f32_e32 v88, v86, v88
	v_pk_fma_f32 v[100:101], v[60:61], v[100:101], v[102:103]
	v_pk_fma_f32 v[80:81], v[58:59], v[80:81], v[72:73]
	v_pk_mul_f32 v[102:103], v[104:105], v[106:107]
	v_exp_f32_e32 v104, v88
	v_fmamk_f32 v88, v89, 0xbdd2d3e7, v175
	v_mul_f32_e32 v88, v87, v88
	v_exp_f32_e32 v105, v88
	v_pk_fma_f32 v[100:101], v[40:41], v[66:67], v[100:101]
	v_pk_fma_f32 v[78:79], v[62:63], v[78:79], v[80:81]
	v_pk_mul_f32 v[88:89], v[102:103], v[100:101]
	v_add_f32_e32 v100, 1.0, v104
	v_add_f32_e32 v101, 1.0, v105
	v_rcp_f32_e32 v100, v100
	v_rcp_f32_e32 v101, v101
	v_pk_fma_f32 v[78:79], v[42:43], v[68:69], v[78:79]
	v_mov_b32_e32 v199, v198
	v_pk_mul_f32 v[36:37], v[36:37], v[198:199]
	v_pk_mul_f32 v[80:81], v[86:87], v[100:101]
	v_pk_mul_f32 v[32:33], v[32:33], v[198:199]
	v_pk_mul_f32 v[78:79], v[80:81], v[78:79]
	v_cvt_pk_bf16_f32 v246, v88, v89
	v_cvt_pk_bf16_f32 v247, v78, v79
	v_mov_b32_e32 v78, v198
	v_mov_b32_e32 v79, v198
	v_pk_mul_f32 v[38:39], v[38:39], v[78:79]
	v_pk_mul_f32 v[34:35], v[34:35], v[78:79]
	v_lshl_add_u64 v[78:79], s[22:23], 1, v[98:99]
	v_lshl_add_u64 v[78:79], v[78:79], 0, s[72:73]
	v_lshl_add_u64 v[78:79], v[78:79], 0, v[64:65]
	v_mov_b32_e32 v244, v222
	v_mov_b32_e32 v245, v223
	global_store_dwordx4 v[78:79], v[244:247], off
	v_mov_b32_dpp v88, v44 row_ror:1 row_mask:0xf bank_mask:0xf bound_ctrl:1
	v_mov_b32_dpp v98, v44 row_ror:2 row_mask:0xf bank_mask:0xf bound_ctrl:1
	v_mov_b32_dpp v89, v45 row_ror:1 row_mask:0xf bank_mask:0xf bound_ctrl:1
	v_mov_b32_dpp v99, v45 row_ror:2 row_mask:0xf bank_mask:0xf bound_ctrl:1
	v_mov_b32_dpp v44, v46 row_ror:1 row_mask:0xf bank_mask:0xf bound_ctrl:1
	v_mov_b32_dpp v46, v46 row_ror:2 row_mask:0xf bank_mask:0xf bound_ctrl:1
	v_mov_b32_dpp v45, v47 row_ror:1 row_mask:0xf bank_mask:0xf bound_ctrl:1
	v_mov_b32_dpp v47, v47 row_ror:2 row_mask:0xf bank_mask:0xf bound_ctrl:1
	v_mov_b32_dpp v80, v40 row_ror:1 row_mask:0xf bank_mask:0xf bound_ctrl:1
	v_mov_b32_dpp v86, v40 row_ror:2 row_mask:0xf bank_mask:0xf bound_ctrl:1
	v_mov_b32_dpp v81, v41 row_ror:1 row_mask:0xf bank_mask:0xf bound_ctrl:1
	v_mov_b32_dpp v87, v41 row_ror:2 row_mask:0xf bank_mask:0xf bound_ctrl:1
	v_mov_b32_dpp v40, v42 row_ror:1 row_mask:0xf bank_mask:0xf bound_ctrl:1
	v_mov_b32_dpp v42, v42 row_ror:2 row_mask:0xf bank_mask:0xf bound_ctrl:1
	v_mov_b32_dpp v41, v43 row_ror:1 row_mask:0xf bank_mask:0xf bound_ctrl:1
	v_mov_b32_dpp v43, v43 row_ror:2 row_mask:0xf bank_mask:0xf bound_ctrl:1
	v_mov_b32_dpp v88, v36 row_shr:1 row_mask:0xf bank_mask:0xf
	v_mov_b32_dpp v98, v36 row_shr:2 row_mask:0xf bank_mask:0xf
	v_mov_b32_dpp v89, v37 row_shr:1 row_mask:0xf bank_mask:0xf
	v_mov_b32_dpp v99, v37 row_shr:2 row_mask:0xf bank_mask:0xf
	v_mov_b32_dpp v44, v38 row_shr:1 row_mask:0xf bank_mask:0xf
	v_mov_b32_dpp v46, v38 row_shr:2 row_mask:0xf bank_mask:0xf
	v_mov_b32_dpp v45, v39 row_shr:1 row_mask:0xf bank_mask:0xf
	v_mov_b32_dpp v47, v39 row_shr:2 row_mask:0xf bank_mask:0xf
	v_mov_b32_dpp v80, v32 row_shr:1 row_mask:0xf bank_mask:0xf
	v_mov_b32_dpp v86, v32 row_shr:2 row_mask:0xf bank_mask:0xf
	v_mov_b32_dpp v81, v33 row_shr:1 row_mask:0xf bank_mask:0xf
	v_mov_b32_dpp v87, v33 row_shr:2 row_mask:0xf bank_mask:0xf
	v_mov_b32_dpp v40, v34 row_shr:1 row_mask:0xf bank_mask:0xf
	v_mov_b32_dpp v42, v34 row_shr:2 row_mask:0xf bank_mask:0xf
	v_mov_b32_dpp v41, v35 row_shr:1 row_mask:0xf bank_mask:0xf
	v_mov_b32_dpp v43, v35 row_shr:2 row_mask:0xf bank_mask:0xf
	s_and_b64 vcc, exec, s[44:45]
	s_mov_b64 s[34:35], -1
	s_cbranch_vccnz .LBB0_303
	s_add_u32 s34, s55, s24
	s_addc_u32 s35, s58, s25
	v_mov_b64_e32 v[78:79], s[34:35]
	v_mad_u64_u32 v[78:79], s[34:35], v197, s0, v[78:79]
	s_mov_b64 s[34:35], 0

; DI unsigned pk2(float lo, float hi) { f32x2_t v = {lo, hi}; bf16x2_t b = __builtin_convertvector(v, bf16x2_t); return __builtin_bit_cast(unsigned, b); }
; template <int CTRL> DI float dppf(float v) { return __int_as_float(__builtin_amdgcn_mov_dpp(__float_as_int(v), CTRL, 0xf, 0xf, true)); }
;     DI void operator()(pg8::f32x4 (&acc)[2][2][4][2], const pg8::Unit& u, int wr, int wc, int fr, int fq) const {
;     ...
;                 for (int m = 0; m < 4; ++m) {
;                     float cv[2][4];
; #pragma unroll
;                     for (int bj = 0; bj < 2; ++bj) {
;                         const pg8::f32x4 cur = acc[ai][bj][m][n];
;                         pg8::f32x4 prv;
;                         if (m > 0) prv = acc[ai][bj][m > 0 ? m - 1 : 0][n]; else prv = (pg8::f32x4){hal[bj][0], hal[bj][1], hal[bj][2], hal[bj][3]};
; #pragma unroll
;                         for (int i = 0; i < 4; ++i) {
;                             const float q1 = dppf<0x121>(prv[i]), q2 = dppf<0x122>(prv[i]);
;                             const float p1 = __int_as_float(__builtin_amdgcn_update_dpp(__float_as_int(q1), __float_as_int(cur[i]), 0x111, 0xf, 0xf, false));
;                             const float p2 = __int_as_float(__builtin_amdgcn_update_dpp(__float_as_int(q2), __float_as_int(cur[i]), 0x112, 0xf, 0xf, false));
;                             cv[bj][i] = cb[bj][i] + w0[bj][i] * p2 + w1[bj][i] * p1 + w2[bj][i] * cur[i];
;                         }
;                     }
;                     float o[4];
; #pragma unroll
;                     for (int i = 0; i < 4; ++i) o[i] = gelu_tanh(cv[0][i]) * cv[1][i];
;                     const int row = u.pm * 256 + ai * 128 + wr * 64 + m * 16 + fr;
;                     v2u w; w.x = pk2(o[0], o[1]); w.y = pk2(o[2], o[3]);
;                     *(v2u*)(a_row(wsb, row) + u.pn * 128 + wc * 32 + 8 * fq + 4 * n) = w;
.LBB0_305:
	v_pk_fma_f32 v[98:99], v[74:75], v[98:99], v[94:95]
	v_pk_fma_f32 v[46:47], v[76:77], v[46:47], v[96:97]
	v_pk_fma_f32 v[88:89], v[82:83], v[88:89], v[98:99]
	v_pk_fma_f32 v[44:45], v[84:85], v[44:45], v[46:47]
	v_pk_fma_f32 v[88:89], v[36:37], v[90:91], v[88:89]
	v_pk_fma_f32 v[44:45], v[38:39], v[92:93], v[44:45]
	v_pk_mul_f32 v[98:99], v[88:89], v[88:89]
	v_pk_mul_f32 v[46:47], v[44:45], v[44:45]
	v_fmamk_f32 v98, v98, 0xbdd2d3e7, v175
	v_fmamk_f32 v99, v99, 0xbdd2d3e7, v175
	v_mul_f32_e32 v98, v88, v98
	v_mul_f32_e32 v99, v89, v99
	v_exp_f32_e32 v98, v98
	v_exp_f32_e32 v99, v99
	v_fmamk_f32 v46, v46, 0xbdd2d3e7, v175
	v_pk_fma_f32 v[86:87], v[56:57], v[86:87], v[70:71]
	v_add_f32_e32 v98, 1.0, v98
	v_add_f32_e32 v99, 1.0, v99
	v_rcp_f32_e32 v98, v98
	v_rcp_f32_e32 v99, v99
	v_mul_f32_e32 v46, v44, v46
	v_pk_fma_f32 v[80:81], v[60:61], v[80:81], v[86:87]
	v_pk_fma_f32 v[42:43], v[58:59], v[42:43], v[72:73]
	v_pk_mul_f32 v[86:87], v[88:89], v[98:99]
	v_exp_f32_e32 v88, v46
	v_fmamk_f32 v46, v47, 0xbdd2d3e7, v175
	v_mul_f32_e32 v46, v45, v46
	v_exp_f32_e32 v89, v46
	v_pk_fma_f32 v[80:81], v[32:33], v[66:67], v[80:81]
	v_pk_fma_f32 v[40:41], v[62:63], v[40:41], v[42:43]
	v_pk_mul_f32 v[46:47], v[86:87], v[80:81]
	v_add_f32_e32 v80, 1.0, v88
	v_add_f32_e32 v81, 1.0, v89
	v_rcp_f32_e32 v80, v80
	v_rcp_f32_e32 v81, v81
	v_pk_fma_f32 v[40:41], v[34:35], v[68:69], v[40:41]
	s_and_b64 vcc, exec, s[44:45]
	s_mov_b64 s[34:35], -1
	v_pk_mul_f32 v[42:43], v[44:45], v[80:81]
	v_mov_b32_dpp v44, v32 row_ror:2 row_mask:0xf bank_mask:0xf bound_ctrl:1
	v_pk_mul_f32 v[40:41], v[42:43], v[40:41]
	v_cvt_pk_bf16_f32 v246, v46, v47
	v_cvt_pk_bf16_f32 v247, v40, v41
	v_lshl_add_u64 v[40:41], s[22:23], 1, v[78:79]
	v_lshl_add_u64 v[40:41], v[40:41], 0, s[72:73]
	v_lshl_add_u64 v[40:41], v[40:41], 0, v[64:65]
	v_mov_b32_e32 v244, v224
	v_mov_b32_e32 v245, v225
	global_store_dwordx4 v[40:41], v[244:247], off
	v_mov_b32_dpp v46, v36 row_ror:1 row_mask:0xf bank_mask:0xf bound_ctrl:1
	v_mov_b32_dpp v78, v36 row_ror:2 row_mask:0xf bank_mask:0xf bound_ctrl:1
	v_mov_b32_dpp v47, v37 row_ror:1 row_mask:0xf bank_mask:0xf bound_ctrl:1
	v_mov_b32_dpp v79, v37 row_ror:2 row_mask:0xf bank_mask:0xf bound_ctrl:1
	v_mov_b32_dpp v36, v38 row_ror:1 row_mask:0xf bank_mask:0xf bound_ctrl:1
	v_mov_b32_dpp v38, v38 row_ror:2 row_mask:0xf bank_mask:0xf bound_ctrl:1
	v_mov_b32_dpp v37, v39 row_ror:1 row_mask:0xf bank_mask:0xf bound_ctrl:1
	v_mov_b32_dpp v39, v39 row_ror:2 row_mask:0xf bank_mask:0xf bound_ctrl:1
	v_mov_b32_dpp v42, v32 row_ror:1 row_mask:0xf bank_mask:0xf bound_ctrl:1
	v_mov_b32_dpp v43, v33 row_ror:1 row_mask:0xf bank_mask:0xf bound_ctrl:1
	v_mov_b32_dpp v45, v33 row_ror:2 row_mask:0xf bank_mask:0xf bound_ctrl:1
	v_mov_b32_dpp v32, v34 row_ror:1 row_mask:0xf bank_mask:0xf bound_ctrl:1
	v_mov_b32_dpp v34, v34 row_ror:2 row_mask:0xf bank_mask:0xf bound_ctrl:1
	v_mov_b32_dpp v33, v35 row_ror:1 row_mask:0xf bank_mask:0xf bound_ctrl:1
	v_mov_b32_dpp v35, v35 row_ror:2 row_mask:0xf bank_mask:0xf bound_ctrl:1
	v_mov_b32_dpp v46, v52 row_shr:1 row_mask:0xf bank_mask:0xf
	v_mov_b32_dpp v78, v52 row_shr:2 row_mask:0xf bank_mask:0xf
	v_mov_b32_dpp v47, v53 row_shr:1 row_mask:0xf bank_mask:0xf
	v_mov_b32_dpp v79, v53 row_shr:2 row_mask:0xf bank_mask:0xf
	v_mov_b32_dpp v36, v54 row_shr:1 row_mask:0xf bank_mask:0xf
	v_mov_b32_dpp v38, v54 row_shr:2 row_mask:0xf bank_mask:0xf
	v_mov_b32_dpp v37, v55 row_shr:1 row_mask:0xf bank_mask:0xf
	v_mov_b32_dpp v39, v55 row_shr:2 row_mask:0xf bank_mask:0xf
	v_mov_b32_dpp v42, v48 row_shr:1 row_mask:0xf bank_mask:0xf
	v_mov_b32_dpp v44, v48 row_shr:2 row_mask:0xf bank_mask:0xf
	v_mov_b32_dpp v43, v49 row_shr:1 row_mask:0xf bank_mask:0xf
	v_mov_b32_dpp v45, v49 row_shr:2 row_mask:0xf bank_mask:0xf
	v_mov_b32_dpp v32, v50 row_shr:1 row_mask:0xf bank_mask:0xf
	v_mov_b32_dpp v34, v50 row_shr:2 row_mask:0xf bank_mask:0xf
	v_mov_b32_dpp v33, v51 row_shr:1 row_mask:0xf bank_mask:0xf
	v_mov_b32_dpp v35, v51 row_shr:2 row_mask:0xf bank_mask:0xf
	s_cbranch_vccnz .LBB0_307
	s_add_u32 s24, s55, s24
	s_addc_u32 s25, s58, s25
	v_mov_b64_e32 v[40:41], s[24:25]
	v_mad_u64_u32 v[40:41], s[24:25], v164, s0, v[40:41]
	s_mov_b64 s[34:35], 0

; DI unsigned pk2(float lo, float hi) { f32x2_t v = {lo, hi}; bf16x2_t b = __builtin_convertvector(v, bf16x2_t); return __builtin_bit_cast(unsigned, b); }
; template <int CTRL> DI float dppf(float v) { return __int_as_float(__builtin_amdgcn_mov_dpp(__float_as_int(v), CTRL, 0xf, 0xf, true)); }
;     DI void operator()(pg8::f32x4 (&acc)[2][2][4][2], const pg8::Unit& u, int wr, int wc, int fr, int fq) const {
;     ...
;                 v4f hal[2];
;                 {
;                     const bool has = (wr == 1) || (ai == 1);
;                     const int as = (wr == 1) ? ai : 0, ws_ = (wr == 1) ? 0 : 1;
; #pragma unroll
;                     for (int bj = 0; bj < 2; ++bj) { v4f hv = H[(((as * 2 + ws_) * 4 + wc) * 4 + bj * 2 + n) * 8 + hl]; hal[bj] = has ? hv : (v4f){0.f, 0.f, 0.f, 0.f}; }
;                 }
; #pragma unroll
;                 for (int m = 0; m < 4; ++m) {
;                     float cv[2][4];
; #pragma unroll
;                     for (int bj = 0; bj < 2; ++bj) {
;                         const pg8::f32x4 cur = acc[ai][bj][m][n];
;                         pg8::f32x4 prv;
;                         if (m > 0) prv = acc[ai][bj][m > 0 ? m - 1 : 0][n]; else prv = (pg8::f32x4){hal[bj][0], hal[bj][1], hal[bj][2], hal[bj][3]};
; #pragma unroll
;                         for (int i = 0; i < 4; ++i) {
;                             const float q1 = dppf<0x121>(prv[i]), q2 = dppf<0x122>(prv[i]);
;                             const float p1 = __int_as_float(__builtin_amdgcn_update_dpp(__float_as_int(q1), __float_as_int(cur[i]), 0x111, 0xf, 0xf, false));
;                             const float p2 = __int_as_float(__builtin_amdgcn_update_dpp(__float_as_int(q2), __float_as_int(cur[i]), 0x112, 0xf, 0xf, false));
;                             cv[bj][i] = cb[bj][i] + w0[bj][i] * p2 + w1[bj][i] * p1 + w2[bj][i] * cur[i];
;                         }
;                     }
;                     float o[4];
; #pragma unroll
;                     for (int i = 0; i < 4; ++i) o[i] = gelu_tanh(cv[0][i]) * cv[1][i];
;                     const int row = u.pm * 256 + ai * 128 + wr * 64 + m * 16 + fr;
;                     v2u w; w.x = pk2(o[0], o[1]); w.y = pk2(o[2], o[3]);
;                     *(v2u*)(a_row(wsb, row) + u.pn * 128 + wc * 32 + 8 * fq + 4 * n) = w;
.LBB0_309:
	v_pk_fma_f32 v[78:79], v[74:75], v[78:79], v[94:95]
	v_pk_fma_f32 v[38:39], v[76:77], v[38:39], v[96:97]
	v_pk_fma_f32 v[46:47], v[82:83], v[46:47], v[78:79]
	v_pk_fma_f32 v[36:37], v[84:85], v[36:37], v[38:39]
	v_pk_fma_f32 v[46:47], v[52:53], v[90:91], v[46:47]
	v_pk_fma_f32 v[36:37], v[54:55], v[92:93], v[36:37]
	v_pk_mul_f32 v[52:53], v[46:47], v[46:47]
	v_pk_mul_f32 v[38:39], v[36:37], v[36:37]
	v_fmamk_f32 v52, v52, 0xbdd2d3e7, v175
	v_fmamk_f32 v53, v53, 0xbdd2d3e7, v175
	v_mul_f32_e32 v52, v46, v52
	v_mul_f32_e32 v53, v47, v53
	v_exp_f32_e32 v52, v52
	v_exp_f32_e32 v53, v53
	v_fmamk_f32 v38, v38, 0xbdd2d3e7, v175
	v_pk_fma_f32 v[44:45], v[56:57], v[44:45], v[70:71]
	v_add_f32_e32 v52, 1.0, v52
	v_add_f32_e32 v53, 1.0, v53
	v_rcp_f32_e32 v52, v52
	v_rcp_f32_e32 v53, v53
	v_mul_f32_e32 v38, v36, v38
	v_pk_fma_f32 v[42:43], v[60:61], v[42:43], v[44:45]
	v_pk_fma_f32 v[34:35], v[58:59], v[34:35], v[72:73]
	v_pk_mul_f32 v[44:45], v[46:47], v[52:53]
	v_exp_f32_e32 v46, v38
	v_fmamk_f32 v38, v39, 0xbdd2d3e7, v175
	v_mul_f32_e32 v38, v37, v38
	v_exp_f32_e32 v47, v38
	v_pk_fma_f32 v[42:43], v[48:49], v[66:67], v[42:43]
	v_pk_fma_f32 v[32:33], v[62:63], v[32:33], v[34:35]
	v_pk_mul_f32 v[38:39], v[44:45], v[42:43]
	v_add_f32_e32 v42, 1.0, v46
	v_add_f32_e32 v43, 1.0, v47
	v_rcp_f32_e32 v42, v42
	v_rcp_f32_e32 v43, v43
	v_pk_fma_f32 v[32:33], v[50:51], v[68:69], v[32:33]
	ds_read_b128 v[50:53], v218 offset:384
	v_cvt_pk_bf16_f32 v246, v38, v39
	v_pk_mul_f32 v[34:35], v[36:37], v[42:43]
	v_mov_b32_e32 v197, v196
	v_pk_mul_f32 v[32:33], v[34:35], v[32:33]
	ds_read_b128 v[34:37], v218 offset:128
	v_cvt_pk_bf16_f32 v247, v32, v33
	v_mov_b32_e32 v32, v196
	v_mov_b32_e32 v33, v196
	v_pk_mul_f32 v[22:23], v[22:23], v[32:33]
	v_pk_mul_f32 v[18:19], v[18:19], v[32:33]
	v_lshl_add_u64 v[32:33], s[22:23], 1, v[40:41]
	v_lshl_add_u64 v[32:33], v[32:33], 0, s[72:73]
	v_lshl_add_u64 v[32:33], v[32:33], 0, v[64:65]
	v_pk_mul_f32 v[20:21], v[20:21], v[196:197]
	v_pk_mul_f32 v[16:17], v[16:17], v[196:197]
	v_mov_b32_e32 v244, v232
	v_mov_b32_e32 v245, v233
	global_store_dwordx4 v[32:33], v[244:247], off
	s_waitcnt lgkmcnt(0)
	v_mov_b32_dpp v46, v34 row_ror:1 row_mask:0xf bank_mask:0xf bound_ctrl:1
	v_mov_b32_dpp v48, v34 row_ror:2 row_mask:0xf bank_mask:0xf bound_ctrl:1
	v_mov_b32_dpp v47, v35 row_ror:1 row_mask:0xf bank_mask:0xf bound_ctrl:1
	v_mov_b32_dpp v49, v35 row_ror:2 row_mask:0xf bank_mask:0xf bound_ctrl:1
	v_mov_b32_dpp v34, v36 row_ror:1 row_mask:0xf bank_mask:0xf bound_ctrl:1
	v_mov_b32_dpp v38, v36 row_ror:2 row_mask:0xf bank_mask:0xf bound_ctrl:1
	v_mov_b32_dpp v35, v37 row_ror:1 row_mask:0xf bank_mask:0xf bound_ctrl:1
	v_mov_b32_dpp v39, v37 row_ror:2 row_mask:0xf bank_mask:0xf bound_ctrl:1
	v_mov_b32_dpp v42, v50 row_ror:1 row_mask:0xf bank_mask:0xf bound_ctrl:1
	v_mov_b32_dpp v44, v50 row_ror:2 row_mask:0xf bank_mask:0xf bound_ctrl:1
	v_mov_b32_dpp v43, v51 row_ror:1 row_mask:0xf bank_mask:0xf bound_ctrl:1
	v_mov_b32_dpp v45, v51 row_ror:2 row_mask:0xf bank_mask:0xf bound_ctrl:1
	v_mov_b32_dpp v32, v52 row_ror:1 row_mask:0xf bank_mask:0xf bound_ctrl:1
	v_mov_b32_dpp v36, v52 row_ror:2 row_mask:0xf bank_mask:0xf bound_ctrl:1
	v_mov_b32_dpp v33, v53 row_ror:1 row_mask:0xf bank_mask:0xf bound_ctrl:1
	v_mov_b32_dpp v37, v53 row_ror:2 row_mask:0xf bank_mask:0xf bound_ctrl:1
	v_mov_b32_dpp v46, v20 row_shr:1 row_mask:0xf bank_mask:0xf
	v_mov_b32_dpp v48, v20 row_shr:2 row_mask:0xf bank_mask:0xf
	v_mov_b32_dpp v47, v21 row_shr:1 row_mask:0xf bank_mask:0xf
	v_mov_b32_dpp v49, v21 row_shr:2 row_mask:0xf bank_mask:0xf
	v_mov_b32_dpp v34, v22 row_shr:1 row_mask:0xf bank_mask:0xf
	v_mov_b32_dpp v38, v22 row_shr:2 row_mask:0xf bank_mask:0xf
	v_mov_b32_dpp v35, v23 row_shr:1 row_mask:0xf bank_mask:0xf
	v_mov_b32_dpp v39, v23 row_shr:2 row_mask:0xf bank_mask:0xf
	v_mov_b32_dpp v42, v16 row_shr:1 row_mask:0xf bank_mask:0xf
	v_mov_b32_dpp v44, v16 row_shr:2 row_mask:0xf bank_mask:0xf
	v_mov_b32_dpp v43, v17 row_shr:1 row_mask:0xf bank_mask:0xf
	v_mov_b32_dpp v45, v17 row_shr:2 row_mask:0xf bank_mask:0xf
	v_mov_b32_dpp v32, v18 row_shr:1 row_mask:0xf bank_mask:0xf
	v_mov_b32_dpp v36, v18 row_shr:2 row_mask:0xf bank_mask:0xf
	v_mov_b32_dpp v33, v19 row_shr:1 row_mask:0xf bank_mask:0xf
	v_mov_b32_dpp v37, v19 row_shr:2 row_mask:0xf bank_mask:0xf
	s_and_b64 vcc, exec, s[46:47]
	s_mov_b64 s[24:25], -1
	s_cbranch_vccnz .LBB0_311
	s_add_u32 s24, s55, s26
	s_addc_u32 s25, s58, s27
	v_mov_b64_e32 v[40:41], s[24:25]
	v_mad_u64_u32 v[40:41], s[24:25], v156, s0, v[40:41]
	s_mov_b64 s[24:25], 0

; DI unsigned pk2(float lo, float hi) { f32x2_t v = {lo, hi}; bf16x2_t b = __builtin_convertvector(v, bf16x2_t); return __builtin_bit_cast(unsigned, b); }
; template <int CTRL> DI float dppf(float v) { return __int_as_float(__builtin_amdgcn_mov_dpp(__float_as_int(v), CTRL, 0xf, 0xf, true)); }
;     DI void operator()(pg8::f32x4 (&acc)[2][2][4][2], const pg8::Unit& u, int wr, int wc, int fr, int fq) const {
;     ...
;                 for (int m = 0; m < 4; ++m) {
;                     float cv[2][4];
; #pragma unroll
;                     for (int bj = 0; bj < 2; ++bj) {
;                         const pg8::f32x4 cur = acc[ai][bj][m][n];
;                         pg8::f32x4 prv;
;                         if (m > 0) prv = acc[ai][bj][m > 0 ? m - 1 : 0][n]; else prv = (pg8::f32x4){hal[bj][0], hal[bj][1], hal[bj][2], hal[bj][3]};
; #pragma unroll
;                         for (int i = 0; i < 4; ++i) {
;                             const float q1 = dppf<0x121>(prv[i]), q2 = dppf<0x122>(prv[i]);
;                             const float p1 = __int_as_float(__builtin_amdgcn_update_dpp(__float_as_int(q1), __float_as_int(cur[i]), 0x111, 0xf, 0xf, false));
;                             const float p2 = __int_as_float(__builtin_amdgcn_update_dpp(__float_as_int(q2), __float_as_int(cur[i]), 0x112, 0xf, 0xf, false));
;                             cv[bj][i] = cb[bj][i] + w0[bj][i] * p2 + w1[bj][i] * p1 + w2[bj][i] * cur[i];
;                         }
;                     }
;                     float o[4];
; #pragma unroll
;                     for (int i = 0; i < 4; ++i) o[i] = gelu_tanh(cv[0][i]) * cv[1][i];
;                     const int row = u.pm * 256 + ai * 128 + wr * 64 + m * 16 + fr;
;                     v2u w; w.x = pk2(o[0], o[1]); w.y = pk2(o[2], o[3]);
;                     *(v2u*)(a_row(wsb, row) + u.pn * 128 + wc * 32 + 8 * fq + 4 * n) = w;
.LBB0_313:
	v_pk_fma_f32 v[48:49], v[74:75], v[48:49], v[94:95]
	v_pk_fma_f32 v[38:39], v[76:77], v[38:39], v[96:97]
	v_pk_fma_f32 v[46:47], v[82:83], v[46:47], v[48:49]
	v_pk_fma_f32 v[34:35], v[84:85], v[34:35], v[38:39]
	v_pk_fma_f32 v[46:47], v[20:21], v[90:91], v[46:47]
	v_pk_fma_f32 v[34:35], v[22:23], v[92:93], v[34:35]
	v_pk_mul_f32 v[48:49], v[46:47], v[46:47]
	v_pk_mul_f32 v[38:39], v[34:35], v[34:35]
	v_fmamk_f32 v48, v48, 0xbdd2d3e7, v175
	v_fmamk_f32 v49, v49, 0xbdd2d3e7, v175
	v_mul_f32_e32 v48, v46, v48
	v_mul_f32_e32 v49, v47, v49
	v_exp_f32_e32 v48, v48
	v_exp_f32_e32 v49, v49
	v_fmamk_f32 v38, v38, 0xbdd2d3e7, v175
	v_pk_fma_f32 v[44:45], v[56:57], v[44:45], v[70:71]
	v_add_f32_e32 v48, 1.0, v48
	v_add_f32_e32 v49, 1.0, v49
	v_rcp_f32_e32 v48, v48
	v_rcp_f32_e32 v49, v49
	v_mul_f32_e32 v38, v34, v38
	v_pk_fma_f32 v[42:43], v[60:61], v[42:43], v[44:45]
	v_pk_fma_f32 v[36:37], v[58:59], v[36:37], v[72:73]
	v_pk_mul_f32 v[44:45], v[46:47], v[48:49]
	v_exp_f32_e32 v46, v38
	v_fmamk_f32 v38, v39, 0xbdd2d3e7, v175
	v_mul_f32_e32 v38, v35, v38
	v_exp_f32_e32 v47, v38
	v_pk_fma_f32 v[42:43], v[16:17], v[66:67], v[42:43]
	v_pk_fma_f32 v[32:33], v[62:63], v[32:33], v[36:37]
	v_pk_mul_f32 v[38:39], v[44:45], v[42:43]
	v_add_f32_e32 v42, 1.0, v46
	v_add_f32_e32 v43, 1.0, v47
	v_rcp_f32_e32 v42, v42
	v_rcp_f32_e32 v43, v43
	v_pk_fma_f32 v[32:33], v[18:19], v[68:69], v[32:33]
	v_mov_b32_e32 v195, v194
	v_pk_mul_f32 v[12:13], v[12:13], v[194:195]
	v_pk_mul_f32 v[34:35], v[34:35], v[42:43]
	v_pk_mul_f32 v[8:9], v[8:9], v[194:195]
	v_pk_mul_f32 v[32:33], v[34:35], v[32:33]
	v_cvt_pk_bf16_f32 v246, v38, v39
	v_cvt_pk_bf16_f32 v247, v32, v33
	v_mov_b32_e32 v32, v194
	v_mov_b32_e32 v33, v194
	v_pk_mul_f32 v[14:15], v[14:15], v[32:33]
	v_pk_mul_f32 v[10:11], v[10:11], v[32:33]
	v_lshl_add_u64 v[32:33], s[22:23], 1, v[40:41]
	v_lshl_add_u64 v[32:33], v[32:33], 0, s[72:73]
	v_lshl_add_u64 v[32:33], v[32:33], 0, v[64:65]
	v_mov_b32_e32 v244, v238
	v_mov_b32_e32 v245, v239
	global_store_dwordx4 v[32:33], v[244:247], off
	v_mov_b32_dpp v38, v20 row_ror:1 row_mask:0xf bank_mask:0xf bound_ctrl:1
	v_mov_b32_dpp v40, v20 row_ror:2 row_mask:0xf bank_mask:0xf bound_ctrl:1
	v_mov_b32_dpp v39, v21 row_ror:1 row_mask:0xf bank_mask:0xf bound_ctrl:1
	v_mov_b32_dpp v41, v21 row_ror:2 row_mask:0xf bank_mask:0xf bound_ctrl:1
	v_mov_b32_dpp v20, v22 row_ror:1 row_mask:0xf bank_mask:0xf bound_ctrl:1
	v_mov_b32_dpp v22, v22 row_ror:2 row_mask:0xf bank_mask:0xf bound_ctrl:1
	v_mov_b32_dpp v21, v23 row_ror:1 row_mask:0xf bank_mask:0xf bound_ctrl:1
	v_mov_b32_dpp v23, v23 row_ror:2 row_mask:0xf bank_mask:0xf bound_ctrl:1
	v_mov_b32_dpp v34, v16 row_ror:1 row_mask:0xf bank_mask:0xf bound_ctrl:1
	v_mov_b32_dpp v36, v16 row_ror:2 row_mask:0xf bank_mask:0xf bound_ctrl:1
	v_mov_b32_dpp v35, v17 row_ror:1 row_mask:0xf bank_mask:0xf bound_ctrl:1
	v_mov_b32_dpp v37, v17 row_ror:2 row_mask:0xf bank_mask:0xf bound_ctrl:1
	v_mov_b32_dpp v16, v18 row_ror:1 row_mask:0xf bank_mask:0xf bound_ctrl:1
	v_mov_b32_dpp v18, v18 row_ror:2 row_mask:0xf bank_mask:0xf bound_ctrl:1
	v_mov_b32_dpp v17, v19 row_ror:1 row_mask:0xf bank_mask:0xf bound_ctrl:1
	v_mov_b32_dpp v19, v19 row_ror:2 row_mask:0xf bank_mask:0xf bound_ctrl:1
	v_mov_b32_dpp v38, v12 row_shr:1 row_mask:0xf bank_mask:0xf
	v_mov_b32_dpp v40, v12 row_shr:2 row_mask:0xf bank_mask:0xf
	v_mov_b32_dpp v39, v13 row_shr:1 row_mask:0xf bank_mask:0xf
	v_mov_b32_dpp v41, v13 row_shr:2 row_mask:0xf bank_mask:0xf
	v_mov_b32_dpp v20, v14 row_shr:1 row_mask:0xf bank_mask:0xf
	v_mov_b32_dpp v22, v14 row_shr:2 row_mask:0xf bank_mask:0xf
	v_mov_b32_dpp v21, v15 row_shr:1 row_mask:0xf bank_mask:0xf
	v_mov_b32_dpp v23, v15 row_shr:2 row_mask:0xf bank_mask:0xf
	v_mov_b32_dpp v34, v8 row_shr:1 row_mask:0xf bank_mask:0xf
	v_mov_b32_dpp v36, v8 row_shr:2 row_mask:0xf bank_mask:0xf
	v_mov_b32_dpp v35, v9 row_shr:1 row_mask:0xf bank_mask:0xf
	v_mov_b32_dpp v37, v9 row_shr:2 row_mask:0xf bank_mask:0xf
	v_mov_b32_dpp v16, v10 row_shr:1 row_mask:0xf bank_mask:0xf
	v_mov_b32_dpp v18, v10 row_shr:2 row_mask:0xf bank_mask:0xf
	v_mov_b32_dpp v17, v11 row_shr:1 row_mask:0xf bank_mask:0xf
	v_mov_b32_dpp v19, v11 row_shr:2 row_mask:0xf bank_mask:0xf
	s_and_b64 vcc, exec, s[46:47]
	s_mov_b64 s[24:25], -1
	s_cbranch_vccnz .LBB0_315
	s_add_u32 s24, s55, s26
	s_addc_u32 s25, s58, s27
	v_mov_b64_e32 v[32:33], s[24:25]
	v_mad_u64_u32 v[32:33], s[24:25], v150, s0, v[32:33]
	s_mov_b64 s[24:25], 0

; DI unsigned pk2(float lo, float hi) { f32x2_t v = {lo, hi}; bf16x2_t b = __builtin_convertvector(v, bf16x2_t); return __builtin_bit_cast(unsigned, b); }
; template <int CTRL> DI float dppf(float v) { return __int_as_float(__builtin_amdgcn_mov_dpp(__float_as_int(v), CTRL, 0xf, 0xf, true)); }
;     DI void operator()(pg8::f32x4 (&acc)[2][2][4][2], const pg8::Unit& u, int wr, int wc, int fr, int fq) const {
;     ...
;                 for (int m = 0; m < 4; ++m) {
;                     float cv[2][4];
; #pragma unroll
;                     for (int bj = 0; bj < 2; ++bj) {
;                         const pg8::f32x4 cur = acc[ai][bj][m][n];
;                         pg8::f32x4 prv;
;                         if (m > 0) prv = acc[ai][bj][m > 0 ? m - 1 : 0][n]; else prv = (pg8::f32x4){hal[bj][0], hal[bj][1], hal[bj][2], hal[bj][3]};
; #pragma unroll
;                         for (int i = 0; i < 4; ++i) {
;                             const float q1 = dppf<0x121>(prv[i]), q2 = dppf<0x122>(prv[i]);
;                             const float p1 = __int_as_float(__builtin_amdgcn_update_dpp(__float_as_int(q1), __float_as_int(cur[i]), 0x111, 0xf, 0xf, false));
;                             const float p2 = __int_as_float(__builtin_amdgcn_update_dpp(__float_as_int(q2), __float_as_int(cur[i]), 0x112, 0xf, 0xf, false));
;                             cv[bj][i] = cb[bj][i] + w0[bj][i] * p2 + w1[bj][i] * p1 + w2[bj][i] * cur[i];
;                         }
;                     }
;                     float o[4];
; #pragma unroll
;                     for (int i = 0; i < 4; ++i) o[i] = gelu_tanh(cv[0][i]) * cv[1][i];
;                     const int row = u.pm * 256 + ai * 128 + wr * 64 + m * 16 + fr;
;                     v2u w; w.x = pk2(o[0], o[1]); w.y = pk2(o[2], o[3]);
;                     *(v2u*)(a_row(wsb, row) + u.pn * 128 + wc * 32 + 8 * fq + 4 * n) = w;
.LBB0_317:
	v_pk_fma_f32 v[40:41], v[74:75], v[40:41], v[94:95]
	v_pk_fma_f32 v[22:23], v[76:77], v[22:23], v[96:97]
	v_pk_fma_f32 v[38:39], v[82:83], v[38:39], v[40:41]
	v_pk_fma_f32 v[20:21], v[84:85], v[20:21], v[22:23]
	v_pk_fma_f32 v[38:39], v[12:13], v[90:91], v[38:39]
	v_pk_fma_f32 v[20:21], v[14:15], v[92:93], v[20:21]
	v_pk_mul_f32 v[40:41], v[38:39], v[38:39]
	v_pk_mul_f32 v[22:23], v[20:21], v[20:21]
	v_fmamk_f32 v40, v40, 0xbdd2d3e7, v175
	v_fmamk_f32 v41, v41, 0xbdd2d3e7, v175
	v_mul_f32_e32 v40, v38, v40
	v_mul_f32_e32 v41, v39, v41
	v_exp_f32_e32 v40, v40
	v_exp_f32_e32 v41, v41
	v_fmamk_f32 v22, v22, 0xbdd2d3e7, v175
	v_pk_fma_f32 v[36:37], v[56:57], v[36:37], v[70:71]
	v_add_f32_e32 v40, 1.0, v40
	v_add_f32_e32 v41, 1.0, v41
	v_rcp_f32_e32 v40, v40
	v_rcp_f32_e32 v41, v41
	v_mul_f32_e32 v22, v20, v22
	v_pk_fma_f32 v[34:35], v[60:61], v[34:35], v[36:37]
	v_pk_fma_f32 v[18:19], v[58:59], v[18:19], v[72:73]
	v_pk_mul_f32 v[36:37], v[38:39], v[40:41]
	v_exp_f32_e32 v38, v22
	v_fmamk_f32 v22, v23, 0xbdd2d3e7, v175
	v_mul_f32_e32 v22, v21, v22
	v_exp_f32_e32 v39, v22
	v_pk_fma_f32 v[34:35], v[8:9], v[66:67], v[34:35]
	v_pk_fma_f32 v[16:17], v[62:63], v[16:17], v[18:19]
	v_pk_mul_f32 v[22:23], v[36:37], v[34:35]
	v_add_f32_e32 v34, 1.0, v38
	v_add_f32_e32 v35, 1.0, v39
	v_rcp_f32_e32 v34, v34
	v_rcp_f32_e32 v35, v35
	v_pk_fma_f32 v[16:17], v[10:11], v[68:69], v[16:17]
	v_mov_b32_e32 v193, v192
	v_pk_mul_f32 v[4:5], v[4:5], v[192:193]
	v_pk_mul_f32 v[18:19], v[20:21], v[34:35]
	v_pk_mul_f32 v[0:1], v[0:1], v[192:193]
	v_pk_mul_f32 v[16:17], v[18:19], v[16:17]
	v_cvt_pk_bf16_f32 v246, v22, v23
	v_cvt_pk_bf16_f32 v247, v16, v17
	v_mov_b32_e32 v16, v192
	v_mov_b32_e32 v17, v192
	v_pk_mul_f32 v[6:7], v[6:7], v[16:17]
	v_pk_mul_f32 v[2:3], v[2:3], v[16:17]
	v_lshl_add_u64 v[16:17], s[22:23], 1, v[32:33]
	v_lshl_add_u64 v[16:17], v[16:17], 0, s[72:73]
	v_lshl_add_u64 v[16:17], v[16:17], 0, v[64:65]
	v_mov_b32_e32 v244, v242
	v_mov_b32_e32 v245, v243
	global_store_dwordx4 v[16:17], v[244:247], off
	v_mov_b32_dpp v22, v12 row_ror:1 row_mask:0xf bank_mask:0xf bound_ctrl:1
	v_mov_b32_dpp v32, v12 row_ror:2 row_mask:0xf bank_mask:0xf bound_ctrl:1
	v_mov_b32_dpp v23, v13 row_ror:1 row_mask:0xf bank_mask:0xf bound_ctrl:1
	v_mov_b32_dpp v33, v13 row_ror:2 row_mask:0xf bank_mask:0xf bound_ctrl:1
	v_mov_b32_dpp v12, v14 row_ror:1 row_mask:0xf bank_mask:0xf bound_ctrl:1
	v_mov_b32_dpp v14, v14 row_ror:2 row_mask:0xf bank_mask:0xf bound_ctrl:1
	v_mov_b32_dpp v13, v15 row_ror:1 row_mask:0xf bank_mask:0xf bound_ctrl:1
	v_mov_b32_dpp v15, v15 row_ror:2 row_mask:0xf bank_mask:0xf bound_ctrl:1
	v_mov_b32_dpp v18, v8 row_ror:1 row_mask:0xf bank_mask:0xf bound_ctrl:1
	v_mov_b32_dpp v20, v8 row_ror:2 row_mask:0xf bank_mask:0xf bound_ctrl:1
	v_mov_b32_dpp v19, v9 row_ror:1 row_mask:0xf bank_mask:0xf bound_ctrl:1
	v_mov_b32_dpp v21, v9 row_ror:2 row_mask:0xf bank_mask:0xf bound_ctrl:1
	v_mov_b32_dpp v8, v10 row_ror:1 row_mask:0xf bank_mask:0xf bound_ctrl:1
	v_mov_b32_dpp v10, v10 row_ror:2 row_mask:0xf bank_mask:0xf bound_ctrl:1
	v_mov_b32_dpp v9, v11 row_ror:1 row_mask:0xf bank_mask:0xf bound_ctrl:1
	v_mov_b32_dpp v11, v11 row_ror:2 row_mask:0xf bank_mask:0xf bound_ctrl:1
	v_mov_b32_dpp v22, v4 row_shr:1 row_mask:0xf bank_mask:0xf
	v_mov_b32_dpp v32, v4 row_shr:2 row_mask:0xf bank_mask:0xf
	v_mov_b32_dpp v23, v5 row_shr:1 row_mask:0xf bank_mask:0xf
	v_mov_b32_dpp v33, v5 row_shr:2 row_mask:0xf bank_mask:0xf
	v_mov_b32_dpp v12, v6 row_shr:1 row_mask:0xf bank_mask:0xf
	v_mov_b32_dpp v14, v6 row_shr:2 row_mask:0xf bank_mask:0xf
	v_mov_b32_dpp v13, v7 row_shr:1 row_mask:0xf bank_mask:0xf
	v_mov_b32_dpp v15, v7 row_shr:2 row_mask:0xf bank_mask:0xf
	v_mov_b32_dpp v18, v0 row_shr:1 row_mask:0xf bank_mask:0xf
	v_mov_b32_dpp v20, v0 row_shr:2 row_mask:0xf bank_mask:0xf
	v_mov_b32_dpp v19, v1 row_shr:1 row_mask:0xf bank_mask:0xf
	v_mov_b32_dpp v21, v1 row_shr:2 row_mask:0xf bank_mask:0xf
	v_mov_b32_dpp v8, v2 row_shr:1 row_mask:0xf bank_mask:0xf
	v_mov_b32_dpp v10, v2 row_shr:2 row_mask:0xf bank_mask:0xf
	v_mov_b32_dpp v9, v3 row_shr:1 row_mask:0xf bank_mask:0xf
	v_mov_b32_dpp v11, v3 row_shr:2 row_mask:0xf bank_mask:0xf
	s_and_b64 vcc, exec, s[46:47]
	s_mov_b64 s[24:25], -1
	s_cbranch_vccnz .LBB0_319
	s_add_u32 s24, s55, s26
	s_addc_u32 s25, s58, s27
	v_mov_b64_e32 v[16:17], s[24:25]
	v_mad_u64_u32 v[16:17], s[24:25], v148, s0, v[16:17]
	s_mov_b64 s[24:25], 0

; DI unsigned pk2(float lo, float hi) { f32x2_t v = {lo, hi}; bf16x2_t b = __builtin_convertvector(v, bf16x2_t); return __builtin_bit_cast(unsigned, b); }
; template <int CTRL> DI float dppf(float v) { return __int_as_float(__builtin_amdgcn_mov_dpp(__float_as_int(v), CTRL, 0xf, 0xf, true)); }
;     DI void operator()(pg8::f32x4 (&acc)[2][2][4][2], const pg8::Unit& u, int wr, int wc, int fr, int fq) const {
;     ...
;                 for (int m = 0; m < 4; ++m) {
;                     float cv[2][4];
; #pragma unroll
;                     for (int bj = 0; bj < 2; ++bj) {
;                         const pg8::f32x4 cur = acc[ai][bj][m][n];
;                         pg8::f32x4 prv;
;                         if (m > 0) prv = acc[ai][bj][m > 0 ? m - 1 : 0][n]; else prv = (pg8::f32x4){hal[bj][0], hal[bj][1], hal[bj][2], hal[bj][3]};
; #pragma unroll
;                         for (int i = 0; i < 4; ++i) {
;                             const float q1 = dppf<0x121>(prv[i]), q2 = dppf<0x122>(prv[i]);
;                             const float p1 = __int_as_float(__builtin_amdgcn_update_dpp(__float_as_int(q1), __float_as_int(cur[i]), 0x111, 0xf, 0xf, false));
;                             const float p2 = __int_as_float(__builtin_amdgcn_update_dpp(__float_as_int(q2), __float_as_int(cur[i]), 0x112, 0xf, 0xf, false));
;                             cv[bj][i] = cb[bj][i] + w0[bj][i] * p2 + w1[bj][i] * p1 + w2[bj][i] * cur[i];
;                         }
;                     }
;                     float o[4];
; #pragma unroll
;                     for (int i = 0; i < 4; ++i) o[i] = gelu_tanh(cv[0][i]) * cv[1][i];
;                     const int row = u.pm * 256 + ai * 128 + wr * 64 + m * 16 + fr;
;                     v2u w; w.x = pk2(o[0], o[1]); w.y = pk2(o[2], o[3]);
;                     *(v2u*)(a_row(wsb, row) + u.pn * 128 + wc * 32 + 8 * fq + 4 * n) = w;
.LBB0_321:
	v_pk_fma_f32 v[32:33], v[74:75], v[32:33], v[94:95]
	v_pk_fma_f32 v[14:15], v[76:77], v[14:15], v[96:97]
	v_pk_fma_f32 v[22:23], v[82:83], v[22:23], v[32:33]
	v_pk_fma_f32 v[12:13], v[84:85], v[12:13], v[14:15]
	v_pk_fma_f32 v[22:23], v[4:5], v[90:91], v[22:23]
	v_pk_fma_f32 v[12:13], v[6:7], v[92:93], v[12:13]
	v_pk_mul_f32 v[32:33], v[22:23], v[22:23]
	v_pk_mul_f32 v[14:15], v[12:13], v[12:13]
	v_fmamk_f32 v32, v32, 0xbdd2d3e7, v175
	v_fmamk_f32 v33, v33, 0xbdd2d3e7, v175
	v_mul_f32_e32 v32, v22, v32
	v_mul_f32_e32 v33, v23, v33
	v_exp_f32_e32 v32, v32
	v_exp_f32_e32 v33, v33
	v_fmamk_f32 v14, v14, 0xbdd2d3e7, v175
	v_pk_fma_f32 v[20:21], v[56:57], v[20:21], v[70:71]
	v_add_f32_e32 v32, 1.0, v32
	v_add_f32_e32 v33, 1.0, v33
	v_rcp_f32_e32 v32, v32
	v_rcp_f32_e32 v33, v33
	v_mul_f32_e32 v14, v12, v14
	v_pk_fma_f32 v[18:19], v[60:61], v[18:19], v[20:21]
	v_pk_fma_f32 v[10:11], v[58:59], v[10:11], v[72:73]
	v_pk_mul_f32 v[20:21], v[22:23], v[32:33]
	v_exp_f32_e32 v22, v14
	v_fmamk_f32 v14, v15, 0xbdd2d3e7, v175
	v_mul_f32_e32 v14, v13, v14
	v_exp_f32_e32 v23, v14
	v_pk_fma_f32 v[18:19], v[0:1], v[66:67], v[18:19]
	v_pk_fma_f32 v[8:9], v[62:63], v[8:9], v[10:11]
	v_pk_mul_f32 v[14:15], v[20:21], v[18:19]
	v_add_f32_e32 v18, 1.0, v22
	v_add_f32_e32 v19, 1.0, v23
	v_rcp_f32_e32 v18, v18
	v_rcp_f32_e32 v19, v19
	v_pk_fma_f32 v[8:9], v[2:3], v[68:69], v[8:9]
	s_and_b64 vcc, exec, s[46:47]
	s_mov_b64 s[24:25], -1
	v_pk_mul_f32 v[10:11], v[12:13], v[18:19]
	v_mov_b32_dpp v12, v4 row_ror:2 row_mask:0xf bank_mask:0xf bound_ctrl:1
	v_pk_mul_f32 v[8:9], v[10:11], v[8:9]
	v_cvt_pk_bf16_f32 v246, v14, v15
	v_cvt_pk_bf16_f32 v247, v8, v9
	v_lshl_add_u64 v[8:9], s[22:23], 1, v[16:17]
	v_lshl_add_u64 v[8:9], v[8:9], 0, s[72:73]
	v_lshl_add_u64 v[8:9], v[8:9], 0, v[64:65]
	v_mov_b32_e32 v244, v248
	v_mov_b32_e32 v245, v249
	global_store_dwordx4 v[8:9], v[244:247], off
	v_mov_b32_dpp v10, v4 row_ror:1 row_mask:0xf bank_mask:0xf bound_ctrl:1
	v_mov_b32_dpp v11, v5 row_ror:1 row_mask:0xf bank_mask:0xf bound_ctrl:1
	v_mov_b32_dpp v13, v5 row_ror:2 row_mask:0xf bank_mask:0xf bound_ctrl:1
	v_mov_b32_dpp v4, v6 row_ror:1 row_mask:0xf bank_mask:0xf bound_ctrl:1
	v_mov_b32_dpp v6, v6 row_ror:2 row_mask:0xf bank_mask:0xf bound_ctrl:1
	v_mov_b32_dpp v5, v7 row_ror:1 row_mask:0xf bank_mask:0xf bound_ctrl:1
	v_mov_b32_dpp v7, v7 row_ror:2 row_mask:0xf bank_mask:0xf bound_ctrl:1
	v_mov_b32_dpp v14, v0 row_ror:1 row_mask:0xf bank_mask:0xf bound_ctrl:1
	v_mov_b32_dpp v16, v0 row_ror:2 row_mask:0xf bank_mask:0xf bound_ctrl:1
	v_mov_b32_dpp v15, v1 row_ror:1 row_mask:0xf bank_mask:0xf bound_ctrl:1
	v_mov_b32_dpp v17, v1 row_ror:2 row_mask:0xf bank_mask:0xf bound_ctrl:1
	v_mov_b32_dpp v0, v2 row_ror:1 row_mask:0xf bank_mask:0xf bound_ctrl:1
	v_mov_b32_dpp v2, v2 row_ror:2 row_mask:0xf bank_mask:0xf bound_ctrl:1
	v_mov_b32_dpp v1, v3 row_ror:1 row_mask:0xf bank_mask:0xf bound_ctrl:1
	v_mov_b32_dpp v3, v3 row_ror:2 row_mask:0xf bank_mask:0xf bound_ctrl:1
	v_mov_b32_dpp v10, v28 row_shr:1 row_mask:0xf bank_mask:0xf
	v_mov_b32_dpp v12, v28 row_shr:2 row_mask:0xf bank_mask:0xf
	v_mov_b32_dpp v11, v29 row_shr:1 row_mask:0xf bank_mask:0xf
	v_mov_b32_dpp v13, v29 row_shr:2 row_mask:0xf bank_mask:0xf
	v_mov_b32_dpp v4, v30 row_shr:1 row_mask:0xf bank_mask:0xf
	v_mov_b32_dpp v6, v30 row_shr:2 row_mask:0xf bank_mask:0xf
	v_mov_b32_dpp v5, v31 row_shr:1 row_mask:0xf bank_mask:0xf
	v_mov_b32_dpp v7, v31 row_shr:2 row_mask:0xf bank_mask:0xf
	v_mov_b32_dpp v14, v24 row_shr:1 row_mask:0xf bank_mask:0xf
	v_mov_b32_dpp v16, v24 row_shr:2 row_mask:0xf bank_mask:0xf
	v_mov_b32_dpp v15, v25 row_shr:1 row_mask:0xf bank_mask:0xf
	v_mov_b32_dpp v17, v25 row_shr:2 row_mask:0xf bank_mask:0xf
	v_mov_b32_dpp v0, v26 row_shr:1 row_mask:0xf bank_mask:0xf
	v_mov_b32_dpp v2, v26 row_shr:2 row_mask:0xf bank_mask:0xf
	v_mov_b32_dpp v1, v27 row_shr:1 row_mask:0xf bank_mask:0xf
	v_mov_b32_dpp v3, v27 row_shr:2 row_mask:0xf bank_mask:0xf
	s_cbranch_vccnz .LBB0_323
	s_add_u32 s24, s55, s26
	s_addc_u32 s25, s58, s27
	v_mov_b64_e32 v[8:9], s[24:25]
	v_mad_u64_u32 v[8:9], s[24:25], v149, s0, v[8:9]
	s_mov_b64 s[24:25], 0

; DI unsigned pk2(float lo, float hi) { f32x2_t v = {lo, hi}; bf16x2_t b = __builtin_convertvector(v, bf16x2_t); return __builtin_bit_cast(unsigned, b); }
; template <int CTRL> DI float dppf(float v) { return __int_as_float(__builtin_amdgcn_mov_dpp(__float_as_int(v), CTRL, 0xf, 0xf, true)); }
;     DI void operator()(pg8::f32x4 (&acc)[2][2][4][2], const pg8::Unit& u, int wr, int wc, int fr, int fq) const {
;     ...
;                 for (int m = 0; m < 4; ++m) {
;                     float cv[2][4];
; #pragma unroll
;                     for (int bj = 0; bj < 2; ++bj) {
;                         const pg8::f32x4 cur = acc[ai][bj][m][n];
;                         pg8::f32x4 prv;
;                         if (m > 0) prv = acc[ai][bj][m > 0 ? m - 1 : 0][n]; else prv = (pg8::f32x4){hal[bj][0], hal[bj][1], hal[bj][2], hal[bj][3]};
; #pragma unroll
;                         for (int i = 0; i < 4; ++i) {
;                             const float q1 = dppf<0x121>(prv[i]), q2 = dppf<0x122>(prv[i]);
;                             const float p1 = __int_as_float(__builtin_amdgcn_update_dpp(__float_as_int(q1), __float_as_int(cur[i]), 0x111, 0xf, 0xf, false));
;                             const float p2 = __int_as_float(__builtin_amdgcn_update_dpp(__float_as_int(q2), __float_as_int(cur[i]), 0x112, 0xf, 0xf, false));
;                             cv[bj][i] = cb[bj][i] + w0[bj][i] * p2 + w1[bj][i] * p1 + w2[bj][i] * cur[i];
;                         }
;                     }
;                     float o[4];
; #pragma unroll
;                     for (int i = 0; i < 4; ++i) o[i] = gelu_tanh(cv[0][i]) * cv[1][i];
;                     const int row = u.pm * 256 + ai * 128 + wr * 64 + m * 16 + fr;
;                     v2u w; w.x = pk2(o[0], o[1]); w.y = pk2(o[2], o[3]);
;                     *(v2u*)(a_row(wsb, row) + u.pn * 128 + wc * 32 + 8 * fq + 4 * n) = w;
.LBB0_325:
	v_pk_fma_f32 v[12:13], v[74:75], v[12:13], v[94:95]
	v_pk_fma_f32 v[6:7], v[76:77], v[6:7], v[96:97]
	v_pk_fma_f32 v[10:11], v[82:83], v[10:11], v[12:13]
	v_pk_fma_f32 v[4:5], v[84:85], v[4:5], v[6:7]
	v_pk_fma_f32 v[10:11], v[28:29], v[90:91], v[10:11]
	v_pk_fma_f32 v[4:5], v[30:31], v[92:93], v[4:5]
	v_pk_mul_f32 v[12:13], v[10:11], v[10:11]
	v_pk_mul_f32 v[6:7], v[4:5], v[4:5]
	v_fmamk_f32 v12, v12, 0xbdd2d3e7, v175
	v_fmamk_f32 v13, v13, 0xbdd2d3e7, v175
	v_mul_f32_e32 v12, v10, v12
	v_mul_f32_e32 v13, v11, v13
	v_exp_f32_e32 v12, v12
	v_exp_f32_e32 v13, v13
	v_fmamk_f32 v6, v6, 0xbdd2d3e7, v175
	v_mul_f32_e32 v6, v4, v6
	v_add_f32_e32 v12, 1.0, v12
	v_add_f32_e32 v13, 1.0, v13
	v_rcp_f32_e32 v12, v12
	v_rcp_f32_e32 v13, v13
	v_pk_fma_f32 v[16:17], v[56:57], v[16:17], v[70:71]
	v_pk_fma_f32 v[2:3], v[58:59], v[2:3], v[72:73]
	v_pk_fma_f32 v[14:15], v[60:61], v[14:15], v[16:17]
	v_pk_mul_f32 v[10:11], v[10:11], v[12:13]
	v_exp_f32_e32 v12, v6
	v_fmamk_f32 v6, v7, 0xbdd2d3e7, v175
	v_mul_f32_e32 v6, v5, v6
	v_exp_f32_e32 v7, v6
	v_pk_fma_f32 v[14:15], v[24:25], v[66:67], v[14:15]
	v_pk_fma_f32 v[0:1], v[62:63], v[0:1], v[2:3]
	v_pk_mul_f32 v[10:11], v[10:11], v[14:15]
	v_add_f32_e32 v7, 1.0, v7
	v_cvt_pk_bf16_f32 v246, v10, v11
	v_add_f32_e32 v10, 1.0, v12
	v_rcp_f32_e32 v10, v10
	v_rcp_f32_e32 v11, v7
	v_pk_fma_f32 v[0:1], v[26:27], v[68:69], v[0:1]
	s_andn2_b64 vcc, exec, s[40:41]
	v_pk_mul_f32 v[2:3], v[4:5], v[10:11]
	s_nop 0
	v_pk_mul_f32 v[0:1], v[2:3], v[0:1]
	s_nop 0
	v_cvt_pk_bf16_f32 v247, v0, v1
	v_lshl_add_u64 v[0:1], s[22:23], 1, v[8:9]
	v_lshl_add_u64 v[0:1], v[0:1], 0, s[72:73]
	v_lshl_add_u64 v[0:1], v[0:1], 0, v[64:65]
	s_mov_b64 s[22:23], -1
	v_mov_b32_e32 v244, v250
	v_mov_b32_e32 v245, v251
	global_store_dwordx4 v[0:1], v[244:247], off
	s_cbranch_vccnz .LBB0_238
	s_and_b64 vcc, exec, s[42:43]
	s_cbranch_vccnz .LBB0_237
	s_barrier
	s_branch .LBB0_237

; #define PG8_STAGE(bufoff, gbase, voff) do { _Pragma("unroll") for (int _i = 0; _i < 2; ++_i) \
;         __builtin_amdgcn_global_load_lds((const unsigned*)((const char*)(gbase) + (voff)[_i]), (PG8_LAS unsigned*)(lds + (bufoff) + ldsw + _i * 8192), 16, 0, 0); } while (0)
; #define PG8_LDA(dst, b, h) do { _Pragma("unroll") for (int m = 0; m < 4; ++m) _Pragma("unroll") for (int k = 0; k < 2; ++k) dst[m][k] = *(const PG8_LAS bf16x8*)(lds + PG8_SA(b, h) + aoff + m * 2048 + k * 1024); } while (0)
; #define PG8_LDB(dst, b, h) do { _Pragma("unroll") for (int n = 0; n < 2; ++n) _Pragma("unroll") for (int k = 0; k < 2; ++k) dst[n][k] = *(const PG8_LAS bf16x8*)(lds + PG8_SB(b, h) + boff + n * 2048 + k * 1024); } while (0)
; #define PG8_MMA(ai, bj, At, Bt) do { __builtin_amdgcn_s_setprio(1); _Pragma("unroll") for (int m = 0; m < 4; ++m) _Pragma("unroll") for (int n = 0; n < 2; ++n) _Pragma("unroll") for (int k = 0; k < 2; ++k) \
;         acc[ai][bj][m][n] = __builtin_amdgcn_mfma_f32_16x16x32_bf16(Bt[n][k], At[m][k], acc[ai][bj][m][n], 0, 0, 0); __builtin_amdgcn_s_setprio(0); } while (0)
; #define PG8_WAIT_V(n) asm volatile("s_waitcnt vmcnt(" #n ")" ::: "memory")
; #define PG8_WAIT_L(n) asm volatile("s_waitcnt lgkmcnt(" #n ")" ::: "memory")
; template <class Epi, class Sched, bool ALIGN_EPI = false, bool SP2 = false>
; __device__ __forceinline__ void gemm_phase(PG8_LAS unsigned char* lds, const Gemm g, const Sched& S, const Epi& E, int tid_in) {
;     ...
;             const bool last = (t == nt - 2);
;             const char* a1 = cA + (size_t)(t + 1) * kstep;
;             const char* a2 = last ? nA : cA + (size_t)(t + 2) * kstep; const char* b2 = last ? nB : cB + (size_t)(t + 2) * kstep;
;             const char* a3 = a2 + kstep; const char* b3 = b2 + kstep;
;             if (last && has_next) S.a_ready(nxt);
;             if constexpr (SP2) {
;             PG8_LDB(B0, 0, 0); PG8_LDB(B1, 0, 1); PG8_SCHED; PG8_LDA(At, 0, 0); PG8_STAGE(PG8_SA(1, 1), a1 + hstep, voffA);
;             PG8_WAIT_V(8); PG8_WAIT_L(0); PG8_BAR; PG8_MMA(0, 0, At, B0); PG8_MMA(0, 1, At, B1); PG8_BAR; PG8_SCHED;
;             PG8_LDA(At, 0, 1); PG8_STAGE(PG8_SB(0, 0), b2, voffB); PG8_STAGE(PG8_SB(0, 1), b2 + hstep, voffB); PG8_STAGE(PG8_SA(0, 0), a2, voffA);
;             PG8_WAIT_V(8); PG8_WAIT_L(0); PG8_BAR; PG8_MMA(1, 0, At, B0); PG8_MMA(1, 1, At, B1); PG8_BAR; PG8_SCHED;
.LBB0_369:
	s_add_i32 s55, s55, 2
	s_add_u32 s34, vcc_lo, s72
	s_addc_u32 s35, vcc_hi, 0
	s_add_u32 s58, s44, s72
	s_addc_u32 s59, s45, 0
	s_add_i32 s61, 0, 0x10000
	s_cmp_eq_u32 s72, s30
	s_cselect_b32 s75, s8, s35
	s_cselect_b32 s74, s21, s34
	v_add_u32_e32 v64, s61, v161
	s_cselect_b32 s35, s23, s59
	s_cselect_b32 s34, s36, s58
	s_add_i32 s10, 0, 0x14000
	ds_read_b128 v[150:153], v64
	ds_read_b128 v[154:157], v64 offset:1024
	ds_read_b128 v[178:181], v64 offset:2048
	ds_read_b128 v[182:185], v64 offset:3072
	v_add_u32_e32 v64, s10, v161
	ds_read_b128 v[186:189], v64
	ds_read_b128 v[190:193], v64 offset:1024
	ds_read_b128 v[194:197], v64 offset:2048
	ds_read_b128 v[198:201], v64 offset:3072
	v_lshl_add_u64 v[158:159], v[148:149], 0, s[72:73]
	s_add_i32 m0, s82, 0xc000
	ds_read_b128 v[202:205], v176
	ds_read_b128 v[206:209], v176 offset:1024
	ds_read_b128 v[210:213], v176 offset:2048
	ds_read_b128 v[214:217], v176 offset:3072
	ds_read_b128 v[218:221], v176 offset:4096
	ds_read_b128 v[222:225], v176 offset:5120
	ds_read_b128 v[242:245], v176 offset:6144
	ds_read_b128 v[246:249], v176 offset:7168
	global_load_lds_dwordx4 v[158:159], off
	v_lshl_add_u64 v[158:159], v[66:67], 0, s[72:73]
	s_add_i32 m0, s82, 0xe000
	s_nop 0
	global_load_lds_dwordx4 v[158:159], off
	s_waitcnt vmcnt(8)
	s_waitcnt lgkmcnt(0)
	s_barrier
	s_setprio 1
	s_waitcnt lgkmcnt(0)
	v_mfma_f32_16x16x32_bf16 v[128:131], v[150:153], v[202:205], v[128:131]
	v_mfma_f32_16x16x32_bf16 v[124:127], v[178:181], v[202:205], v[124:127]
	v_mfma_f32_16x16x32_bf16 v[112:115], v[150:153], v[210:213], v[112:115]
	v_mfma_f32_16x16x32_bf16 v[108:111], v[178:181], v[210:213], v[108:111]
	v_mfma_f32_16x16x32_bf16 v[96:99], v[150:153], v[218:221], v[96:99]
	v_mfma_f32_16x16x32_bf16 v[92:95], v[178:181], v[218:221], v[92:95]
	v_mfma_f32_16x16x32_bf16 v[80:83], v[150:153], v[242:245], v[80:83]
	v_mfma_f32_16x16x32_bf16 v[76:79], v[178:181], v[242:245], v[76:79]
	v_mfma_f32_16x16x32_bf16 v[128:131], v[154:157], v[206:209], v[128:131]
	v_mfma_f32_16x16x32_bf16 v[124:127], v[182:185], v[206:209], v[124:127]
	v_mfma_f32_16x16x32_bf16 v[112:115], v[154:157], v[214:217], v[112:115]
	v_mfma_f32_16x16x32_bf16 v[108:111], v[182:185], v[214:217], v[108:111]
	v_mfma_f32_16x16x32_bf16 v[96:99], v[154:157], v[222:225], v[96:99]
	v_mfma_f32_16x16x32_bf16 v[92:95], v[182:185], v[222:225], v[92:95]
	v_mfma_f32_16x16x32_bf16 v[80:83], v[154:157], v[246:249], v[80:83]
	v_mfma_f32_16x16x32_bf16 v[76:79], v[182:185], v[246:249], v[76:79]
	v_mfma_f32_16x16x32_bf16 v[120:123], v[186:189], v[202:205], v[120:123]
	v_mfma_f32_16x16x32_bf16 v[116:119], v[194:197], v[202:205], v[116:119]
	v_mfma_f32_16x16x32_bf16 v[104:107], v[186:189], v[210:213], v[104:107]
	v_mfma_f32_16x16x32_bf16 v[100:103], v[194:197], v[210:213], v[100:103]
	v_mfma_f32_16x16x32_bf16 v[88:91], v[186:189], v[218:221], v[88:91]
	v_mfma_f32_16x16x32_bf16 v[84:87], v[194:197], v[218:221], v[84:87]
	v_mfma_f32_16x16x32_bf16 v[72:75], v[186:189], v[242:245], v[72:75]
	v_mfma_f32_16x16x32_bf16 v[68:71], v[194:197], v[242:245], v[68:71]
	v_mfma_f32_16x16x32_bf16 v[120:123], v[190:193], v[206:209], v[120:123]
	v_mfma_f32_16x16x32_bf16 v[116:119], v[198:201], v[206:209], v[116:119]
	v_mfma_f32_16x16x32_bf16 v[104:107], v[190:193], v[214:217], v[104:107]
	v_mfma_f32_16x16x32_bf16 v[100:103], v[198:201], v[214:217], v[100:103]
	v_mfma_f32_16x16x32_bf16 v[88:91], v[190:193], v[222:225], v[88:91]
	v_mfma_f32_16x16x32_bf16 v[84:87], v[198:201], v[222:225], v[84:87]
	v_mfma_f32_16x16x32_bf16 v[72:75], v[190:193], v[246:249], v[72:75]
	v_mfma_f32_16x16x32_bf16 v[68:71], v[198:201], v[246:249], v[68:71]
	s_setprio 0
	s_barrier
	s_add_i32 s11, s61, s6
	v_lshl_add_u64 v[158:159], s[34:35], 0, v[134:135]
	s_mov_b32 m0, s11
	ds_read_b128 v[202:205], v176 offset:16384
	ds_read_b128 v[206:209], v176 offset:17408
	ds_read_b128 v[210:213], v176 offset:18432
	ds_read_b128 v[214:217], v176 offset:19456
	ds_read_b128 v[218:221], v176 offset:20480
	ds_read_b128 v[222:225], v176 offset:21504
	ds_read_b128 v[242:245], v176 offset:22528
	ds_read_b128 v[246:249], v176 offset:23552
	global_load_lds_dwordx4 v[158:159], off
	s_add_i32 m0, s11, 0x2000
	s_add_u32 s58, s34, 0x40000
	v_lshl_add_u64 v[232:233], s[34:35], 0, v[138:139]
	s_addc_u32 s59, s35, 0
	s_add_i32 s10, s10, s6
	global_load_lds_dwordx4 v[232:233], off
	v_lshl_add_u64 v[250:251], s[58:59], 0, v[134:135]
	s_mov_b32 m0, s10
	v_lshl_add_u64 v[172:173], s[74:75], 0, v[136:137]
	global_load_lds_dwordx4 v[250:251], off
	v_lshl_add_u64 v[250:251], s[58:59], 0, v[138:139]
	s_add_i32 m0, s10, 0x2000
	s_nop 0
	global_load_lds_dwordx4 v[250:251], off
	v_lshl_add_u64 v[250:251], s[74:75], 0, v[132:133]
	s_mov_b32 m0, s82
	s_nop 0
	global_load_lds_dwordx4 v[250:251], off
	s_mov_b32 m0, s69
	s_nop 0
	global_load_lds_dwordx4 v[172:173], off
	s_waitcnt vmcnt(8)
	s_waitcnt lgkmcnt(0)
	s_barrier
; #define PG8_STAGE(bufoff, gbase, voff) do { _Pragma("unroll") for (int _i = 0; _i < 2; ++_i) \
;         __builtin_amdgcn_global_load_lds((const unsigned*)((const char*)(gbase) + (voff)[_i]), (PG8_LAS unsigned*)(lds + (bufoff) + ldsw + _i * 8192), 16, 0, 0); } while (0)
; #define PG8_LDA(dst, b, h) do { _Pragma("unroll") for (int m = 0; m < 4; ++m) _Pragma("unroll") for (int k = 0; k < 2; ++k) dst[m][k] = *(const PG8_LAS bf16x8*)(lds + PG8_SA(b, h) + aoff + m * 2048 + k * 1024); } while (0)
; #define PG8_LDB(dst, b, h) do { _Pragma("unroll") for (int n = 0; n < 2; ++n) _Pragma("unroll") for (int k = 0; k < 2; ++k) dst[n][k] = *(const PG8_LAS bf16x8*)(lds + PG8_SB(b, h) + boff + n * 2048 + k * 1024); } while (0)
; #define PG8_MMA(ai, bj, At, Bt) do { __builtin_amdgcn_s_setprio(1); _Pragma("unroll") for (int m = 0; m < 4; ++m) _Pragma("unroll") for (int n = 0; n < 2; ++n) _Pragma("unroll") for (int k = 0; k < 2; ++k) \
;         acc[ai][bj][m][n] = __builtin_amdgcn_mfma_f32_16x16x32_bf16(Bt[n][k], At[m][k], acc[ai][bj][m][n], 0, 0, 0); __builtin_amdgcn_s_setprio(0); } while (0)
; #define PG8_WAIT_V(n) asm volatile("s_waitcnt vmcnt(" #n ")" ::: "memory")
; #define PG8_WAIT_L(n) asm volatile("s_waitcnt lgkmcnt(" #n ")" ::: "memory")
; #define PG8_BAR __builtin_amdgcn_s_barrier()
; #define PG8_SCHED __builtin_amdgcn_sched_barrier(0)
; template <class Epi, class Sched, bool ALIGN_EPI = false, bool SP2 = false>
; __device__ __forceinline__ void gemm_phase(PG8_LAS unsigned char* lds, const Gemm g, const Sched& S, const Epi& E, int tid_in) {
;     ...
;             PG8_WAIT_V(8); PG8_WAIT_L(0); PG8_BAR; PG8_MMA(1, 0, At, B0); PG8_MMA(1, 1, At, B1); PG8_BAR; PG8_SCHED;
;             PG8_LDB(B0, 1, 0); PG8_LDB(B1, 1, 1); PG8_SCHED; PG8_LDA(At, 1, 0); PG8_STAGE(PG8_SA(0, 1), a2 + hstep, voffA);
;             PG8_WAIT_V(8); PG8_WAIT_L(0); PG8_BAR; PG8_MMA(0, 0, At, B0); PG8_MMA(0, 1, At, B1); PG8_BAR; PG8_SCHED;
	s_setprio 1
	s_waitcnt lgkmcnt(0)
	v_mfma_f32_16x16x32_bf16 v[60:63], v[150:153], v[202:205], v[60:63]
	v_mfma_f32_16x16x32_bf16 v[56:59], v[178:181], v[202:205], v[56:59]
	v_mfma_f32_16x16x32_bf16 v[44:47], v[150:153], v[210:213], v[44:47]
	v_mfma_f32_16x16x32_bf16 v[40:43], v[178:181], v[210:213], v[40:43]
	v_mfma_f32_16x16x32_bf16 v[28:31], v[150:153], v[218:221], v[28:31]
	v_mfma_f32_16x16x32_bf16 v[24:27], v[178:181], v[218:221], v[24:27]
	v_mfma_f32_16x16x32_bf16 v[12:15], v[150:153], v[242:245], v[12:15]
	v_mfma_f32_16x16x32_bf16 v[8:11], v[178:181], v[242:245], v[8:11]
	v_mfma_f32_16x16x32_bf16 v[60:63], v[154:157], v[206:209], v[60:63]
	v_mfma_f32_16x16x32_bf16 v[56:59], v[182:185], v[206:209], v[56:59]
	v_mfma_f32_16x16x32_bf16 v[44:47], v[154:157], v[214:217], v[44:47]
	v_mfma_f32_16x16x32_bf16 v[40:43], v[182:185], v[214:217], v[40:43]
	v_mfma_f32_16x16x32_bf16 v[28:31], v[154:157], v[222:225], v[28:31]
	v_mfma_f32_16x16x32_bf16 v[24:27], v[182:185], v[222:225], v[24:27]
	v_mfma_f32_16x16x32_bf16 v[12:15], v[154:157], v[246:249], v[12:15]
	v_mfma_f32_16x16x32_bf16 v[8:11], v[182:185], v[246:249], v[8:11]
	v_mfma_f32_16x16x32_bf16 v[52:55], v[186:189], v[202:205], v[52:55]
	v_mfma_f32_16x16x32_bf16 v[48:51], v[194:197], v[202:205], v[48:51]
	v_mfma_f32_16x16x32_bf16 v[36:39], v[186:189], v[210:213], v[36:39]
	v_mfma_f32_16x16x32_bf16 v[32:35], v[194:197], v[210:213], v[32:35]
	v_mfma_f32_16x16x32_bf16 v[20:23], v[186:189], v[218:221], v[20:23]
	v_mfma_f32_16x16x32_bf16 v[16:19], v[194:197], v[218:221], v[16:19]
	v_mfma_f32_16x16x32_bf16 v[4:7], v[186:189], v[242:245], v[4:7]
	v_mfma_f32_16x16x32_bf16 v[0:3], v[194:197], v[242:245], v[0:3]
	v_mfma_f32_16x16x32_bf16 v[52:55], v[190:193], v[206:209], v[52:55]
	v_mfma_f32_16x16x32_bf16 v[48:51], v[198:201], v[206:209], v[48:51]
	v_mfma_f32_16x16x32_bf16 v[36:39], v[190:193], v[214:217], v[36:39]
	v_mfma_f32_16x16x32_bf16 v[32:35], v[198:201], v[214:217], v[32:35]
	v_mfma_f32_16x16x32_bf16 v[20:23], v[190:193], v[222:225], v[20:23]
	v_mfma_f32_16x16x32_bf16 v[16:19], v[198:201], v[222:225], v[16:19]
	v_mfma_f32_16x16x32_bf16 v[4:7], v[190:193], v[246:249], v[4:7]
	v_mfma_f32_16x16x32_bf16 v[0:3], v[198:201], v[246:249], v[0:3]
	s_setprio 0
	s_barrier
	s_add_i32 s10, 0, 0x18000
	v_add_u32_e32 v64, s10, v161
	s_add_i32 s11, 0, 0x1c000
	ds_read_b128 v[150:153], v64
	ds_read_b128 v[154:157], v64 offset:1024
	ds_read_b128 v[178:181], v64 offset:2048
	ds_read_b128 v[182:185], v64 offset:3072
	v_add_u32_e32 v64, s11, v161
	ds_read_b128 v[186:189], v64
	ds_read_b128 v[190:193], v64 offset:1024
	ds_read_b128 v[194:197], v64 offset:2048
	ds_read_b128 v[198:201], v64 offset:3072
	s_add_u32 s58, s74, 0x40000
	s_addc_u32 s59, s75, 0
	s_mov_b32 m0, s2
	v_lshl_add_u64 v[238:239], s[58:59], 0, v[132:133]
	ds_read_b128 v[202:205], v176 offset:32768
	ds_read_b128 v[206:209], v176 offset:33792
	ds_read_b128 v[210:213], v176 offset:34816
	ds_read_b128 v[214:217], v176 offset:35840
	ds_read_b128 v[218:221], v176 offset:36864
	ds_read_b128 v[222:225], v176 offset:37888
	ds_read_b128 v[242:245], v176 offset:38912
	ds_read_b128 v[246:249], v176 offset:39936
	global_load_lds_dwordx4 v[238:239], off
	v_lshl_add_u64 v[238:239], s[58:59], 0, v[136:137]
	s_mov_b32 m0, s63
	s_nop 0
	global_load_lds_dwordx4 v[238:239], off
	s_waitcnt vmcnt(8)
	s_waitcnt lgkmcnt(0)
	s_barrier
	s_setprio 1
	s_waitcnt lgkmcnt(0)
	v_mfma_f32_16x16x32_bf16 v[128:131], v[150:153], v[202:205], v[128:131]
	v_mfma_f32_16x16x32_bf16 v[124:127], v[178:181], v[202:205], v[124:127]
	v_mfma_f32_16x16x32_bf16 v[112:115], v[150:153], v[210:213], v[112:115]
	v_mfma_f32_16x16x32_bf16 v[108:111], v[178:181], v[210:213], v[108:111]
	v_mfma_f32_16x16x32_bf16 v[96:99], v[150:153], v[218:221], v[96:99]
	v_mfma_f32_16x16x32_bf16 v[92:95], v[178:181], v[218:221], v[92:95]
	v_mfma_f32_16x16x32_bf16 v[80:83], v[150:153], v[242:245], v[80:83]
	v_mfma_f32_16x16x32_bf16 v[76:79], v[178:181], v[242:245], v[76:79]
	v_mfma_f32_16x16x32_bf16 v[128:131], v[154:157], v[206:209], v[128:131]
	v_mfma_f32_16x16x32_bf16 v[124:127], v[182:185], v[206:209], v[124:127]
	v_mfma_f32_16x16x32_bf16 v[112:115], v[154:157], v[214:217], v[112:115]
	v_mfma_f32_16x16x32_bf16 v[108:111], v[182:185], v[214:217], v[108:111]
	v_mfma_f32_16x16x32_bf16 v[96:99], v[154:157], v[222:225], v[96:99]
	v_mfma_f32_16x16x32_bf16 v[92:95], v[182:185], v[222:225], v[92:95]
	v_mfma_f32_16x16x32_bf16 v[80:83], v[154:157], v[246:249], v[80:83]
	v_mfma_f32_16x16x32_bf16 v[76:79], v[182:185], v[246:249], v[76:79]
	v_mfma_f32_16x16x32_bf16 v[120:123], v[186:189], v[202:205], v[120:123]
	v_mfma_f32_16x16x32_bf16 v[116:119], v[194:197], v[202:205], v[116:119]
	v_mfma_f32_16x16x32_bf16 v[104:107], v[186:189], v[210:213], v[104:107]
	v_mfma_f32_16x16x32_bf16 v[100:103], v[194:197], v[210:213], v[100:103]
	v_mfma_f32_16x16x32_bf16 v[88:91], v[186:189], v[218:221], v[88:91]
	v_mfma_f32_16x16x32_bf16 v[84:87], v[194:197], v[218:221], v[84:87]
	v_mfma_f32_16x16x32_bf16 v[72:75], v[186:189], v[242:245], v[72:75]
	v_mfma_f32_16x16x32_bf16 v[68:71], v[194:197], v[242:245], v[68:71]
	v_mfma_f32_16x16x32_bf16 v[120:123], v[190:193], v[206:209], v[120:123]
	v_mfma_f32_16x16x32_bf16 v[116:119], v[198:201], v[206:209], v[116:119]
	v_mfma_f32_16x16x32_bf16 v[104:107], v[190:193], v[214:217], v[104:107]
	v_mfma_f32_16x16x32_bf16 v[100:103], v[198:201], v[214:217], v[100:103]
	v_mfma_f32_16x16x32_bf16 v[88:91], v[190:193], v[222:225], v[88:91]
	v_mfma_f32_16x16x32_bf16 v[84:87], v[198:201], v[222:225], v[84:87]
	v_mfma_f32_16x16x32_bf16 v[72:75], v[190:193], v[246:249], v[72:75]
	v_mfma_f32_16x16x32_bf16 v[68:71], v[198:201], v[246:249], v[68:71]
	s_setprio 0
	s_barrier
; #define PG8_STAGE(bufoff, gbase, voff) do { _Pragma("unroll") for (int _i = 0; _i < 2; ++_i) \
;         __builtin_amdgcn_global_load_lds((const unsigned*)((const char*)(gbase) + (voff)[_i]), (PG8_LAS unsigned*)(lds + (bufoff) + ldsw + _i * 8192), 16, 0, 0); } while (0)
; #define PG8_LDA(dst, b, h) do { _Pragma("unroll") for (int m = 0; m < 4; ++m) _Pragma("unroll") for (int k = 0; k < 2; ++k) dst[m][k] = *(const PG8_LAS bf16x8*)(lds + PG8_SA(b, h) + aoff + m * 2048 + k * 1024); } while (0)
; #define PG8_MMA(ai, bj, At, Bt) do { __builtin_amdgcn_s_setprio(1); _Pragma("unroll") for (int m = 0; m < 4; ++m) _Pragma("unroll") for (int n = 0; n < 2; ++n) _Pragma("unroll") for (int k = 0; k < 2; ++k) \
;         acc[ai][bj][m][n] = __builtin_amdgcn_mfma_f32_16x16x32_bf16(Bt[n][k], At[m][k], acc[ai][bj][m][n], 0, 0, 0); __builtin_amdgcn_s_setprio(0); } while (0)
; #define PG8_WAIT_V(n) asm volatile("s_waitcnt vmcnt(" #n ")" ::: "memory")
; #define PG8_WAIT_L(n) asm volatile("s_waitcnt lgkmcnt(" #n ")" ::: "memory")
; #define PG8_BAR __builtin_amdgcn_s_barrier()
; #define PG8_SCHED __builtin_amdgcn_sched_barrier(0)
; template <class Epi, class Sched, bool ALIGN_EPI = false, bool SP2 = false>
; __device__ __forceinline__ void gemm_phase(PG8_LAS unsigned char* lds, const Gemm g, const Sched& S, const Epi& E, int tid_in) {
;     ...
;             PG8_LDA(At, 1, 1); PG8_STAGE(PG8_SB(1, 0), b3, voffB); PG8_STAGE(PG8_SB(1, 1), b3 + hstep, voffB); PG8_STAGE(PG8_SA(1, 0), a3, voffA);
;             PG8_WAIT_V(8); PG8_WAIT_L(0); PG8_BAR; PG8_MMA(1, 0, At, B0); PG8_MMA(1, 1, At, B1); PG8_BAR; PG8_SCHED;
	s_add_i32 s10, s10, s6
	v_lshl_add_u64 v[158:159], v[158:159], 0, s[92:93]
	s_mov_b32 m0, s10
	ds_read_b128 v[202:205], v176 offset:49152
	ds_read_b128 v[206:209], v176 offset:50176
	ds_read_b128 v[210:213], v176 offset:51200
	ds_read_b128 v[214:217], v176 offset:52224
	ds_read_b128 v[218:221], v176 offset:53248
	ds_read_b128 v[222:225], v176 offset:54272
	ds_read_b128 v[242:245], v176 offset:55296
	ds_read_b128 v[246:249], v176 offset:56320
	global_load_lds_dwordx4 v[158:159], off
	s_add_i32 m0, s10, 0x2000
	s_add_u32 s34, s34, 0x40080
	v_lshl_add_u64 v[158:159], v[232:233], 0, s[92:93]
	s_addc_u32 s35, s35, 0
	s_add_i32 s10, s11, s6
	global_load_lds_dwordx4 v[158:159], off
	v_lshl_add_u64 v[158:159], s[34:35], 0, v[134:135]
	s_mov_b32 m0, s10
	s_nop 0
	global_load_lds_dwordx4 v[158:159], off
	v_lshl_add_u64 v[158:159], s[34:35], 0, v[138:139]
	s_add_i32 m0, s10, 0x2000
	s_nop 0
	global_load_lds_dwordx4 v[158:159], off
	v_lshl_add_u64 v[158:159], v[250:251], 0, s[92:93]
	s_mov_b32 m0, s66
	s_nop 0
	global_load_lds_dwordx4 v[158:159], off
	v_lshl_add_u64 v[158:159], v[172:173], 0, s[92:93]
	s_mov_b32 m0, s67
	s_nop 0
	global_load_lds_dwordx4 v[158:159], off
	s_waitcnt vmcnt(8)
	s_waitcnt lgkmcnt(0)
	s_barrier
	s_setprio 1
	s_waitcnt lgkmcnt(0)
	v_mfma_f32_16x16x32_bf16 v[60:63], v[150:153], v[202:205], v[60:63]
	v_mfma_f32_16x16x32_bf16 v[56:59], v[178:181], v[202:205], v[56:59]
	v_mfma_f32_16x16x32_bf16 v[44:47], v[150:153], v[210:213], v[44:47]
	v_mfma_f32_16x16x32_bf16 v[40:43], v[178:181], v[210:213], v[40:43]
	v_mfma_f32_16x16x32_bf16 v[28:31], v[150:153], v[218:221], v[28:31]
	v_mfma_f32_16x16x32_bf16 v[24:27], v[178:181], v[218:221], v[24:27]
	v_mfma_f32_16x16x32_bf16 v[12:15], v[150:153], v[242:245], v[12:15]
	v_mfma_f32_16x16x32_bf16 v[8:11], v[178:181], v[242:245], v[8:11]
	v_mfma_f32_16x16x32_bf16 v[60:63], v[154:157], v[206:209], v[60:63]
	v_mfma_f32_16x16x32_bf16 v[56:59], v[182:185], v[206:209], v[56:59]
	v_mfma_f32_16x16x32_bf16 v[44:47], v[154:157], v[214:217], v[44:47]
	v_mfma_f32_16x16x32_bf16 v[40:43], v[182:185], v[214:217], v[40:43]
	v_mfma_f32_16x16x32_bf16 v[28:31], v[154:157], v[222:225], v[28:31]
	v_mfma_f32_16x16x32_bf16 v[24:27], v[182:185], v[222:225], v[24:27]
	v_mfma_f32_16x16x32_bf16 v[12:15], v[154:157], v[246:249], v[12:15]
	v_mfma_f32_16x16x32_bf16 v[8:11], v[182:185], v[246:249], v[8:11]
	v_mfma_f32_16x16x32_bf16 v[52:55], v[186:189], v[202:205], v[52:55]
	v_mfma_f32_16x16x32_bf16 v[48:51], v[194:197], v[202:205], v[48:51]
	v_mfma_f32_16x16x32_bf16 v[36:39], v[186:189], v[210:213], v[36:39]
	v_mfma_f32_16x16x32_bf16 v[32:35], v[194:197], v[210:213], v[32:35]
	v_mfma_f32_16x16x32_bf16 v[20:23], v[186:189], v[218:221], v[20:23]
	v_mfma_f32_16x16x32_bf16 v[16:19], v[194:197], v[218:221], v[16:19]
	v_mfma_f32_16x16x32_bf16 v[4:7], v[186:189], v[242:245], v[4:7]
	v_mfma_f32_16x16x32_bf16 v[0:3], v[194:197], v[242:245], v[0:3]
	v_mfma_f32_16x16x32_bf16 v[52:55], v[190:193], v[206:209], v[52:55]
	v_mfma_f32_16x16x32_bf16 v[48:51], v[198:201], v[206:209], v[48:51]
	v_mfma_f32_16x16x32_bf16 v[36:39], v[190:193], v[214:217], v[36:39]
	v_mfma_f32_16x16x32_bf16 v[32:35], v[198:201], v[214:217], v[32:35]
	v_mfma_f32_16x16x32_bf16 v[20:23], v[190:193], v[222:225], v[20:23]
	v_mfma_f32_16x16x32_bf16 v[16:19], v[198:201], v[222:225], v[16:19]
	v_mfma_f32_16x16x32_bf16 v[4:7], v[190:193], v[246:249], v[4:7]
	v_mfma_f32_16x16x32_bf16 v[0:3], v[198:201], v[246:249], v[0:3]
	s_setprio 0
	s_barrier
	s_add_u32 vcc_lo, vcc_lo, 0x100
	s_addc_u32 vcc_hi, vcc_hi, 0
	s_add_u32 s44, s44, 0x100
	s_addc_u32 s45, s45, 0
	s_add_u32 s30, s30, 0xffffff00
	s_addc_u32 s31, s31, -1
	v_lshl_add_u64 v[148:149], v[148:149], 0, s[96:97]
	s_cmp_ge_u32 s55, s57
	v_lshl_add_u64 v[66:67], v[66:67], 0, s[96:97]
	s_cbranch_scc0 .LBB0_369
	s_branch .LBB0_364

; template <class Epi, class Sched, bool ALIGN_EPI = false, bool SP2 = false>
; __device__ __forceinline__ void gemm_phase(PG8_LAS unsigned char* lds, const Gemm g, const Sched& S, const Epi& E, int tid_in) {
;     ...
;         for (int a = 0; a < 2; ++a)
; #pragma unroll
;             for (int b = 0; b < 2; ++b)
; #pragma unroll
;                 for (int m = 0; m < 4; ++m)
; #pragma unroll
;                     for (int n = 0; n < 2; ++n) acc[a][b][m][n] = (f32x4){0.f, 0.f, 0.f, 0.f};
;         cur = nxt; cA = nA; cB = nB; ++ui;
;     DI void operator()(const pg8::f32x4 (&acc)[2][2][4][2], const pg8::Unit& u, int wr, int wc, int fr, int fq) const {
;     ...
;                 const int row = u.pm * 256 + ai * 128 + wr * 64 + m * 16 + fr; const float rs = rstdx[row];
.LBB0_753:
	s_ashr_i32 s19, s18, 31
	s_lshl_b64 s[20:21], s[18:19], 19
	s_add_u32 s20, s7, s20
	s_addc_u32 s21, s34, s21
	s_and_b64 s[22:23], s[38:39], exec
	s_cselect_b32 s19, s21, s27
	s_cselect_b32 s44, s20, s26
	s_ashr_i32 s17, s16, 31
	s_lshl_b64 s[22:23], s[16:17], 19
	v_readlane_b32 s30, v255, 3
	v_readlane_b32 s31, v255, 4
	s_add_u32 s22, s30, s22
	s_addc_u32 s23, s31, s23
	s_and_b64 s[30:31], s[38:39], exec
	s_cselect_b32 s17, s23, s29
	s_cselect_b32 s45, s22, s28
	s_add_u32 s26, s26, 0x40080
	s_addc_u32 s27, s27, 0
	s_add_u32 s46, s28, 0x100
	v_mov_b32_e32 v0, 0
	s_addc_u32 s47, s29, 0
	s_mov_b32 s48, -2
	v_mov_b32_e32 v1, v0
	v_mov_b32_e32 v2, v0
	v_mov_b32_e32 v3, v0
	v_mov_b32_e32 v4, v0
	v_mov_b32_e32 v5, v0
	v_mov_b32_e32 v6, v0
	v_mov_b32_e32 v7, v0
	v_mov_b32_e32 v16, v0
	v_mov_b32_e32 v17, v0
	v_mov_b32_e32 v18, v0
	v_mov_b32_e32 v19, v0
	v_mov_b32_e32 v20, v0
	v_mov_b32_e32 v21, v0
	v_mov_b32_e32 v22, v0
	v_mov_b32_e32 v23, v0
	v_mov_b32_e32 v32, v0
	v_mov_b32_e32 v33, v0
	v_mov_b32_e32 v34, v0
	v_mov_b32_e32 v35, v0
	v_mov_b32_e32 v36, v0
	v_mov_b32_e32 v37, v0
	v_mov_b32_e32 v38, v0
	v_mov_b32_e32 v39, v0
	v_mov_b32_e32 v48, v0
	v_mov_b32_e32 v49, v0
	v_mov_b32_e32 v50, v0
	v_mov_b32_e32 v51, v0
	v_mov_b32_e32 v52, v0
	v_mov_b32_e32 v53, v0
	v_mov_b32_e32 v54, v0
	v_mov_b32_e32 v55, v0
	v_mov_b32_e32 v8, v0
	v_mov_b32_e32 v9, v0
	v_mov_b32_e32 v10, v0
	v_mov_b32_e32 v11, v0
	v_mov_b32_e32 v12, v0
	v_mov_b32_e32 v13, v0
	v_mov_b32_e32 v14, v0
	v_mov_b32_e32 v15, v0
	v_mov_b32_e32 v24, v0
	v_mov_b32_e32 v25, v0
	v_mov_b32_e32 v26, v0
	v_mov_b32_e32 v27, v0
	v_mov_b32_e32 v28, v0
	v_mov_b32_e32 v29, v0
	v_mov_b32_e32 v30, v0
	v_mov_b32_e32 v31, v0
	v_mov_b32_e32 v40, v0
	v_mov_b32_e32 v41, v0
	v_mov_b32_e32 v42, v0
	v_mov_b32_e32 v43, v0
	v_mov_b32_e32 v44, v0
	v_mov_b32_e32 v45, v0
	v_mov_b32_e32 v46, v0
	v_mov_b32_e32 v47, v0
	v_mov_b32_e32 v56, v0
	v_mov_b32_e32 v57, v0
	v_mov_b32_e32 v58, v0
	v_mov_b32_e32 v59, v0
	v_mov_b32_e32 v60, v0
	v_mov_b32_e32 v61, v0
	v_mov_b32_e32 v62, v0
	v_mov_b32_e32 v63, v0
	s_waitcnt vmcnt(0)
	v_mov_b32_e32 v66, v0
	v_mov_b32_e32 v67, v0
	v_mov_b32_e32 v68, v0
	v_mov_b32_e32 v69, v0
	v_mov_b32_e32 v70, v0
	v_mov_b32_e32 v71, v0
	v_mov_b32_e32 v72, v0
	v_mov_b32_e32 v73, v0
	v_mov_b32_e32 v82, v0
	v_mov_b32_e32 v83, v0
	v_mov_b32_e32 v84, v0
	v_mov_b32_e32 v85, v0
	v_mov_b32_e32 v86, v0
	v_mov_b32_e32 v87, v0
	v_mov_b32_e32 v88, v0
	v_mov_b32_e32 v89, v0
	v_mov_b32_e32 v98, v0
	v_mov_b32_e32 v99, v0
	v_mov_b32_e32 v100, v0
	v_mov_b32_e32 v101, v0
	v_mov_b32_e32 v102, v0
	v_mov_b32_e32 v103, v0
	v_mov_b32_e32 v104, v0
	v_mov_b32_e32 v105, v0
	v_mov_b32_e32 v114, v0
	v_mov_b32_e32 v115, v0
	v_mov_b32_e32 v116, v0
	v_mov_b32_e32 v117, v0
	v_mov_b32_e32 v118, v0
	v_mov_b32_e32 v119, v0
	v_mov_b32_e32 v120, v0
	v_mov_b32_e32 v121, v0
	v_mov_b32_e32 v74, v0
	v_mov_b32_e32 v75, v0
	v_mov_b32_e32 v76, v0
	v_mov_b32_e32 v77, v0
	v_mov_b32_e32 v78, v0
	v_mov_b32_e32 v79, v0
	v_mov_b32_e32 v80, v0
	v_mov_b32_e32 v81, v0
	v_mov_b32_e32 v90, v0
	v_mov_b32_e32 v91, v0
	v_mov_b32_e32 v92, v0
	v_mov_b32_e32 v93, v0
	v_mov_b32_e32 v94, v0
	v_mov_b32_e32 v95, v0
	v_mov_b32_e32 v96, v0
	v_mov_b32_e32 v97, v0
	v_mov_b32_e32 v106, v0
	v_mov_b32_e32 v107, v0
	v_mov_b32_e32 v108, v0
	v_mov_b32_e32 v109, v0
	v_mov_b32_e32 v110, v0
	v_mov_b32_e32 v111, v0
	v_mov_b32_e32 v112, v0
	v_mov_b32_e32 v113, v0
	v_mov_b32_e32 v122, v0
	v_mov_b32_e32 v123, v0
	v_mov_b32_e32 v124, v0
	v_mov_b32_e32 v125, v0
	v_mov_b32_e32 v126, v0
	v_mov_b32_e32 v127, v0
	v_mov_b32_e32 v128, v0
	v_mov_b32_e32 v129, v0
	s_lshl_b32 s100, s24, 8
	v_add_u32_e32 v173, s100, v144
	v_mov_b32_e32 v250, v173
	v_ashrrev_i32_e32 v251, 31, v250
	v_lshl_add_u64 v[250:251], v[250:251], 2, s[8:9]
	global_load_dword v174, v[250:251], off
	v_add_u32_e32 v232, s100, v146
	v_ashrrev_i32_e32 v233, 31, v232
	v_lshl_add_u64 v[232:233], v[232:233], 2, s[8:9]
	global_load_dword v232, v[232:233], off
	v_add_u32_e32 v238, s100, v147
	v_ashrrev_i32_e32 v239, 31, v238
	v_lshl_add_u64 v[238:239], v[238:239], 2, s[8:9]
	global_load_dword v238, v[238:239], off
	v_add_u32_e32 v242, s100, v148
	v_ashrrev_i32_e32 v243, 31, v242
	v_lshl_add_u64 v[242:243], v[242:243], 2, s[8:9]
	global_load_dword v242, v[242:243], off
	v_add_u32_e32 v244, 0x80, v173
	v_ashrrev_i32_e32 v245, 31, v244
	v_lshl_add_u64 v[244:245], v[244:245], 2, s[8:9]
	global_load_dword v244, v[244:245], off
	v_add_u32_e32 v246, 0x90, v173
	v_ashrrev_i32_e32 v247, 31, v246
	v_lshl_add_u64 v[246:247], v[246:247], 2, s[8:9]
	global_load_dword v246, v[246:247], off
	v_add_u32_e32 v248, 0xa0, v173
	v_ashrrev_i32_e32 v249, 31, v248
	v_lshl_add_u64 v[248:249], v[248:249], 2, s[8:9]
	global_load_dword v248, v[248:249], off
	v_add_u32_e32 v250, 0xb0, v173
	v_ashrrev_i32_e32 v251, 31, v250
	v_lshl_add_u64 v[250:251], v[250:251], 2, s[8:9]
	global_load_dword v250, v[250:251], off
; #define PG8_STAGE(bufoff, gbase, voff) do { _Pragma("unroll") for (int _i = 0; _i < 2; ++_i) \
;         __builtin_amdgcn_global_load_lds((const unsigned*)((const char*)(gbase) + (voff)[_i]), (PG8_LAS unsigned*)(lds + (bufoff) + ldsw + _i * 8192), 16, 0, 0); } while (0)
; #define PG8_LDA(dst, b, h) do { _Pragma("unroll") for (int m = 0; m < 4; ++m) _Pragma("unroll") for (int k = 0; k < 2; ++k) dst[m][k] = *(const PG8_LAS bf16x8*)(lds + PG8_SA(b, h) + aoff + m * 2048 + k * 1024); } while (0)
; #define PG8_LDB(dst, b, h) do { _Pragma("unroll") for (int n = 0; n < 2; ++n) _Pragma("unroll") for (int k = 0; k < 2; ++k) dst[n][k] = *(const PG8_LAS bf16x8*)(lds + PG8_SB(b, h) + boff + n * 2048 + k * 1024); } while (0)
; #define PG8_MMA(ai, bj, At, Bt) do { __builtin_amdgcn_s_setprio(1); _Pragma("unroll") for (int m = 0; m < 4; ++m) _Pragma("unroll") for (int n = 0; n < 2; ++n) _Pragma("unroll") for (int k = 0; k < 2; ++k) \
;         acc[ai][bj][m][n] = __builtin_amdgcn_mfma_f32_16x16x32_bf16(Bt[n][k], At[m][k], acc[ai][bj][m][n], 0, 0, 0); __builtin_amdgcn_s_setprio(0); } while (0)
; #define PG8_WAIT_V(n) asm volatile("s_waitcnt vmcnt(" #n ")" ::: "memory")
; #define PG8_WAIT_L(n) asm volatile("s_waitcnt lgkmcnt(" #n ")" ::: "memory")
; template <class Epi, class Sched, bool ALIGN_EPI = false, bool SP2 = false>
; __device__ __forceinline__ void gemm_phase(PG8_LAS unsigned char* lds, const Gemm g, const Sched& S, const Epi& E, int tid_in) {
;     ...
;             const bool last = (t == nt - 2);
;             const char* a1 = cA + (size_t)(t + 1) * kstep;
;             const char* a2 = last ? nA : cA + (size_t)(t + 2) * kstep; const char* b2 = last ? nB : cB + (size_t)(t + 2) * kstep;
;             const char* a3 = a2 + kstep; const char* b3 = b2 + kstep;
;             if (last && has_next) S.a_ready(nxt);
;             if constexpr (SP2) {
;             PG8_LDB(B0, 0, 0); PG8_LDB(B1, 0, 1); PG8_SCHED; PG8_LDA(At, 0, 0); PG8_STAGE(PG8_SA(1, 1), a1 + hstep, voffA);
;             PG8_WAIT_V(8); PG8_WAIT_L(0); PG8_BAR; PG8_MMA(0, 0, At, B0); PG8_MMA(0, 1, At, B1); PG8_BAR; PG8_SCHED;
;             PG8_LDA(At, 0, 1); PG8_STAGE(PG8_SB(0, 0), b2, voffB); PG8_STAGE(PG8_SB(0, 1), b2 + hstep, voffB); PG8_STAGE(PG8_SA(0, 0), a2, voffA);
;             PG8_WAIT_V(8); PG8_WAIT_L(0); PG8_BAR; PG8_MMA(1, 0, At, B0); PG8_MMA(1, 1, At, B1); PG8_BAR; PG8_SCHED;
.LBB0_754:
	s_add_u32 s28, s26, 0xfffc0080
	s_addc_u32 s29, s27, -1
	s_add_i32 s49, 0, 0x10000
	s_cmp_eq_u32 s48, 12
	s_cselect_b32 s31, s19, s29
	s_cselect_b32 s30, s44, s28
	v_add_u32_e32 v142, s49, v145
	s_cselect_b32 s29, s17, s47
	s_cselect_b32 s28, s45, s46
	s_add_i32 s52, 0, 0x14000
	ds_read_b128 v[150:153], v142
	ds_read_b128 v[154:157], v142 offset:1024
	ds_read_b128 v[158:161], v142 offset:2048
	ds_read_b128 v[162:165], v142 offset:3072
	v_add_u32_e32 v142, s52, v145
	ds_read_b128 v[166:169], v142
	ds_read_b128 v[176:179], v142 offset:1024
	ds_read_b128 v[180:183], v142 offset:2048
	ds_read_b128 v[184:187], v142 offset:3072
	v_lshl_add_u64 v[142:143], s[26:27], 0, v[138:139]
	s_add_i32 m0, s35, 0xc000
	ds_read_b128 v[188:191], v149
	ds_read_b128 v[192:195], v149 offset:1024
	ds_read_b128 v[196:199], v149 offset:2048
	ds_read_b128 v[200:203], v149 offset:3072
	ds_read_b128 v[204:207], v149 offset:4096
	ds_read_b128 v[208:211], v149 offset:5120
	ds_read_b128 v[212:215], v149 offset:6144
	ds_read_b128 v[216:219], v149 offset:7168
	global_load_lds_dwordx4 v[142:143], off
	v_lshl_add_u64 v[142:143], s[26:27], 0, v[140:141]
	s_add_i32 m0, s35, 0xe000
	s_nop 0
	global_load_lds_dwordx4 v[142:143], off
	s_waitcnt vmcnt(8)
	s_waitcnt lgkmcnt(0)
	s_barrier
	s_setprio 1
	s_waitcnt lgkmcnt(0)
	v_mfma_f32_16x16x32_bf16 v[126:129], v[150:153], v[188:191], v[126:129]
	v_mfma_f32_16x16x32_bf16 v[122:125], v[158:161], v[188:191], v[122:125]
	v_mfma_f32_16x16x32_bf16 v[110:113], v[150:153], v[196:199], v[110:113]
	v_mfma_f32_16x16x32_bf16 v[106:109], v[158:161], v[196:199], v[106:109]
	v_mfma_f32_16x16x32_bf16 v[94:97], v[150:153], v[204:207], v[94:97]
	v_mfma_f32_16x16x32_bf16 v[90:93], v[158:161], v[204:207], v[90:93]
	v_mfma_f32_16x16x32_bf16 v[78:81], v[150:153], v[212:215], v[78:81]
	v_mfma_f32_16x16x32_bf16 v[74:77], v[158:161], v[212:215], v[74:77]
	v_mfma_f32_16x16x32_bf16 v[126:129], v[154:157], v[192:195], v[126:129]
	v_mfma_f32_16x16x32_bf16 v[122:125], v[162:165], v[192:195], v[122:125]
	v_mfma_f32_16x16x32_bf16 v[110:113], v[154:157], v[200:203], v[110:113]
	v_mfma_f32_16x16x32_bf16 v[106:109], v[162:165], v[200:203], v[106:109]
	v_mfma_f32_16x16x32_bf16 v[94:97], v[154:157], v[208:211], v[94:97]
	v_mfma_f32_16x16x32_bf16 v[90:93], v[162:165], v[208:211], v[90:93]
	v_mfma_f32_16x16x32_bf16 v[78:81], v[154:157], v[216:219], v[78:81]
	v_mfma_f32_16x16x32_bf16 v[74:77], v[162:165], v[216:219], v[74:77]
	v_mfma_f32_16x16x32_bf16 v[118:121], v[166:169], v[188:191], v[118:121]
	v_mfma_f32_16x16x32_bf16 v[114:117], v[180:183], v[188:191], v[114:117]
	v_mfma_f32_16x16x32_bf16 v[102:105], v[166:169], v[196:199], v[102:105]
	v_mfma_f32_16x16x32_bf16 v[98:101], v[180:183], v[196:199], v[98:101]
	v_mfma_f32_16x16x32_bf16 v[86:89], v[166:169], v[204:207], v[86:89]
	v_mfma_f32_16x16x32_bf16 v[82:85], v[180:183], v[204:207], v[82:85]
	v_mfma_f32_16x16x32_bf16 v[70:73], v[166:169], v[212:215], v[70:73]
	v_mfma_f32_16x16x32_bf16 v[66:69], v[180:183], v[212:215], v[66:69]
	v_mfma_f32_16x16x32_bf16 v[118:121], v[176:179], v[192:195], v[118:121]
	v_mfma_f32_16x16x32_bf16 v[114:117], v[184:187], v[192:195], v[114:117]
	v_mfma_f32_16x16x32_bf16 v[102:105], v[176:179], v[200:203], v[102:105]
	v_mfma_f32_16x16x32_bf16 v[98:101], v[184:187], v[200:203], v[98:101]
	v_mfma_f32_16x16x32_bf16 v[86:89], v[176:179], v[208:211], v[86:89]
	v_mfma_f32_16x16x32_bf16 v[82:85], v[184:187], v[208:211], v[82:85]
	v_mfma_f32_16x16x32_bf16 v[70:73], v[176:179], v[216:219], v[70:73]
	v_mfma_f32_16x16x32_bf16 v[66:69], v[184:187], v[216:219], v[66:69]
	s_setprio 0
	s_barrier
	s_add_i32 s49, s49, s6
	v_lshl_add_u64 v[142:143], s[28:29], 0, v[132:133]
	s_mov_b32 m0, s49
	ds_read_b128 v[188:191], v149 offset:16384
	ds_read_b128 v[192:195], v149 offset:17408
	ds_read_b128 v[196:199], v149 offset:18432
	ds_read_b128 v[200:203], v149 offset:19456
	ds_read_b128 v[204:207], v149 offset:20480
	ds_read_b128 v[208:211], v149 offset:21504
	ds_read_b128 v[212:215], v149 offset:22528
	ds_read_b128 v[216:219], v149 offset:23552
	global_load_lds_dwordx4 v[142:143], off
	s_add_i32 m0, s49, 0x2000
	s_add_u32 s50, s28, 0x40000
	v_lshl_add_u64 v[170:171], s[28:29], 0, v[136:137]
	s_addc_u32 s51, s29, 0
	s_add_i32 s49, s52, s6
	global_load_lds_dwordx4 v[170:171], off
	v_lshl_add_u64 v[220:221], s[50:51], 0, v[132:133]
	s_mov_b32 m0, s49
	v_lshl_add_u64 v[222:223], s[30:31], 0, v[134:135]
	global_load_lds_dwordx4 v[220:221], off
	v_lshl_add_u64 v[220:221], s[50:51], 0, v[136:137]
	s_add_i32 m0, s49, 0x2000
	s_nop 0
	global_load_lds_dwordx4 v[220:221], off
	v_lshl_add_u64 v[220:221], s[30:31], 0, v[130:131]
	s_mov_b32 m0, s35
	s_nop 0
	global_load_lds_dwordx4 v[220:221], off
	s_mov_b32 m0, s36
	s_nop 0
	global_load_lds_dwordx4 v[222:223], off
	s_waitcnt vmcnt(8)
	s_waitcnt lgkmcnt(0)
	s_barrier
; #define PG8_STAGE(bufoff, gbase, voff) do { _Pragma("unroll") for (int _i = 0; _i < 2; ++_i) \
;         __builtin_amdgcn_global_load_lds((const unsigned*)((const char*)(gbase) + (voff)[_i]), (PG8_LAS unsigned*)(lds + (bufoff) + ldsw + _i * 8192), 16, 0, 0); } while (0)
; #define PG8_LDA(dst, b, h) do { _Pragma("unroll") for (int m = 0; m < 4; ++m) _Pragma("unroll") for (int k = 0; k < 2; ++k) dst[m][k] = *(const PG8_LAS bf16x8*)(lds + PG8_SA(b, h) + aoff + m * 2048 + k * 1024); } while (0)
; #define PG8_LDB(dst, b, h) do { _Pragma("unroll") for (int n = 0; n < 2; ++n) _Pragma("unroll") for (int k = 0; k < 2; ++k) dst[n][k] = *(const PG8_LAS bf16x8*)(lds + PG8_SB(b, h) + boff + n * 2048 + k * 1024); } while (0)
; #define PG8_MMA(ai, bj, At, Bt) do { __builtin_amdgcn_s_setprio(1); _Pragma("unroll") for (int m = 0; m < 4; ++m) _Pragma("unroll") for (int n = 0; n < 2; ++n) _Pragma("unroll") for (int k = 0; k < 2; ++k) \
;         acc[ai][bj][m][n] = __builtin_amdgcn_mfma_f32_16x16x32_bf16(Bt[n][k], At[m][k], acc[ai][bj][m][n], 0, 0, 0); __builtin_amdgcn_s_setprio(0); } while (0)
; #define PG8_WAIT_V(n) asm volatile("s_waitcnt vmcnt(" #n ")" ::: "memory")
; #define PG8_WAIT_L(n) asm volatile("s_waitcnt lgkmcnt(" #n ")" ::: "memory")
; #define PG8_BAR __builtin_amdgcn_s_barrier()
; #define PG8_SCHED __builtin_amdgcn_sched_barrier(0)
; template <class Epi, class Sched, bool ALIGN_EPI = false, bool SP2 = false>
; __device__ __forceinline__ void gemm_phase(PG8_LAS unsigned char* lds, const Gemm g, const Sched& S, const Epi& E, int tid_in) {
;     ...
;             PG8_WAIT_V(8); PG8_WAIT_L(0); PG8_BAR; PG8_MMA(1, 0, At, B0); PG8_MMA(1, 1, At, B1); PG8_BAR; PG8_SCHED;
;             PG8_LDB(B0, 1, 0); PG8_LDB(B1, 1, 1); PG8_SCHED; PG8_LDA(At, 1, 0); PG8_STAGE(PG8_SA(0, 1), a2 + hstep, voffA);
;             PG8_WAIT_V(8); PG8_WAIT_L(0); PG8_BAR; PG8_MMA(0, 0, At, B0); PG8_MMA(0, 1, At, B1); PG8_BAR; PG8_SCHED;
	s_setprio 1
	s_waitcnt lgkmcnt(0)
	v_mfma_f32_16x16x32_bf16 v[60:63], v[150:153], v[188:191], v[60:63]
	v_mfma_f32_16x16x32_bf16 v[56:59], v[158:161], v[188:191], v[56:59]
	v_mfma_f32_16x16x32_bf16 v[44:47], v[150:153], v[196:199], v[44:47]
	v_mfma_f32_16x16x32_bf16 v[40:43], v[158:161], v[196:199], v[40:43]
	v_mfma_f32_16x16x32_bf16 v[28:31], v[150:153], v[204:207], v[28:31]
	v_mfma_f32_16x16x32_bf16 v[24:27], v[158:161], v[204:207], v[24:27]
	v_mfma_f32_16x16x32_bf16 v[12:15], v[150:153], v[212:215], v[12:15]
	v_mfma_f32_16x16x32_bf16 v[8:11], v[158:161], v[212:215], v[8:11]
	v_mfma_f32_16x16x32_bf16 v[60:63], v[154:157], v[192:195], v[60:63]
	v_mfma_f32_16x16x32_bf16 v[56:59], v[162:165], v[192:195], v[56:59]
	v_mfma_f32_16x16x32_bf16 v[44:47], v[154:157], v[200:203], v[44:47]
	v_mfma_f32_16x16x32_bf16 v[40:43], v[162:165], v[200:203], v[40:43]
	v_mfma_f32_16x16x32_bf16 v[28:31], v[154:157], v[208:211], v[28:31]
	v_mfma_f32_16x16x32_bf16 v[24:27], v[162:165], v[208:211], v[24:27]
	v_mfma_f32_16x16x32_bf16 v[12:15], v[154:157], v[216:219], v[12:15]
	v_mfma_f32_16x16x32_bf16 v[8:11], v[162:165], v[216:219], v[8:11]
	v_mfma_f32_16x16x32_bf16 v[52:55], v[166:169], v[188:191], v[52:55]
	v_mfma_f32_16x16x32_bf16 v[48:51], v[180:183], v[188:191], v[48:51]
	v_mfma_f32_16x16x32_bf16 v[36:39], v[166:169], v[196:199], v[36:39]
	v_mfma_f32_16x16x32_bf16 v[32:35], v[180:183], v[196:199], v[32:35]
	v_mfma_f32_16x16x32_bf16 v[20:23], v[166:169], v[204:207], v[20:23]
	v_mfma_f32_16x16x32_bf16 v[16:19], v[180:183], v[204:207], v[16:19]
	v_mfma_f32_16x16x32_bf16 v[4:7], v[166:169], v[212:215], v[4:7]
	v_mfma_f32_16x16x32_bf16 v[0:3], v[180:183], v[212:215], v[0:3]
	v_mfma_f32_16x16x32_bf16 v[52:55], v[176:179], v[192:195], v[52:55]
	v_mfma_f32_16x16x32_bf16 v[48:51], v[184:187], v[192:195], v[48:51]
	v_mfma_f32_16x16x32_bf16 v[36:39], v[176:179], v[200:203], v[36:39]
	v_mfma_f32_16x16x32_bf16 v[32:35], v[184:187], v[200:203], v[32:35]
	v_mfma_f32_16x16x32_bf16 v[20:23], v[176:179], v[208:211], v[20:23]
	v_mfma_f32_16x16x32_bf16 v[16:19], v[184:187], v[208:211], v[16:19]
	v_mfma_f32_16x16x32_bf16 v[4:7], v[176:179], v[216:219], v[4:7]
	v_mfma_f32_16x16x32_bf16 v[0:3], v[184:187], v[216:219], v[0:3]
	s_setprio 0
	s_barrier
	s_add_i32 s49, 0, 0x18000
	s_add_i32 s50, 0, 0x1c000
	v_add_u32_e32 v162, s49, v145
	v_add_u32_e32 v172, s50, v145
	ds_read_b128 v[150:153], v162
	ds_read_b128 v[154:157], v162 offset:1024
	ds_read_b128 v[158:161], v162 offset:2048
	ds_read_b128 v[162:165], v162 offset:3072
	ds_read_b128 v[166:169], v172
	ds_read_b128 v[176:179], v172 offset:1024
	ds_read_b128 v[180:183], v172 offset:2048
	ds_read_b128 v[184:187], v172 offset:3072
	s_add_u32 s30, s30, 0x40000
	s_addc_u32 s31, s31, 0
	s_mov_b32 m0, s37
	v_lshl_add_u64 v[224:225], s[30:31], 0, v[130:131]
	ds_read_b128 v[188:191], v149 offset:32768
	ds_read_b128 v[192:195], v149 offset:33792
	ds_read_b128 v[196:199], v149 offset:34816
	ds_read_b128 v[200:203], v149 offset:35840
	ds_read_b128 v[204:207], v149 offset:36864
	ds_read_b128 v[208:211], v149 offset:37888
	ds_read_b128 v[212:215], v149 offset:38912
	ds_read_b128 v[216:219], v149 offset:39936
	global_load_lds_dwordx4 v[224:225], off
	v_lshl_add_u64 v[224:225], s[30:31], 0, v[134:135]
	s_mov_b32 m0, s40
	s_nop 0
	global_load_lds_dwordx4 v[224:225], off
	s_waitcnt vmcnt(8)
	s_waitcnt lgkmcnt(0)
	s_barrier
	s_setprio 1
	s_waitcnt lgkmcnt(0)
	v_mfma_f32_16x16x32_bf16 v[126:129], v[150:153], v[188:191], v[126:129]
	v_mfma_f32_16x16x32_bf16 v[122:125], v[158:161], v[188:191], v[122:125]
	v_mfma_f32_16x16x32_bf16 v[110:113], v[150:153], v[196:199], v[110:113]
	v_mfma_f32_16x16x32_bf16 v[106:109], v[158:161], v[196:199], v[106:109]
	v_mfma_f32_16x16x32_bf16 v[94:97], v[150:153], v[204:207], v[94:97]
	v_mfma_f32_16x16x32_bf16 v[90:93], v[158:161], v[204:207], v[90:93]
	v_mfma_f32_16x16x32_bf16 v[78:81], v[150:153], v[212:215], v[78:81]
	v_mfma_f32_16x16x32_bf16 v[74:77], v[158:161], v[212:215], v[74:77]
	v_mfma_f32_16x16x32_bf16 v[126:129], v[154:157], v[192:195], v[126:129]
	v_mfma_f32_16x16x32_bf16 v[122:125], v[162:165], v[192:195], v[122:125]
	v_mfma_f32_16x16x32_bf16 v[110:113], v[154:157], v[200:203], v[110:113]
	v_mfma_f32_16x16x32_bf16 v[106:109], v[162:165], v[200:203], v[106:109]
	v_mfma_f32_16x16x32_bf16 v[94:97], v[154:157], v[208:211], v[94:97]
	v_mfma_f32_16x16x32_bf16 v[90:93], v[162:165], v[208:211], v[90:93]
	v_mfma_f32_16x16x32_bf16 v[78:81], v[154:157], v[216:219], v[78:81]
	v_mfma_f32_16x16x32_bf16 v[74:77], v[162:165], v[216:219], v[74:77]
	v_mfma_f32_16x16x32_bf16 v[118:121], v[166:169], v[188:191], v[118:121]
	v_mfma_f32_16x16x32_bf16 v[114:117], v[180:183], v[188:191], v[114:117]
	v_mfma_f32_16x16x32_bf16 v[102:105], v[166:169], v[196:199], v[102:105]
	v_mfma_f32_16x16x32_bf16 v[98:101], v[180:183], v[196:199], v[98:101]
	v_mfma_f32_16x16x32_bf16 v[86:89], v[166:169], v[204:207], v[86:89]
	v_mfma_f32_16x16x32_bf16 v[82:85], v[180:183], v[204:207], v[82:85]
	v_mfma_f32_16x16x32_bf16 v[70:73], v[166:169], v[212:215], v[70:73]
	v_mfma_f32_16x16x32_bf16 v[66:69], v[180:183], v[212:215], v[66:69]
	v_mfma_f32_16x16x32_bf16 v[118:121], v[176:179], v[192:195], v[118:121]
	v_mfma_f32_16x16x32_bf16 v[114:117], v[184:187], v[192:195], v[114:117]
	v_mfma_f32_16x16x32_bf16 v[102:105], v[176:179], v[200:203], v[102:105]
	v_mfma_f32_16x16x32_bf16 v[98:101], v[184:187], v[200:203], v[98:101]
	v_mfma_f32_16x16x32_bf16 v[86:89], v[176:179], v[208:211], v[86:89]
	v_mfma_f32_16x16x32_bf16 v[82:85], v[184:187], v[208:211], v[82:85]
	v_mfma_f32_16x16x32_bf16 v[70:73], v[176:179], v[216:219], v[70:73]
	v_mfma_f32_16x16x32_bf16 v[66:69], v[184:187], v[216:219], v[66:69]
	s_setprio 0
	s_barrier
; #define PG8_STAGE(bufoff, gbase, voff) do { _Pragma("unroll") for (int _i = 0; _i < 2; ++_i) \
;         __builtin_amdgcn_global_load_lds((const unsigned*)((const char*)(gbase) + (voff)[_i]), (PG8_LAS unsigned*)(lds + (bufoff) + ldsw + _i * 8192), 16, 0, 0); } while (0)
; #define PG8_LDA(dst, b, h) do { _Pragma("unroll") for (int m = 0; m < 4; ++m) _Pragma("unroll") for (int k = 0; k < 2; ++k) dst[m][k] = *(const PG8_LAS bf16x8*)(lds + PG8_SA(b, h) + aoff + m * 2048 + k * 1024); } while (0)
; #define PG8_MMA(ai, bj, At, Bt) do { __builtin_amdgcn_s_setprio(1); _Pragma("unroll") for (int m = 0; m < 4; ++m) _Pragma("unroll") for (int n = 0; n < 2; ++n) _Pragma("unroll") for (int k = 0; k < 2; ++k) \
;         acc[ai][bj][m][n] = __builtin_amdgcn_mfma_f32_16x16x32_bf16(Bt[n][k], At[m][k], acc[ai][bj][m][n], 0, 0, 0); __builtin_amdgcn_s_setprio(0); } while (0)
; #define PG8_WAIT_V(n) asm volatile("s_waitcnt vmcnt(" #n ")" ::: "memory")
; #define PG8_WAIT_L(n) asm volatile("s_waitcnt lgkmcnt(" #n ")" ::: "memory")
; #define PG8_BAR __builtin_amdgcn_s_barrier()
; #define PG8_SCHED __builtin_amdgcn_sched_barrier(0)
; template <class Epi, class Sched, bool ALIGN_EPI = false, bool SP2 = false>
; __device__ __forceinline__ void gemm_phase(PG8_LAS unsigned char* lds, const Gemm g, const Sched& S, const Epi& E, int tid_in) {
;     ...
;             PG8_LDA(At, 1, 1); PG8_STAGE(PG8_SB(1, 0), b3, voffB); PG8_STAGE(PG8_SB(1, 1), b3 + hstep, voffB); PG8_STAGE(PG8_SA(1, 0), a3, voffA);
;             PG8_WAIT_V(8); PG8_WAIT_L(0); PG8_BAR; PG8_MMA(1, 0, At, B0); PG8_MMA(1, 1, At, B1); PG8_BAR; PG8_SCHED;
;     DI void operator()(const pg8::f32x4 (&acc)[2][2][4][2], const pg8::Unit& u, int wr, int wc, int fr, int fq) const {
; #pragma unroll
;         for (int ai = 0; ai < 2; ++ai)
; #pragma unroll
;             for (int m = 0; m < 4; ++m) {
;                 const int row = u.pm * 256 + ai * 128 + wr * 64 + m * 16 + fr; const float rs = rstdx[row];
; #pragma unroll
;                 for (int bj = 0; bj < 2; ++bj) {
;                     const pg8::f32x4 v0 = acc[ai][bj][m][0] * rs, v1 = acc[ai][bj][m][1] * rs;
;                     v4u w; w.x = pk2(v0[0], v0[1]); w.y = pk2(v0[2], v0[3]); w.z = pk2(v1[0], v1[1]); w.w = pk2(v1[2], v1[3]);
;                     *(v4u*)(O + (size_t)row * NPROJ + u.pn * 256 + bj * 128 + wc * 32 + 8 * fq) = w;
	s_add_i32 s30, s49, s6
	v_lshl_add_u64 v[142:143], v[142:143], 0, s[92:93]
	s_mov_b32 m0, s30
	ds_read_b128 v[188:191], v149 offset:49152
	ds_read_b128 v[192:195], v149 offset:50176
	ds_read_b128 v[196:199], v149 offset:51200
	ds_read_b128 v[200:203], v149 offset:52224
	ds_read_b128 v[204:207], v149 offset:53248
	ds_read_b128 v[208:211], v149 offset:54272
	ds_read_b128 v[212:215], v149 offset:55296
	ds_read_b128 v[216:219], v149 offset:56320
	global_load_lds_dwordx4 v[142:143], off
	s_add_i32 m0, s30, 0x2000
	s_add_u32 s28, s28, 0x40080
	v_lshl_add_u64 v[142:143], v[170:171], 0, s[92:93]
	s_addc_u32 s29, s29, 0
	s_add_i32 s30, s50, s6
	global_load_lds_dwordx4 v[142:143], off
	v_lshl_add_u64 v[142:143], s[28:29], 0, v[132:133]
	s_mov_b32 m0, s30
	s_nop 0
	global_load_lds_dwordx4 v[142:143], off
	v_lshl_add_u64 v[142:143], s[28:29], 0, v[136:137]
	s_add_i32 m0, s30, 0x2000
	s_nop 0
	global_load_lds_dwordx4 v[142:143], off
	v_lshl_add_u64 v[142:143], v[220:221], 0, s[92:93]
	s_mov_b32 m0, s41
	s_nop 0
	global_load_lds_dwordx4 v[142:143], off
	v_lshl_add_u64 v[142:143], v[222:223], 0, s[92:93]
	s_mov_b32 m0, s42
	s_nop 0
	global_load_lds_dwordx4 v[142:143], off
	s_waitcnt vmcnt(8)
	s_waitcnt lgkmcnt(0)
	s_barrier
	s_setprio 1
	s_waitcnt lgkmcnt(0)
	v_mfma_f32_16x16x32_bf16 v[60:63], v[150:153], v[188:191], v[60:63]
	v_mfma_f32_16x16x32_bf16 v[56:59], v[158:161], v[188:191], v[56:59]
	v_mfma_f32_16x16x32_bf16 v[44:47], v[150:153], v[196:199], v[44:47]
	v_mfma_f32_16x16x32_bf16 v[40:43], v[158:161], v[196:199], v[40:43]
	v_mfma_f32_16x16x32_bf16 v[28:31], v[150:153], v[204:207], v[28:31]
	v_mfma_f32_16x16x32_bf16 v[24:27], v[158:161], v[204:207], v[24:27]
	v_mfma_f32_16x16x32_bf16 v[12:15], v[150:153], v[212:215], v[12:15]
	v_mfma_f32_16x16x32_bf16 v[8:11], v[158:161], v[212:215], v[8:11]
	v_mfma_f32_16x16x32_bf16 v[60:63], v[154:157], v[192:195], v[60:63]
	v_mfma_f32_16x16x32_bf16 v[56:59], v[162:165], v[192:195], v[56:59]
	v_mfma_f32_16x16x32_bf16 v[44:47], v[154:157], v[200:203], v[44:47]
	v_mfma_f32_16x16x32_bf16 v[40:43], v[162:165], v[200:203], v[40:43]
	v_mfma_f32_16x16x32_bf16 v[28:31], v[154:157], v[208:211], v[28:31]
	v_mfma_f32_16x16x32_bf16 v[24:27], v[162:165], v[208:211], v[24:27]
	v_mfma_f32_16x16x32_bf16 v[12:15], v[154:157], v[216:219], v[12:15]
	v_mfma_f32_16x16x32_bf16 v[8:11], v[162:165], v[216:219], v[8:11]
	v_mfma_f32_16x16x32_bf16 v[52:55], v[166:169], v[188:191], v[52:55]
	v_mfma_f32_16x16x32_bf16 v[48:51], v[180:183], v[188:191], v[48:51]
	v_mfma_f32_16x16x32_bf16 v[36:39], v[166:169], v[196:199], v[36:39]
	v_mfma_f32_16x16x32_bf16 v[32:35], v[180:183], v[196:199], v[32:35]
	v_mfma_f32_16x16x32_bf16 v[20:23], v[166:169], v[204:207], v[20:23]
	v_mfma_f32_16x16x32_bf16 v[16:19], v[180:183], v[204:207], v[16:19]
	v_mfma_f32_16x16x32_bf16 v[4:7], v[166:169], v[212:215], v[4:7]
	v_mfma_f32_16x16x32_bf16 v[0:3], v[180:183], v[212:215], v[0:3]
	v_mfma_f32_16x16x32_bf16 v[52:55], v[176:179], v[192:195], v[52:55]
	v_mfma_f32_16x16x32_bf16 v[48:51], v[184:187], v[192:195], v[48:51]
	v_mfma_f32_16x16x32_bf16 v[36:39], v[176:179], v[200:203], v[36:39]
	v_mfma_f32_16x16x32_bf16 v[32:35], v[184:187], v[200:203], v[32:35]
	v_mfma_f32_16x16x32_bf16 v[20:23], v[176:179], v[208:211], v[20:23]
	v_mfma_f32_16x16x32_bf16 v[16:19], v[184:187], v[208:211], v[16:19]
	v_mfma_f32_16x16x32_bf16 v[4:7], v[176:179], v[216:219], v[4:7]
	v_mfma_f32_16x16x32_bf16 v[0:3], v[184:187], v[216:219], v[0:3]
	s_setprio 0
	s_barrier
	s_add_i32 s48, s48, 2
	s_add_u32 s26, s26, 0x100
	s_addc_u32 s27, s27, 0
	s_add_u32 s46, s46, 0x100
	s_addc_u32 s47, s47, 0
	s_cmp_gt_u32 s48, 13
	s_cbranch_scc0 .LBB0_754
	s_and_b64 vcc, exec, s[14:15]
	s_cbranch_vccz .LBB0_757
	s_barrier
.LBB0_757:
	s_lshl_b32 s17, s24, 8
	v_add_u32_e32 v142, s17, v144
	v_ashrrev_i32_e32 v143, 31, v142
	s_lshl_b32 s24, s25, 8
	v_lshlrev_b64 v[152:153], 12, v[142:143]
	s_ashr_i32 s25, s24, 31
	s_lshl_b64 s[24:25], s[24:25], 1
	s_andn2_b64 vcc, exec, s[38:39]
	s_mov_b32 s46, 0xdb629599
	s_mov_b32 s47, 0xf534ddc0
	s_mov_b32 s52, 0xfc2757d1
	v_pk_mul_f32 v[126:127], v[126:127], v[174:175] op_sel_hi:[1,0]
	v_pk_mul_f32 v[154:155], v[124:125], v[174:175] op_sel_hi:[1,0]
	v_pk_mul_f32 v[124:125], v[122:123], v[174:175] op_sel_hi:[1,0]
	v_cvt_pk_bf16_f32 v122, v126, v127
	v_lshl_add_u64 v[126:127], s[12:13], 0, v[152:153]
	v_lshl_add_u64 v[126:127], v[126:127], 0, s[24:25]
	v_pk_mul_f32 v[128:129], v[128:129], v[174:175] op_sel_hi:[1,0]
	v_lshl_add_u64 v[126:127], v[126:127], 0, s[72:73]
	v_cvt_pk_bf16_f32 v123, v128, v129
	v_cvt_pk_bf16_f32 v124, v124, v125
	v_cvt_pk_bf16_f32 v125, v154, v155
	v_lshl_add_u64 v[126:127], v[126:127], 0, v[64:65]
	global_store_dwordx4 v[126:127], v[122:125], off
	v_pk_mul_f32 v[120:121], v[120:121], v[174:175] op_sel_hi:[1,0]
	v_pk_mul_f32 v[118:119], v[118:119], v[174:175] op_sel_hi:[1,0]
	v_pk_mul_f32 v[122:123], v[116:117], v[174:175] op_sel_hi:[1,0]
	v_pk_mul_f32 v[116:117], v[114:115], v[174:175] op_sel_hi:[1,0]
	v_cvt_pk_bf16_f32 v114, v118, v119
	v_cvt_pk_bf16_f32 v115, v120, v121
	v_cvt_pk_bf16_f32 v116, v116, v117
	v_cvt_pk_bf16_f32 v117, v122, v123
	global_store_dwordx4 v[126:127], v[114:117], off offset:256
	s_nop 1
	v_add_u32_e32 v114, s17, v146
	v_ashrrev_i32_e32 v115, 31, v114
	v_lshlrev_b64 v[114:115], 12, v[114:115]
	v_pk_mul_f32 v[110:111], v[110:111], v[232:233] op_sel_hi:[1,0]
	v_pk_mul_f32 v[118:119], v[108:109], v[232:233] op_sel_hi:[1,0]
	v_pk_mul_f32 v[108:109], v[106:107], v[232:233] op_sel_hi:[1,0]
	v_cvt_pk_bf16_f32 v106, v110, v111
	v_lshl_add_u64 v[110:111], s[12:13], 0, v[114:115]
	v_lshl_add_u64 v[110:111], v[110:111], 0, s[24:25]
; DI unsigned pk2(float lo, float hi) { f32x2_t v = {lo, hi}; bf16x2_t b = __builtin_convertvector(v, bf16x2_t); return __builtin_bit_cast(unsigned, b); }
;     DI void operator()(const pg8::f32x4 (&acc)[2][2][4][2], const pg8::Unit& u, int wr, int wc, int fr, int fq) const {
; #pragma unroll
;         for (int ai = 0; ai < 2; ++ai)
; #pragma unroll
;             for (int m = 0; m < 4; ++m) {
;                 const int row = u.pm * 256 + ai * 128 + wr * 64 + m * 16 + fr; const float rs = rstdx[row];
; #pragma unroll
;                 for (int bj = 0; bj < 2; ++bj) {
;                     const pg8::f32x4 v0 = acc[ai][bj][m][0] * rs, v1 = acc[ai][bj][m][1] * rs;
;                     v4u w; w.x = pk2(v0[0], v0[1]); w.y = pk2(v0[2], v0[3]); w.z = pk2(v1[0], v1[1]); w.w = pk2(v1[2], v1[3]);
;                     *(v4u*)(O + (size_t)row * NPROJ + u.pn * 256 + bj * 128 + wc * 32 + 8 * fq) = w;
;                 }
	v_pk_mul_f32 v[112:113], v[112:113], v[232:233] op_sel_hi:[1,0]
	v_lshl_add_u64 v[110:111], v[110:111], 0, s[72:73]
	v_cvt_pk_bf16_f32 v107, v112, v113
	v_cvt_pk_bf16_f32 v108, v108, v109
	v_cvt_pk_bf16_f32 v109, v118, v119
	v_lshl_add_u64 v[110:111], v[110:111], 0, v[64:65]
	global_store_dwordx4 v[110:111], v[106:109], off
	v_pk_mul_f32 v[104:105], v[104:105], v[232:233] op_sel_hi:[1,0]
	v_pk_mul_f32 v[102:103], v[102:103], v[232:233] op_sel_hi:[1,0]
	v_pk_mul_f32 v[106:107], v[100:101], v[232:233] op_sel_hi:[1,0]
	v_pk_mul_f32 v[100:101], v[98:99], v[232:233] op_sel_hi:[1,0]
	v_cvt_pk_bf16_f32 v98, v102, v103
	v_cvt_pk_bf16_f32 v99, v104, v105
	v_cvt_pk_bf16_f32 v100, v100, v101
	v_cvt_pk_bf16_f32 v101, v106, v107
	global_store_dwordx4 v[110:111], v[98:101], off offset:256
	s_nop 1
	v_add_u32_e32 v98, s17, v147
	v_ashrrev_i32_e32 v99, 31, v98
	v_lshlrev_b64 v[98:99], 12, v[98:99]
	v_pk_mul_f32 v[94:95], v[94:95], v[238:239] op_sel_hi:[1,0]
	v_pk_mul_f32 v[102:103], v[92:93], v[238:239] op_sel_hi:[1,0]
	v_pk_mul_f32 v[92:93], v[90:91], v[238:239] op_sel_hi:[1,0]
	v_cvt_pk_bf16_f32 v90, v94, v95
	v_lshl_add_u64 v[94:95], s[12:13], 0, v[98:99]
	v_lshl_add_u64 v[94:95], v[94:95], 0, s[24:25]
	v_pk_mul_f32 v[96:97], v[96:97], v[238:239] op_sel_hi:[1,0]
	v_lshl_add_u64 v[94:95], v[94:95], 0, s[72:73]
	v_cvt_pk_bf16_f32 v91, v96, v97
	v_cvt_pk_bf16_f32 v92, v92, v93
	v_cvt_pk_bf16_f32 v93, v102, v103
	v_lshl_add_u64 v[94:95], v[94:95], 0, v[64:65]
	global_store_dwordx4 v[94:95], v[90:93], off
	v_pk_mul_f32 v[88:89], v[88:89], v[238:239] op_sel_hi:[1,0]
	v_pk_mul_f32 v[86:87], v[86:87], v[238:239] op_sel_hi:[1,0]
	v_pk_mul_f32 v[90:91], v[84:85], v[238:239] op_sel_hi:[1,0]
	v_pk_mul_f32 v[84:85], v[82:83], v[238:239] op_sel_hi:[1,0]
	v_cvt_pk_bf16_f32 v82, v86, v87
	v_cvt_pk_bf16_f32 v83, v88, v89
	v_cvt_pk_bf16_f32 v84, v84, v85
	v_cvt_pk_bf16_f32 v85, v90, v91
	global_store_dwordx4 v[94:95], v[82:85], off offset:256
	s_nop 1
	v_add_u32_e32 v82, s17, v148
	v_ashrrev_i32_e32 v83, 31, v82
	v_lshlrev_b64 v[82:83], 12, v[82:83]
	v_pk_mul_f32 v[78:79], v[78:79], v[242:243] op_sel_hi:[1,0]
	v_pk_mul_f32 v[86:87], v[76:77], v[242:243] op_sel_hi:[1,0]
	v_pk_mul_f32 v[76:77], v[74:75], v[242:243] op_sel_hi:[1,0]
	v_cvt_pk_bf16_f32 v74, v78, v79
	v_lshl_add_u64 v[78:79], s[12:13], 0, v[82:83]
	v_lshl_add_u64 v[78:79], v[78:79], 0, s[24:25]
	v_pk_mul_f32 v[80:81], v[80:81], v[242:243] op_sel_hi:[1,0]
	v_lshl_add_u64 v[78:79], v[78:79], 0, s[72:73]
	v_cvt_pk_bf16_f32 v75, v80, v81
	v_cvt_pk_bf16_f32 v76, v76, v77
	v_cvt_pk_bf16_f32 v77, v86, v87
	v_lshl_add_u64 v[78:79], v[78:79], 0, v[64:65]
	global_store_dwordx4 v[78:79], v[74:77], off
	v_pk_mul_f32 v[72:73], v[72:73], v[242:243] op_sel_hi:[1,0]
	v_pk_mul_f32 v[70:71], v[70:71], v[242:243] op_sel_hi:[1,0]
	v_pk_mul_f32 v[74:75], v[68:69], v[242:243] op_sel_hi:[1,0]
	v_pk_mul_f32 v[68:69], v[66:67], v[242:243] op_sel_hi:[1,0]
	v_cvt_pk_bf16_f32 v66, v70, v71
	v_cvt_pk_bf16_f32 v67, v72, v73
	v_cvt_pk_bf16_f32 v68, v68, v69
	v_cvt_pk_bf16_f32 v69, v74, v75
	global_store_dwordx4 v[78:79], v[66:69], off offset:256
	s_nop 1
	v_add_u32_e32 v66, 0x80, v142
	v_ashrrev_i32_e32 v67, 31, v66
	v_lshlrev_b64 v[66:67], 12, v[66:67]
	v_pk_mul_f32 v[60:61], v[60:61], v[244:245] op_sel_hi:[1,0]
	v_pk_mul_f32 v[70:71], v[58:59], v[244:245] op_sel_hi:[1,0]
	v_pk_mul_f32 v[58:59], v[56:57], v[244:245] op_sel_hi:[1,0]
	v_cvt_pk_bf16_f32 v56, v60, v61
	v_lshl_add_u64 v[60:61], s[12:13], 0, v[66:67]
	v_lshl_add_u64 v[60:61], v[60:61], 0, s[24:25]
	v_pk_mul_f32 v[62:63], v[62:63], v[244:245] op_sel_hi:[1,0]
	v_lshl_add_u64 v[60:61], v[60:61], 0, s[72:73]
	v_cvt_pk_bf16_f32 v57, v62, v63
	v_cvt_pk_bf16_f32 v58, v58, v59
	v_cvt_pk_bf16_f32 v59, v70, v71
	v_lshl_add_u64 v[60:61], v[60:61], 0, v[64:65]
	global_store_dwordx4 v[60:61], v[56:59], off
	v_pk_mul_f32 v[54:55], v[54:55], v[244:245] op_sel_hi:[1,0]
	v_pk_mul_f32 v[52:53], v[52:53], v[244:245] op_sel_hi:[1,0]
; DI unsigned pk2(float lo, float hi) { f32x2_t v = {lo, hi}; bf16x2_t b = __builtin_convertvector(v, bf16x2_t); return __builtin_bit_cast(unsigned, b); }
;     DI void operator()(const pg8::f32x4 (&acc)[2][2][4][2], const pg8::Unit& u, int wr, int wc, int fr, int fq) const {
; #pragma unroll
;         for (int ai = 0; ai < 2; ++ai)
; #pragma unroll
;             for (int m = 0; m < 4; ++m) {
;                 const int row = u.pm * 256 + ai * 128 + wr * 64 + m * 16 + fr; const float rs = rstdx[row];
; #pragma unroll
;                 for (int bj = 0; bj < 2; ++bj) {
;                     const pg8::f32x4 v0 = acc[ai][bj][m][0] * rs, v1 = acc[ai][bj][m][1] * rs;
;                     v4u w; w.x = pk2(v0[0], v0[1]); w.y = pk2(v0[2], v0[3]); w.z = pk2(v1[0], v1[1]); w.w = pk2(v1[2], v1[3]);
;                     *(v4u*)(O + (size_t)row * NPROJ + u.pn * 256 + bj * 128 + wc * 32 + 8 * fq) = w;
;                 }
	v_pk_mul_f32 v[56:57], v[50:51], v[244:245] op_sel_hi:[1,0]
	v_pk_mul_f32 v[50:51], v[48:49], v[244:245] op_sel_hi:[1,0]
	v_cvt_pk_bf16_f32 v48, v52, v53
	v_cvt_pk_bf16_f32 v49, v54, v55
	v_cvt_pk_bf16_f32 v50, v50, v51
	v_cvt_pk_bf16_f32 v51, v56, v57
	global_store_dwordx4 v[60:61], v[48:51], off offset:256
	s_nop 1
	v_add_u32_e32 v48, 0x90, v142
	v_ashrrev_i32_e32 v49, 31, v48
	v_lshlrev_b64 v[48:49], 12, v[48:49]
	v_pk_mul_f32 v[44:45], v[44:45], v[246:247] op_sel_hi:[1,0]
	v_pk_mul_f32 v[52:53], v[42:43], v[246:247] op_sel_hi:[1,0]
	v_pk_mul_f32 v[42:43], v[40:41], v[246:247] op_sel_hi:[1,0]
	v_cvt_pk_bf16_f32 v40, v44, v45
	v_lshl_add_u64 v[44:45], s[12:13], 0, v[48:49]
	v_lshl_add_u64 v[44:45], v[44:45], 0, s[24:25]
	v_pk_mul_f32 v[46:47], v[46:47], v[246:247] op_sel_hi:[1,0]
	v_lshl_add_u64 v[44:45], v[44:45], 0, s[72:73]
	v_cvt_pk_bf16_f32 v41, v46, v47
	v_cvt_pk_bf16_f32 v42, v42, v43
	v_cvt_pk_bf16_f32 v43, v52, v53
	v_lshl_add_u64 v[44:45], v[44:45], 0, v[64:65]
	global_store_dwordx4 v[44:45], v[40:43], off
	v_pk_mul_f32 v[38:39], v[38:39], v[246:247] op_sel_hi:[1,0]
	v_pk_mul_f32 v[36:37], v[36:37], v[246:247] op_sel_hi:[1,0]
	v_pk_mul_f32 v[40:41], v[34:35], v[246:247] op_sel_hi:[1,0]
	v_pk_mul_f32 v[34:35], v[32:33], v[246:247] op_sel_hi:[1,0]
	v_cvt_pk_bf16_f32 v32, v36, v37
	v_cvt_pk_bf16_f32 v33, v38, v39
	v_cvt_pk_bf16_f32 v34, v34, v35
	v_cvt_pk_bf16_f32 v35, v40, v41
	global_store_dwordx4 v[44:45], v[32:35], off offset:256
	s_nop 1
	v_add_u32_e32 v32, 0xa0, v142
	v_ashrrev_i32_e32 v33, 31, v32
	v_lshlrev_b64 v[32:33], 12, v[32:33]
	v_pk_mul_f32 v[28:29], v[28:29], v[248:249] op_sel_hi:[1,0]
	v_pk_mul_f32 v[36:37], v[26:27], v[248:249] op_sel_hi:[1,0]
	v_pk_mul_f32 v[26:27], v[24:25], v[248:249] op_sel_hi:[1,0]
	v_cvt_pk_bf16_f32 v24, v28, v29
	v_lshl_add_u64 v[28:29], s[12:13], 0, v[32:33]
	v_lshl_add_u64 v[28:29], v[28:29], 0, s[24:25]
	v_pk_mul_f32 v[30:31], v[30:31], v[248:249] op_sel_hi:[1,0]
	v_lshl_add_u64 v[28:29], v[28:29], 0, s[72:73]
	v_cvt_pk_bf16_f32 v25, v30, v31
	v_cvt_pk_bf16_f32 v26, v26, v27
	v_cvt_pk_bf16_f32 v27, v36, v37
	v_lshl_add_u64 v[28:29], v[28:29], 0, v[64:65]
	global_store_dwordx4 v[28:29], v[24:27], off
	v_pk_mul_f32 v[22:23], v[22:23], v[248:249] op_sel_hi:[1,0]
	v_pk_mul_f32 v[20:21], v[20:21], v[248:249] op_sel_hi:[1,0]
	v_pk_mul_f32 v[24:25], v[18:19], v[248:249] op_sel_hi:[1,0]
	v_pk_mul_f32 v[18:19], v[16:17], v[248:249] op_sel_hi:[1,0]
	v_cvt_pk_bf16_f32 v16, v20, v21
	v_cvt_pk_bf16_f32 v17, v22, v23
	v_cvt_pk_bf16_f32 v18, v18, v19
	v_cvt_pk_bf16_f32 v19, v24, v25
	global_store_dwordx4 v[28:29], v[16:19], off offset:256
	s_nop 1
	v_add_u32_e32 v16, 0xb0, v142
	v_ashrrev_i32_e32 v17, 31, v16
	v_lshlrev_b64 v[16:17], 12, v[16:17]
	v_pk_mul_f32 v[12:13], v[12:13], v[250:251] op_sel_hi:[1,0]
	v_pk_mul_f32 v[20:21], v[10:11], v[250:251] op_sel_hi:[1,0]
	v_pk_mul_f32 v[10:11], v[8:9], v[250:251] op_sel_hi:[1,0]
	v_cvt_pk_bf16_f32 v8, v12, v13
	v_lshl_add_u64 v[12:13], s[12:13], 0, v[16:17]
	v_lshl_add_u64 v[12:13], v[12:13], 0, s[24:25]
	v_pk_mul_f32 v[14:15], v[14:15], v[250:251] op_sel_hi:[1,0]
	v_lshl_add_u64 v[12:13], v[12:13], 0, s[72:73]
	v_cvt_pk_bf16_f32 v9, v14, v15
	v_cvt_pk_bf16_f32 v10, v10, v11
	v_cvt_pk_bf16_f32 v11, v20, v21
	v_lshl_add_u64 v[12:13], v[12:13], 0, v[64:65]
	global_store_dwordx4 v[12:13], v[8:11], off
	v_pk_mul_f32 v[6:7], v[6:7], v[250:251] op_sel_hi:[1,0]
	v_pk_mul_f32 v[4:5], v[4:5], v[250:251] op_sel_hi:[1,0]
	v_pk_mul_f32 v[8:9], v[2:3], v[250:251] op_sel_hi:[1,0]
	v_pk_mul_f32 v[2:3], v[0:1], v[250:251] op_sel_hi:[1,0]
	v_cvt_pk_bf16_f32 v0, v4, v5
	v_cvt_pk_bf16_f32 v1, v6, v7
	v_cvt_pk_bf16_f32 v2, v2, v3
	v_cvt_pk_bf16_f32 v3, v8, v9
	s_mov_b64 s[24:25], -1
	global_store_dwordx4 v[12:13], v[0:3], off offset:256
	s_cbranch_vccnz .LBB0_746
	s_andn2_b64 vcc, exec, s[10:11]
	s_cbranch_vccnz .LBB0_745
	s_barrier
	s_branch .LBB0_745
